# norm phases P3/P10/P13: 4-trip row loop fully unrolled, row loads prefetched two rows ahead into a second register set via SGPR-base loads, counted vmcnt
# baseline (speedup 1.0000x reference)
; __device__ __forceinline__ void unpack8(const u32x4 w, f32x4& a, f32x4& b) { a = (f32x4){bflo(w.x), bfhi(w.x), bflo(w.y), bfhi(w.y)}; b = (f32x4){bflo(w.z), bfhi(w.z), bflo(w.w), bfhi(w.w)}; }
; __device__ __forceinline__ void load_xrow(Frame& F, int m, f32x4 (&v)[16]) {
;     const v4u* xr = (const v4u*)((const bf16*)(F.ws + WS_XRES) + (size_t)m * D) + F.lane;
;     v4u w[8];
; #pragma unroll
;     for (int j = 0; j < 8; ++j) w[j] = xr[64 * j];
; #pragma unroll
;     for (int j = 0; j < 8; ++j) pg8::unpack8(w[j], v[2 * j], v[2 * j + 1]);
; }
; __device__ __forceinline__ float row_rnorm(const f32x4 (&v)[16]) {
;     float s = 0.f;
; #pragma unroll
;     for (int j = 0; j < 16; ++j) s += (v[j].x * v[j].x + v[j].y * v[j].y) + (v[j].z * v[j].z + v[j].w * v[j].w);
;     return 1.0f / sqrtf(wave_sum(s) * (1.0f / D) + EPS);
; __device__ __forceinline__ void norm_phase(Frame& F, const float* gain, int nsplit, float scale, const float* samp_base) {
;     ...
;     for (int m = F.gw; m < NPROMPT; m += F.ngw) {
;         f32x4 v[16]; load_xrow(F, m, v);
;         const float r = row_rnorm(v);
.LBB0_413:
	v_lshlrev_b32_e32 v199, 4, v198
	v_readfirstlane_b32 s98, v82
	v_readfirstlane_b32 s99, v83
	s_nop 4
	global_load_dwordx4 v[74:77], v[82:83], off offset:1024
	global_load_dwordx4 v[70:73], v[82:83], off offset:2048
	global_load_dwordx4 v[66:69], v[82:83], off offset:3072
	global_load_dwordx4 v[78:81], v[82:83], off
	v_add_co_u32_e32 v84, vcc, s4, v82
	v_add_co_u32_e64 v88, s[0:1], s8, v82
	s_nop 0
	v_addc_co_u32_e32 v85, vcc, 0, v83, vcc
	global_load_dwordx4 v[98:101], v[84:85], off
	global_load_dwordx4 v[102:105], v[84:85], off offset:1024
	global_load_dwordx4 v[106:109], v[84:85], off offset:2048
	global_load_dwordx4 v[110:113], v[84:85], off offset:3072
	s_add_u32 s98, s98, s2
	s_addc_u32 s99, s99, s3
	s_add_u32 s100, s98, 0x1000
	s_addc_u32 s101, s99, 0
	global_load_dwordx4 v[200:203], v199, s[98:99] offset:1024
	global_load_dwordx4 v[204:207], v199, s[98:99] offset:2048
	global_load_dwordx4 v[208:211], v199, s[98:99] offset:3072
	global_load_dwordx4 v[212:215], v199, s[98:99]
	global_load_dwordx4 v[216:219], v199, s[100:101]
	global_load_dwordx4 v[220:223], v199, s[100:101] offset:1024
	global_load_dwordx4 v[224:227], v199, s[100:101] offset:2048
	global_load_dwordx4 v[228:231], v199, s[100:101] offset:3072
	v_addc_co_u32_e64 v89, s[0:1], 0, v83, s[0:1]
	v_add_co_u32_e64 v86, s[0:1], s9, v82
	s_add_i32 s10, s10, s90
	s_nop 0
	v_addc_co_u32_e64 v87, s[0:1], 0, v83, s[0:1]
	v_lshl_add_u64 v[82:83], v[82:83], 0, s[2:3]
	s_cmpk_lt_i32 s10, 0x2000
	s_waitcnt vmcnt(8)
	v_lshlrev_b32_e32 v120, 16, v74
	v_and_b32_e32 v121, 0xffff0000, v74
	v_lshlrev_b32_e32 v74, 16, v75
	v_lshlrev_b32_e32 v116, 16, v78
	v_and_b32_e32 v117, 0xffff0000, v78
	v_lshlrev_b32_e32 v78, 16, v79
	v_lshlrev_b32_e32 v119, 16, v81
	v_lshlrev_b32_e32 v118, 16, v80
	v_and_b32_e32 v81, 0xffff0000, v81
	v_and_b32_e32 v80, 0xffff0000, v80
	v_and_b32_e32 v79, 0xffff0000, v79
	v_mul_f32_e32 v128, v116, v116
	v_mul_f32_e32 v130, v78, v78
	v_pk_mul_f32 v[132:133], v[80:81], v[80:81]
	v_and_b32_e32 v75, 0xffff0000, v75
	v_mul_f32_e32 v134, v120, v120
	v_mul_f32_e32 v136, v74, v74
	v_mov_b32_e32 v150, v118
	v_mov_b32_e32 v151, v80
	v_mov_b32_e32 v80, v119
	v_pk_fma_f32 v[128:129], v[116:117], v[116:117], v[128:129] op_sel_hi:[1,1,0]
	v_pk_fma_f32 v[130:131], v[78:79], v[78:79], v[130:131] op_sel_hi:[1,1,0]
	v_pk_fma_f32 v[118:119], v[118:119], v[118:119], v[132:133]
	v_lshlrev_b32_e32 v84, 16, v76
	v_and_b32_e32 v85, 0xffff0000, v76
	v_lshlrev_b32_e32 v76, 16, v77
	v_and_b32_e32 v77, 0xffff0000, v77
	v_pk_fma_f32 v[132:133], v[120:121], v[120:121], v[134:135] op_sel_hi:[1,1,0]
	v_pk_fma_f32 v[134:135], v[74:75], v[74:75], v[136:137] op_sel_hi:[1,1,0]
	v_pk_add_f32 v[118:119], v[118:119], v[118:119] op_sel_hi:[0,1]
	v_pk_add_f32 v[128:129], v[128:129], v[130:131]
	v_lshlrev_b32_e32 v123, 16, v71
	v_lshlrev_b32_e32 v122, 16, v70
	v_and_b32_e32 v71, 0xffff0000, v71
	v_and_b32_e32 v70, 0xffff0000, v70
	v_mul_f32_e32 v138, v84, v84
	v_mul_f32_e32 v132, v76, v76
	v_mul_f32_e32 v134, v77, v77
	v_mul_f32_e32 v118, v85, v85
	v_mov_b32_e32 v139, v129
	v_lshlrev_b32_e32 v114, 16, v72
	v_and_b32_e32 v115, 0xffff0000, v72
	v_lshlrev_b32_e32 v72, 16, v66
	v_lshlrev_b32_e32 v124, 16, v73
	v_pk_mul_f32 v[140:141], v[70:71], v[70:71]
	v_pk_add_f32 v[132:133], v[132:133], v[134:135]
	v_pk_add_f32 v[118:119], v[138:139], v[118:119]
	v_and_b32_e32 v125, 0xffff0000, v73
	v_lshlrev_b32_e32 v127, 16, v69
	v_lshlrev_b32_e32 v126, 16, v68
	v_and_b32_e32 v69, 0xffff0000, v69
	v_and_b32_e32 v68, 0xffff0000, v68
	v_mul_f32_e32 v73, v114, v114
	v_mul_f32_e32 v143, v115, v115
	v_mul_f32_e32 v144, v124, v124
	v_mov_b32_e32 v142, v72
	v_mov_b32_e32 v152, v122
	v_mov_b32_e32 v153, v70
	v_mov_b32_e32 v70, v123
	v_pk_fma_f32 v[122:123], v[122:123], v[122:123], v[140:141]
	v_pk_add_f32 v[118:119], v[118:119], v[132:133]
	v_and_b32_e32 v97, 0xffff0000, v66
	v_lshlrev_b32_e32 v66, 16, v67
	v_and_b32_e32 v67, 0xffff0000, v67
	v_pk_mul_f32 v[148:149], v[68:69], v[68:69]
	v_pk_fma_f32 v[136:137], v[124:125], v[124:125], v[144:145] op_sel_hi:[1,1,0]
	v_pk_add_f32 v[140:141], v[72:73], v[142:143]
	v_pk_add_f32 v[122:123], v[122:123], v[122:123] op_sel_hi:[0,1]
	v_pk_add_f32 v[118:119], v[118:119], v[118:119] op_sel_hi:[0,1]
	v_mul_f32_e32 v146, v72, v72
	v_mov_b32_e32 v154, v126
	v_mov_b32_e32 v155, v68
	v_mov_b32_e32 v68, v127
	v_pk_fma_f32 v[126:127], v[126:127], v[126:127], v[148:149]
	v_mul_f32_e32 v136, v97, v97
	v_mov_b32_e32 v147, v141
	v_mul_f32_e32 v122, v66, v66
	v_mul_f32_e32 v118, v67, v67
	v_lshlrev_b32_e32 v156, 16, v98
	v_and_b32_e32 v157, 0xffff0000, v98
	v_lshlrev_b32_e32 v98, 16, v100
	v_lshlrev_b32_e32 v142, 16, v99
	v_pk_add_f32 v[126:127], v[126:127], v[126:127] op_sel_hi:[0,1]
	v_pk_add_f32 v[134:135], v[146:147], v[136:137]
	v_pk_add_f32 v[118:119], v[122:123], v[118:119]
	v_and_b32_e32 v143, 0xffff0000, v99
	v_mul_f32_e32 v99, v156, v156
	v_mul_f32_e32 v131, v157, v157
	v_mul_f32_e32 v126, v142, v142
	v_mov_b32_e32 v130, v98
	v_pk_add_f32 v[118:119], v[134:135], v[118:119]
	s_waitcnt lgkmcnt(0)
; __device__ __forceinline__ float wave_sum(float v) {
; #pragma unroll
;     for (int o = 1; o < 64; o <<= 1) v += __shfl_xor(v, o);
;     return v;
; __device__ __forceinline__ float row_rnorm(const f32x4 (&v)[16]) {
;     float s = 0.f;
; #pragma unroll
;     for (int j = 0; j < 16; ++j) s += (v[j].x * v[j].x + v[j].y * v[j].y) + (v[j].z * v[j].z + v[j].w * v[j].w);
;     return 1.0f / sqrtf(wave_sum(s) * (1.0f / D) + EPS);
	v_and_b32_e32 v171, 0xffff0000, v100
	v_lshlrev_b32_e32 v100, 16, v101
	v_and_b32_e32 v101, 0xffff0000, v101
	v_pk_fma_f32 v[136:137], v[142:143], v[142:143], v[126:127] op_sel_hi:[1,1,0]
	v_pk_add_f32 v[130:131], v[98:99], v[130:131]
	v_pk_add_f32 v[118:119], v[118:119], v[118:119] op_sel_hi:[0,1]
	v_lshlrev_b32_e32 v145, 16, v103
	v_lshlrev_b32_e32 v144, 16, v102
	v_and_b32_e32 v103, 0xffff0000, v103
	v_and_b32_e32 v102, 0xffff0000, v102
	v_mul_f32_e32 v128, v98, v98
	v_mul_f32_e32 v126, v100, v100
	v_mul_f32_e32 v136, v171, v171
	v_mov_b32_e32 v129, v131
	v_mul_f32_e32 v118, v101, v101
	v_lshlrev_b32_e32 v158, 16, v104
	v_and_b32_e32 v159, 0xffff0000, v104
	v_lshlrev_b32_e32 v104, 16, v106
	v_lshlrev_b32_e32 v148, 16, v105
	v_pk_mul_f32 v[140:141], v[102:103], v[102:103]
	v_pk_add_f32 v[128:129], v[128:129], v[136:137]
	v_pk_add_f32 v[118:119], v[126:127], v[118:119]
	v_and_b32_e32 v149, 0xffff0000, v105
	v_mul_f32_e32 v105, v158, v158
	v_mul_f32_e32 v167, v159, v159
	v_mul_f32_e32 v168, v148, v148
	v_mov_b32_e32 v166, v104
	v_pk_fma_f32 v[140:141], v[144:145], v[144:145], v[140:141]
	v_pk_add_f32 v[118:119], v[128:129], v[118:119]
	v_and_b32_e32 v177, 0xffff0000, v106
	v_lshlrev_b32_e32 v106, 16, v107
	v_and_b32_e32 v107, 0xffff0000, v107
	v_mov_b32_e32 v180, v144
	v_mov_b32_e32 v181, v102
	v_mov_b32_e32 v102, v145
	v_pk_fma_f32 v[144:145], v[148:149], v[148:149], v[168:169] op_sel_hi:[1,1,0]
	v_pk_add_f32 v[146:147], v[104:105], v[166:167]
	v_pk_add_f32 v[130:131], v[140:141], v[140:141] op_sel_hi:[0,1]
	v_pk_add_f32 v[118:119], v[118:119], v[118:119] op_sel_hi:[0,1]
	v_lshlrev_b32_e32 v163, 16, v109
	v_lshlrev_b32_e32 v162, 16, v108
	v_and_b32_e32 v109, 0xffff0000, v109
	v_and_b32_e32 v108, 0xffff0000, v108
	v_mul_f32_e32 v170, v104, v104
	v_mov_b32_e32 v99, v171
	v_mul_f32_e32 v144, v177, v177
	v_mov_b32_e32 v171, v147
	v_mul_f32_e32 v130, v106, v106
	v_mul_f32_e32 v118, v107, v107
	v_lshlrev_b32_e32 v160, 16, v110
	v_and_b32_e32 v161, 0xffff0000, v110
	v_lshlrev_b32_e32 v110, 16, v112
	v_lshlrev_b32_e32 v164, 16, v111
	v_pk_mul_f32 v[172:173], v[108:109], v[108:109]
	v_pk_add_f32 v[132:133], v[170:171], v[144:145]
	v_pk_add_f32 v[118:119], v[130:131], v[118:119]
	v_and_b32_e32 v165, 0xffff0000, v111
	v_mul_f32_e32 v111, v160, v160
	v_mul_f32_e32 v175, v161, v161
	v_mul_f32_e32 v176, v164, v164
	v_mov_b32_e32 v174, v110
	v_mov_b32_e32 v182, v162
	v_mov_b32_e32 v183, v108
	v_mov_b32_e32 v108, v163
	v_pk_fma_f32 v[162:163], v[162:163], v[162:163], v[172:173]
	v_pk_add_f32 v[118:119], v[132:133], v[118:119]
	v_and_b32_e32 v179, 0xffff0000, v112
	v_lshlrev_b32_e32 v112, 16, v113
	v_and_b32_e32 v113, 0xffff0000, v113
	v_pk_fma_f32 v[166:167], v[164:165], v[164:165], v[176:177] op_sel_hi:[1,1,0]
	v_pk_add_f32 v[168:169], v[110:111], v[174:175]
	v_pk_add_f32 v[138:139], v[162:163], v[162:163] op_sel_hi:[0,1]
	v_pk_add_f32 v[118:119], v[118:119], v[118:119] op_sel_hi:[0,1]
	v_mul_f32_e32 v178, v110, v110
	v_mov_b32_e32 v111, v179
	v_mul_f32_e32 v166, v179, v179
	v_mov_b32_e32 v179, v169
	v_mul_f32_e32 v138, v112, v112
	v_mul_f32_e32 v118, v113, v113
	v_pk_add_f32 v[136:137], v[178:179], v[166:167]
	v_pk_add_f32 v[118:119], v[138:139], v[118:119]
	v_mov_b32_e32 v73, v97
	v_pk_add_f32 v[118:119], v[136:137], v[118:119]
	v_mov_b32_e32 v105, v177
	v_add_f32_e32 v97, v118, v119
	ds_bpermute_b32 v118, v1, v97
	s_waitcnt lgkmcnt(0)
	v_add_f32_e32 v97, v97, v118
	ds_bpermute_b32 v118, v90, v97
	s_waitcnt lgkmcnt(0)
	v_add_f32_e32 v97, v97, v118
	ds_bpermute_b32 v118, v91, v97
	s_waitcnt lgkmcnt(0)
	v_add_f32_e32 v97, v97, v118
	ds_bpermute_b32 v118, v92, v97
	s_waitcnt lgkmcnt(0)
	v_add_f32_e32 v97, v97, v118
	ds_bpermute_b32 v118, v93, v97
	s_waitcnt lgkmcnt(0)
	v_add_f32_e32 v97, v97, v118
	ds_bpermute_b32 v118, v94, v97
	s_waitcnt lgkmcnt(0)
	v_add_f32_e32 v97, v97, v118
	v_fmamk_f32 v97, v97, 0x39800000, v95
	v_mul_f32_e32 v118, 0x4f800000, v97
	v_cmp_gt_f32_e32 vcc, s5, v97
	s_nop 1
	v_cndmask_b32_e32 v97, v97, v118, vcc
	v_sqrt_f32_e32 v118, v97
	s_nop 0
	v_add_u32_e32 v119, -1, v118
	v_add_u32_e32 v122, 1, v118
	v_fma_f32 v123, -v119, v118, v97
	v_fma_f32 v126, -v122, v118, v97
	v_cmp_ge_f32_e64 s[0:1], 0, v123
	s_nop 1
	v_cndmask_b32_e64 v118, v118, v119, s[0:1]
	v_cmp_lt_f32_e64 s[0:1], 0, v126
	s_nop 1
	v_cndmask_b32_e64 v118, v118, v122, s[0:1]
	v_mul_f32_e32 v119, 0x37800000, v118
	v_cndmask_b32_e32 v118, v118, v119, vcc
	v_cmp_class_f32_e32 vcc, v97, v96
	s_nop 1
	v_cndmask_b32_e32 v97, v118, v97, vcc
	v_div_scale_f32 v118, s[0:1], v97, v97, 1.0
	v_rcp_f32_e32 v122, v118
	v_div_scale_f32 v119, vcc, 1.0, v97, 1.0
	v_fma_f32 v123, -v118, v122, 1.0
	v_fmac_f32_e32 v122, v123, v122
	v_mul_f32_e32 v123, v119, v122
	v_fma_f32 v126, -v118, v123, v119
	v_fmac_f32_e32 v123, v126, v122
	v_fma_f32 v118, -v118, v123, v119
	v_div_fmas_f32 v118, v118, v122, v123
	v_div_fixup_f32 v118, v118, v97, 1.0
	v_pk_mul_f32 v[116:117], v[118:119], v[116:117] op_sel_hi:[0,1]
	v_pk_mul_f32 v[78:79], v[118:119], v[78:79] op_sel_hi:[0,1]
	v_pk_mul_f32 v[122:123], v[118:119], v[150:151] op_sel_hi:[0,1]
	v_pk_mul_f32 v[80:81], v[118:119], v[80:81] op_sel_hi:[0,1]
	v_pk_mul_f32 v[126:127], v[118:119], v[152:153] op_sel_hi:[0,1]
	v_pk_mul_f32 v[66:67], v[118:119], v[66:67] op_sel_hi:[0,1]
	v_pk_mul_f32 v[68:69], v[118:119], v[68:69] op_sel_hi:[0,1]
	v_pk_mul_f32 v[120:121], v[118:119], v[120:121] op_sel_hi:[0,1]
	v_pk_mul_f32 v[74:75], v[118:119], v[74:75] op_sel_hi:[0,1]
	v_pk_mul_f32 v[84:85], v[118:119], v[84:85] op_sel_hi:[0,1]
	v_pk_mul_f32 v[76:77], v[118:119], v[76:77] op_sel_hi:[0,1]
	v_pk_mul_f32 v[70:71], v[118:119], v[70:71] op_sel_hi:[0,1]
; __device__ __forceinline__ u32x4 pack8(const f32x4 a, const f32x4 b) { u32x4 w; w.x = cvt_pk_bf16(a[0], a[1]); w.y = cvt_pk_bf16(a[2], a[3]); w.z = cvt_pk_bf16(b[0], b[1]); w.w = cvt_pk_bf16(b[2], b[3]); return w; }
; __device__ __forceinline__ void load_xrow(Frame& F, int m, f32x4 (&v)[16]) {
;     const v4u* xr = (const v4u*)((const bf16*)(F.ws + WS_XRES) + (size_t)m * D) + F.lane;
; __device__ __forceinline__ void norm_phase(Frame& F, const float* gain, int nsplit, float scale, const float* samp_base) {
;     ...
;     for (int m = F.gw; m < NPROMPT; m += F.ngw) {
;         f32x4 v[16]; load_xrow(F, m, v);
;         const float r = row_rnorm(v);
;         v4u* o8 = (v4u*)((bf16*)(F.ws + WS_H) + (size_t)m * D) + F.lane;
; #pragma unroll
;         for (int j = 0; j < 8; ++j) o8[64 * j] = pg8::pack8(v[2 * j] * r * gn[2 * j], v[2 * j + 1] * r * gn[2 * j + 1]);
	v_pk_mul_f32 v[114:115], v[118:119], v[114:115] op_sel_hi:[0,1]
	v_pk_mul_f32 v[124:125], v[118:119], v[124:125] op_sel_hi:[0,1]
	v_pk_mul_f32 v[72:73], v[118:119], v[72:73] op_sel_hi:[0,1]
	v_pk_mul_f32 v[128:129], v[118:119], v[154:155] op_sel_hi:[0,1]
	v_pk_mul_f32 v[130:131], v[118:119], v[156:157] op_sel_hi:[0,1]
	v_pk_mul_f32 v[132:133], v[118:119], v[142:143] op_sel_hi:[0,1]
	v_pk_mul_f32 v[98:99], v[118:119], v[98:99] op_sel_hi:[0,1]
	v_pk_mul_f32 v[100:101], v[118:119], v[100:101] op_sel_hi:[0,1]
	v_pk_mul_f32 v[134:135], v[118:119], v[180:181] op_sel_hi:[0,1]
	v_pk_mul_f32 v[102:103], v[118:119], v[102:103] op_sel_hi:[0,1]
	v_pk_mul_f32 v[136:137], v[118:119], v[158:159] op_sel_hi:[0,1]
	v_pk_mul_f32 v[138:139], v[118:119], v[148:149] op_sel_hi:[0,1]
	v_pk_mul_f32 v[104:105], v[118:119], v[104:105] op_sel_hi:[0,1]
	v_pk_mul_f32 v[106:107], v[118:119], v[106:107] op_sel_hi:[0,1]
	v_pk_mul_f32 v[140:141], v[118:119], v[182:183] op_sel_hi:[0,1]
	v_pk_mul_f32 v[108:109], v[118:119], v[108:109] op_sel_hi:[0,1]
	v_pk_mul_f32 v[142:143], v[118:119], v[160:161] op_sel_hi:[0,1]
	v_pk_mul_f32 v[144:145], v[118:119], v[164:165] op_sel_hi:[0,1]
	v_pk_mul_f32 v[110:111], v[118:119], v[110:111] op_sel_hi:[0,1]
	v_pk_mul_f32 v[112:113], v[118:119], v[112:113] op_sel_hi:[0,1]
	v_pk_mul_f32 v[78:79], v[52:53], v[78:79]
	v_pk_mul_f32 v[116:117], v[50:51], v[116:117]
	v_pk_mul_f32 v[80:81], v[4:5], v[80:81]
	v_pk_mul_f32 v[118:119], v[2:3], v[122:123]
	v_pk_mul_f32 v[122:123], v[14:15], v[126:127]
	v_pk_mul_f32 v[126:127], v[44:45], v[66:67]
	v_pk_mul_f32 v[146:147], v[24:25], v[68:69]
	v_cvt_pk_bf16_f32 v66, v116, v117
	v_cvt_pk_bf16_f32 v67, v78, v79
	v_cvt_pk_bf16_f32 v68, v118, v119
	v_cvt_pk_bf16_f32 v69, v80, v81
	v_pk_mul_f32 v[74:75], v[8:9], v[74:75]
	v_pk_mul_f32 v[120:121], v[6:7], v[120:121]
	v_pk_mul_f32 v[76:77], v[12:13], v[76:77]
	v_pk_mul_f32 v[84:85], v[10:11], v[84:85]
	global_store_dwordx4 v[86:87], v[66:69], off offset:-4096
	v_pk_mul_f32 v[70:71], v[16:17], v[70:71]
	v_pk_mul_f32 v[124:125], v[20:21], v[124:125]
	v_cvt_pk_bf16_f32 v66, v120, v121
	v_cvt_pk_bf16_f32 v67, v74, v75
	v_cvt_pk_bf16_f32 v68, v84, v85
	v_cvt_pk_bf16_f32 v69, v76, v77
	v_pk_mul_f32 v[114:115], v[18:19], v[114:115]
	global_store_dwordx4 v[88:89], v[66:69], off offset:1024
	v_pk_mul_f32 v[72:73], v[42:43], v[72:73]
	v_pk_mul_f32 v[128:129], v[22:23], v[128:129]
	v_cvt_pk_bf16_f32 v66, v122, v123
	v_cvt_pk_bf16_f32 v67, v70, v71
	v_cvt_pk_bf16_f32 v68, v114, v115
	v_cvt_pk_bf16_f32 v69, v124, v125
	global_store_dwordx4 v[88:89], v[66:69], off offset:2048
	v_pk_mul_f32 v[132:133], v[28:29], v[132:133]
	v_pk_mul_f32 v[130:131], v[26:27], v[130:131]
	v_cvt_pk_bf16_f32 v66, v72, v73
	v_cvt_pk_bf16_f32 v67, v126, v127
	v_cvt_pk_bf16_f32 v68, v128, v129
	v_cvt_pk_bf16_f32 v69, v146, v147
	v_pk_mul_f32 v[100:101], v[36:37], v[100:101]
	v_pk_mul_f32 v[98:99], v[34:35], v[98:99]
	global_store_dwordx4 v[88:89], v[66:69], off offset:3072
	v_pk_mul_f32 v[102:103], v[32:33], v[102:103]
	v_pk_mul_f32 v[134:135], v[30:31], v[134:135]
	v_cvt_pk_bf16_f32 v66, v130, v131
	v_cvt_pk_bf16_f32 v67, v132, v133
	v_cvt_pk_bf16_f32 v68, v98, v99
	v_cvt_pk_bf16_f32 v69, v100, v101
	v_pk_mul_f32 v[138:139], v[40:41], v[138:139]
	v_pk_mul_f32 v[136:137], v[38:39], v[136:137]
	global_store_dwordx4 v[86:87], v[66:69], off
	v_pk_mul_f32 v[106:107], v[48:49], v[106:107]
	v_pk_mul_f32 v[104:105], v[46:47], v[104:105]
	v_cvt_pk_bf16_f32 v66, v134, v135
	v_cvt_pk_bf16_f32 v67, v102, v103
	v_cvt_pk_bf16_f32 v68, v136, v137
	v_cvt_pk_bf16_f32 v69, v138, v139
	v_pk_mul_f32 v[108:109], v[60:61], v[108:109]
	v_pk_mul_f32 v[140:141], v[58:59], v[140:141]
	global_store_dwordx4 v[86:87], v[66:69], off offset:1024
	v_pk_mul_f32 v[144:145], v[56:57], v[144:145]
	v_pk_mul_f32 v[142:143], v[54:55], v[142:143]
	v_cvt_pk_bf16_f32 v66, v104, v105
	v_cvt_pk_bf16_f32 v67, v106, v107
	v_cvt_pk_bf16_f32 v68, v140, v141
	v_cvt_pk_bf16_f32 v69, v108, v109
	v_pk_mul_f32 v[112:113], v[64:65], v[112:113]
	v_pk_mul_f32 v[110:111], v[62:63], v[110:111]
	global_store_dwordx4 v[86:87], v[66:69], off offset:2048
	s_nop 1
	v_cvt_pk_bf16_f32 v66, v142, v143
	v_cvt_pk_bf16_f32 v67, v144, v145
	v_cvt_pk_bf16_f32 v68, v110, v111
	v_cvt_pk_bf16_f32 v69, v112, v113
	global_store_dwordx4 v[86:87], v[66:69], off offset:3072
	s_add_u32 s98, s98, s2
	s_addc_u32 s99, s99, s3
	s_add_u32 s100, s98, 0x1000
	s_addc_u32 s101, s99, 0
	global_load_dwordx4 v[74:77], v199, s[98:99] offset:1024
	global_load_dwordx4 v[70:73], v199, s[98:99] offset:2048
	global_load_dwordx4 v[66:69], v199, s[98:99] offset:3072
	global_load_dwordx4 v[78:81], v199, s[98:99]
	global_load_dwordx4 v[98:101], v199, s[100:101]
	global_load_dwordx4 v[102:105], v199, s[100:101] offset:1024
	global_load_dwordx4 v[106:109], v199, s[100:101] offset:2048
	global_load_dwordx4 v[110:113], v199, s[100:101] offset:3072
	v_add_co_u32_e32 v84, vcc, s4, v82
	v_add_co_u32_e64 v88, s[0:1], s8, v82
	s_nop 0
	v_addc_co_u32_e32 v85, vcc, 0, v83, vcc
	v_addc_co_u32_e64 v89, s[0:1], 0, v83, s[0:1]
	v_add_co_u32_e64 v86, s[0:1], s9, v82
	s_add_i32 s10, s10, s90
	s_nop 0
	v_addc_co_u32_e64 v87, s[0:1], 0, v83, s[0:1]
	v_lshl_add_u64 v[82:83], v[82:83], 0, s[2:3]
	s_cmpk_lt_i32 s10, 0x2000
	s_waitcnt vmcnt(16)
; __device__ __forceinline__ void unpack8(const u32x4 w, f32x4& a, f32x4& b) { a = (f32x4){bflo(w.x), bfhi(w.x), bflo(w.y), bfhi(w.y)}; b = (f32x4){bflo(w.z), bfhi(w.z), bflo(w.w), bfhi(w.w)}; }
; __device__ __forceinline__ void load_xrow(Frame& F, int m, f32x4 (&v)[16]) {
;     const v4u* xr = (const v4u*)((const bf16*)(F.ws + WS_XRES) + (size_t)m * D) + F.lane;
;     v4u w[8];
; #pragma unroll
;     for (int j = 0; j < 8; ++j) w[j] = xr[64 * j];
; #pragma unroll
;     for (int j = 0; j < 8; ++j) pg8::unpack8(w[j], v[2 * j], v[2 * j + 1]);
; }
; __device__ __forceinline__ float row_rnorm(const f32x4 (&v)[16]) {
;     float s = 0.f;
; #pragma unroll
;     for (int j = 0; j < 16; ++j) s += (v[j].x * v[j].x + v[j].y * v[j].y) + (v[j].z * v[j].z + v[j].w * v[j].w);
;     return 1.0f / sqrtf(wave_sum(s) * (1.0f / D) + EPS);
	v_lshlrev_b32_e32 v120, 16, v200
	v_and_b32_e32 v121, 0xffff0000, v200
	v_lshlrev_b32_e32 v200, 16, v201
	v_lshlrev_b32_e32 v116, 16, v212
	v_and_b32_e32 v117, 0xffff0000, v212
	v_lshlrev_b32_e32 v212, 16, v213
	v_lshlrev_b32_e32 v119, 16, v215
	v_lshlrev_b32_e32 v118, 16, v214
	v_and_b32_e32 v215, 0xffff0000, v215
	v_and_b32_e32 v214, 0xffff0000, v214
	v_and_b32_e32 v213, 0xffff0000, v213
	v_mul_f32_e32 v128, v116, v116
	v_mul_f32_e32 v130, v212, v212
	v_pk_mul_f32 v[132:133], v[214:215], v[214:215]
	v_and_b32_e32 v201, 0xffff0000, v201
	v_mul_f32_e32 v134, v120, v120
	v_mul_f32_e32 v136, v200, v200
	v_mov_b32_e32 v150, v118
	v_mov_b32_e32 v151, v214
	v_mov_b32_e32 v214, v119
	v_pk_fma_f32 v[128:129], v[116:117], v[116:117], v[128:129] op_sel_hi:[1,1,0]
	v_pk_fma_f32 v[130:131], v[212:213], v[212:213], v[130:131] op_sel_hi:[1,1,0]
	v_pk_fma_f32 v[118:119], v[118:119], v[118:119], v[132:133]
	v_lshlrev_b32_e32 v84, 16, v202
	v_and_b32_e32 v85, 0xffff0000, v202
	v_lshlrev_b32_e32 v202, 16, v203
	v_and_b32_e32 v203, 0xffff0000, v203
	v_pk_fma_f32 v[132:133], v[120:121], v[120:121], v[134:135] op_sel_hi:[1,1,0]
	v_pk_fma_f32 v[134:135], v[200:201], v[200:201], v[136:137] op_sel_hi:[1,1,0]
	v_pk_add_f32 v[118:119], v[118:119], v[118:119] op_sel_hi:[0,1]
	v_pk_add_f32 v[128:129], v[128:129], v[130:131]
	v_lshlrev_b32_e32 v123, 16, v205
	v_lshlrev_b32_e32 v122, 16, v204
	v_and_b32_e32 v205, 0xffff0000, v205
	v_and_b32_e32 v204, 0xffff0000, v204
	v_mul_f32_e32 v138, v84, v84
	v_mul_f32_e32 v132, v202, v202
	v_mul_f32_e32 v134, v203, v203
	v_mul_f32_e32 v118, v85, v85
	v_mov_b32_e32 v139, v129
	v_lshlrev_b32_e32 v114, 16, v206
	v_and_b32_e32 v115, 0xffff0000, v206
	v_lshlrev_b32_e32 v206, 16, v208
	v_lshlrev_b32_e32 v124, 16, v207
	v_pk_mul_f32 v[140:141], v[204:205], v[204:205]
	v_pk_add_f32 v[132:133], v[132:133], v[134:135]
	v_pk_add_f32 v[118:119], v[138:139], v[118:119]
	v_and_b32_e32 v125, 0xffff0000, v207
	v_lshlrev_b32_e32 v127, 16, v211
	v_lshlrev_b32_e32 v126, 16, v210
	v_and_b32_e32 v211, 0xffff0000, v211
	v_and_b32_e32 v210, 0xffff0000, v210
	v_mul_f32_e32 v207, v114, v114
	v_mul_f32_e32 v143, v115, v115
	v_mul_f32_e32 v144, v124, v124
	v_mov_b32_e32 v142, v206
	v_mov_b32_e32 v152, v122
	v_mov_b32_e32 v153, v204
	v_mov_b32_e32 v204, v123
	v_pk_fma_f32 v[122:123], v[122:123], v[122:123], v[140:141]
	v_pk_add_f32 v[118:119], v[118:119], v[132:133]
	v_and_b32_e32 v97, 0xffff0000, v208
	v_lshlrev_b32_e32 v208, 16, v209
	v_and_b32_e32 v209, 0xffff0000, v209
	v_pk_mul_f32 v[148:149], v[210:211], v[210:211]
	v_pk_fma_f32 v[136:137], v[124:125], v[124:125], v[144:145] op_sel_hi:[1,1,0]
	v_pk_add_f32 v[140:141], v[206:207], v[142:143]
	v_pk_add_f32 v[122:123], v[122:123], v[122:123] op_sel_hi:[0,1]
	v_pk_add_f32 v[118:119], v[118:119], v[118:119] op_sel_hi:[0,1]
	v_mul_f32_e32 v146, v206, v206
	v_mov_b32_e32 v154, v126
	v_mov_b32_e32 v155, v210
	v_mov_b32_e32 v210, v127
	v_pk_fma_f32 v[126:127], v[126:127], v[126:127], v[148:149]
	v_mul_f32_e32 v136, v97, v97
	v_mov_b32_e32 v147, v141
	v_mul_f32_e32 v122, v208, v208
	v_mul_f32_e32 v118, v209, v209
	v_lshlrev_b32_e32 v156, 16, v216
	v_and_b32_e32 v157, 0xffff0000, v216
	v_lshlrev_b32_e32 v216, 16, v218
	v_lshlrev_b32_e32 v142, 16, v217
	v_pk_add_f32 v[126:127], v[126:127], v[126:127] op_sel_hi:[0,1]
	v_pk_add_f32 v[134:135], v[146:147], v[136:137]
	v_pk_add_f32 v[118:119], v[122:123], v[118:119]
	v_and_b32_e32 v143, 0xffff0000, v217
	v_mul_f32_e32 v217, v156, v156
	v_mul_f32_e32 v131, v157, v157
	v_mul_f32_e32 v126, v142, v142
	v_mov_b32_e32 v130, v216
	v_pk_add_f32 v[118:119], v[134:135], v[118:119]
	s_waitcnt lgkmcnt(0)
	v_and_b32_e32 v171, 0xffff0000, v218
	v_lshlrev_b32_e32 v218, 16, v219
	v_and_b32_e32 v219, 0xffff0000, v219
	v_pk_fma_f32 v[136:137], v[142:143], v[142:143], v[126:127] op_sel_hi:[1,1,0]
	v_pk_add_f32 v[130:131], v[216:217], v[130:131]
	v_pk_add_f32 v[118:119], v[118:119], v[118:119] op_sel_hi:[0,1]
	v_lshlrev_b32_e32 v145, 16, v221
	v_lshlrev_b32_e32 v144, 16, v220
	v_and_b32_e32 v221, 0xffff0000, v221
	v_and_b32_e32 v220, 0xffff0000, v220
	v_mul_f32_e32 v128, v216, v216
	v_mul_f32_e32 v126, v218, v218
	v_mul_f32_e32 v136, v171, v171
	v_mov_b32_e32 v129, v131
	v_mul_f32_e32 v118, v219, v219
	v_lshlrev_b32_e32 v158, 16, v222
	v_and_b32_e32 v159, 0xffff0000, v222
	v_lshlrev_b32_e32 v222, 16, v224
	v_lshlrev_b32_e32 v148, 16, v223
	v_pk_mul_f32 v[140:141], v[220:221], v[220:221]
	v_pk_add_f32 v[128:129], v[128:129], v[136:137]
	v_pk_add_f32 v[118:119], v[126:127], v[118:119]
	v_and_b32_e32 v149, 0xffff0000, v223
	v_mul_f32_e32 v223, v158, v158
	v_mul_f32_e32 v167, v159, v159
	v_mul_f32_e32 v168, v148, v148
	v_mov_b32_e32 v166, v222
	v_pk_fma_f32 v[140:141], v[144:145], v[144:145], v[140:141]
	v_pk_add_f32 v[118:119], v[128:129], v[118:119]
	v_and_b32_e32 v177, 0xffff0000, v224
	v_lshlrev_b32_e32 v224, 16, v225
	v_and_b32_e32 v225, 0xffff0000, v225
	v_mov_b32_e32 v180, v144
	v_mov_b32_e32 v181, v220
	v_mov_b32_e32 v220, v145
	v_pk_fma_f32 v[144:145], v[148:149], v[148:149], v[168:169] op_sel_hi:[1,1,0]
	v_pk_add_f32 v[146:147], v[222:223], v[166:167]
	v_pk_add_f32 v[130:131], v[140:141], v[140:141] op_sel_hi:[0,1]
	v_pk_add_f32 v[118:119], v[118:119], v[118:119] op_sel_hi:[0,1]
	v_lshlrev_b32_e32 v163, 16, v227
	v_lshlrev_b32_e32 v162, 16, v226
	v_and_b32_e32 v227, 0xffff0000, v227
	v_and_b32_e32 v226, 0xffff0000, v226
	v_mul_f32_e32 v170, v222, v222
	v_mov_b32_e32 v217, v171
	v_mul_f32_e32 v144, v177, v177
	v_mov_b32_e32 v171, v147
	v_mul_f32_e32 v130, v224, v224
	v_mul_f32_e32 v118, v225, v225
	v_lshlrev_b32_e32 v160, 16, v228
	v_and_b32_e32 v161, 0xffff0000, v228
	v_lshlrev_b32_e32 v228, 16, v230
	v_lshlrev_b32_e32 v164, 16, v229
	v_pk_mul_f32 v[172:173], v[226:227], v[226:227]
	v_pk_add_f32 v[132:133], v[170:171], v[144:145]
	v_pk_add_f32 v[118:119], v[130:131], v[118:119]
	v_and_b32_e32 v165, 0xffff0000, v229
	v_mul_f32_e32 v229, v160, v160
	v_mul_f32_e32 v175, v161, v161
	v_mul_f32_e32 v176, v164, v164
	v_mov_b32_e32 v174, v228
	v_mov_b32_e32 v182, v162
	v_mov_b32_e32 v183, v226
	v_mov_b32_e32 v226, v163
	v_pk_fma_f32 v[162:163], v[162:163], v[162:163], v[172:173]
	v_pk_add_f32 v[118:119], v[132:133], v[118:119]
	v_and_b32_e32 v179, 0xffff0000, v230
	v_lshlrev_b32_e32 v230, 16, v231
	v_and_b32_e32 v231, 0xffff0000, v231
	v_pk_fma_f32 v[166:167], v[164:165], v[164:165], v[176:177] op_sel_hi:[1,1,0]
	v_pk_add_f32 v[168:169], v[228:229], v[174:175]
	v_pk_add_f32 v[138:139], v[162:163], v[162:163] op_sel_hi:[0,1]
	v_pk_add_f32 v[118:119], v[118:119], v[118:119] op_sel_hi:[0,1]
	v_mul_f32_e32 v178, v228, v228
	v_mov_b32_e32 v229, v179
	v_mul_f32_e32 v166, v179, v179
	v_mov_b32_e32 v179, v169
	v_mul_f32_e32 v138, v230, v230
	v_mul_f32_e32 v118, v231, v231
	v_pk_add_f32 v[136:137], v[178:179], v[166:167]
	v_pk_add_f32 v[118:119], v[138:139], v[118:119]
	v_mov_b32_e32 v207, v97
	v_pk_add_f32 v[118:119], v[136:137], v[118:119]
	v_mov_b32_e32 v223, v177
	v_add_f32_e32 v97, v118, v119
	ds_bpermute_b32 v118, v1, v97
	s_waitcnt lgkmcnt(0)
; __device__ __forceinline__ u32x4 pack8(const f32x4 a, const f32x4 b) { u32x4 w; w.x = cvt_pk_bf16(a[0], a[1]); w.y = cvt_pk_bf16(a[2], a[3]); w.z = cvt_pk_bf16(b[0], b[1]); w.w = cvt_pk_bf16(b[2], b[3]); return w; }
; __device__ __forceinline__ float wave_sum(float v) {
; #pragma unroll
;     for (int o = 1; o < 64; o <<= 1) v += __shfl_xor(v, o);
;     return v;
; __device__ __forceinline__ float row_rnorm(const f32x4 (&v)[16]) {
;     float s = 0.f;
; #pragma unroll
;     for (int j = 0; j < 16; ++j) s += (v[j].x * v[j].x + v[j].y * v[j].y) + (v[j].z * v[j].z + v[j].w * v[j].w);
;     return 1.0f / sqrtf(wave_sum(s) * (1.0f / D) + EPS);
; }
; __device__ __forceinline__ void norm_phase(Frame& F, const float* gain, int nsplit, float scale, const float* samp_base) {
;     (void)nsplit;
;     norm_sample_row<false>(F, gain, scale, samp_base, nullptr);
;     f32x4 gn[16]; load_gain8(gain, F.lane, gn);
;     for (int m = F.gw; m < NPROMPT; m += F.ngw) {
;         f32x4 v[16]; load_xrow(F, m, v);
;         const float r = row_rnorm(v);
;         v4u* o8 = (v4u*)((bf16*)(F.ws + WS_H) + (size_t)m * D) + F.lane;
; #pragma unroll
;         for (int j = 0; j < 8; ++j) o8[64 * j] = pg8::pack8(v[2 * j] * r * gn[2 * j], v[2 * j + 1] * r * gn[2 * j + 1]);
	v_add_f32_e32 v97, v97, v118
	ds_bpermute_b32 v118, v90, v97
	s_waitcnt lgkmcnt(0)
	v_add_f32_e32 v97, v97, v118
	ds_bpermute_b32 v118, v91, v97
	s_waitcnt lgkmcnt(0)
	v_add_f32_e32 v97, v97, v118
	ds_bpermute_b32 v118, v92, v97
	s_waitcnt lgkmcnt(0)
	v_add_f32_e32 v97, v97, v118
	ds_bpermute_b32 v118, v93, v97
	s_waitcnt lgkmcnt(0)
	v_add_f32_e32 v97, v97, v118
	ds_bpermute_b32 v118, v94, v97
	s_waitcnt lgkmcnt(0)
	v_add_f32_e32 v97, v97, v118
	v_fmamk_f32 v97, v97, 0x39800000, v95
	v_mul_f32_e32 v118, 0x4f800000, v97
	v_cmp_gt_f32_e32 vcc, s5, v97
	s_nop 1
	v_cndmask_b32_e32 v97, v97, v118, vcc
	v_sqrt_f32_e32 v118, v97
	s_nop 0
	v_add_u32_e32 v119, -1, v118
	v_add_u32_e32 v122, 1, v118
	v_fma_f32 v123, -v119, v118, v97
	v_fma_f32 v126, -v122, v118, v97
	v_cmp_ge_f32_e64 s[0:1], 0, v123
	s_nop 1
	v_cndmask_b32_e64 v118, v118, v119, s[0:1]
	v_cmp_lt_f32_e64 s[0:1], 0, v126
	s_nop 1
	v_cndmask_b32_e64 v118, v118, v122, s[0:1]
	v_mul_f32_e32 v119, 0x37800000, v118
	v_cndmask_b32_e32 v118, v118, v119, vcc
	v_cmp_class_f32_e32 vcc, v97, v96
	s_nop 1
	v_cndmask_b32_e32 v97, v118, v97, vcc
	v_div_scale_f32 v118, s[0:1], v97, v97, 1.0
	v_rcp_f32_e32 v122, v118
	v_div_scale_f32 v119, vcc, 1.0, v97, 1.0
	v_fma_f32 v123, -v118, v122, 1.0
	v_fmac_f32_e32 v122, v123, v122
	v_mul_f32_e32 v123, v119, v122
	v_fma_f32 v126, -v118, v123, v119
	v_fmac_f32_e32 v123, v126, v122
	v_fma_f32 v118, -v118, v123, v119
	v_div_fmas_f32 v118, v118, v122, v123
	v_div_fixup_f32 v118, v118, v97, 1.0
	v_pk_mul_f32 v[116:117], v[118:119], v[116:117] op_sel_hi:[0,1]
	v_pk_mul_f32 v[212:213], v[118:119], v[212:213] op_sel_hi:[0,1]
	v_pk_mul_f32 v[122:123], v[118:119], v[150:151] op_sel_hi:[0,1]
	v_pk_mul_f32 v[214:215], v[118:119], v[214:215] op_sel_hi:[0,1]
	v_pk_mul_f32 v[126:127], v[118:119], v[152:153] op_sel_hi:[0,1]
	v_pk_mul_f32 v[208:209], v[118:119], v[208:209] op_sel_hi:[0,1]
	v_pk_mul_f32 v[210:211], v[118:119], v[210:211] op_sel_hi:[0,1]
	v_pk_mul_f32 v[120:121], v[118:119], v[120:121] op_sel_hi:[0,1]
	v_pk_mul_f32 v[200:201], v[118:119], v[200:201] op_sel_hi:[0,1]
	v_pk_mul_f32 v[84:85], v[118:119], v[84:85] op_sel_hi:[0,1]
	v_pk_mul_f32 v[202:203], v[118:119], v[202:203] op_sel_hi:[0,1]
	v_pk_mul_f32 v[204:205], v[118:119], v[204:205] op_sel_hi:[0,1]
	v_pk_mul_f32 v[114:115], v[118:119], v[114:115] op_sel_hi:[0,1]
	v_pk_mul_f32 v[124:125], v[118:119], v[124:125] op_sel_hi:[0,1]
	v_pk_mul_f32 v[206:207], v[118:119], v[206:207] op_sel_hi:[0,1]
	v_pk_mul_f32 v[128:129], v[118:119], v[154:155] op_sel_hi:[0,1]
	v_pk_mul_f32 v[130:131], v[118:119], v[156:157] op_sel_hi:[0,1]
	v_pk_mul_f32 v[132:133], v[118:119], v[142:143] op_sel_hi:[0,1]
	v_pk_mul_f32 v[216:217], v[118:119], v[216:217] op_sel_hi:[0,1]
	v_pk_mul_f32 v[218:219], v[118:119], v[218:219] op_sel_hi:[0,1]
	v_pk_mul_f32 v[134:135], v[118:119], v[180:181] op_sel_hi:[0,1]
	v_pk_mul_f32 v[220:221], v[118:119], v[220:221] op_sel_hi:[0,1]
	v_pk_mul_f32 v[136:137], v[118:119], v[158:159] op_sel_hi:[0,1]
	v_pk_mul_f32 v[138:139], v[118:119], v[148:149] op_sel_hi:[0,1]
	v_pk_mul_f32 v[222:223], v[118:119], v[222:223] op_sel_hi:[0,1]
	v_pk_mul_f32 v[224:225], v[118:119], v[224:225] op_sel_hi:[0,1]
	v_pk_mul_f32 v[140:141], v[118:119], v[182:183] op_sel_hi:[0,1]
	v_pk_mul_f32 v[226:227], v[118:119], v[226:227] op_sel_hi:[0,1]
	v_pk_mul_f32 v[142:143], v[118:119], v[160:161] op_sel_hi:[0,1]
	v_pk_mul_f32 v[144:145], v[118:119], v[164:165] op_sel_hi:[0,1]
	v_pk_mul_f32 v[228:229], v[118:119], v[228:229] op_sel_hi:[0,1]
	v_pk_mul_f32 v[230:231], v[118:119], v[230:231] op_sel_hi:[0,1]
	v_pk_mul_f32 v[212:213], v[52:53], v[212:213]
	v_pk_mul_f32 v[116:117], v[50:51], v[116:117]
	v_pk_mul_f32 v[214:215], v[4:5], v[214:215]
	v_pk_mul_f32 v[118:119], v[2:3], v[122:123]
	v_pk_mul_f32 v[122:123], v[14:15], v[126:127]
	v_pk_mul_f32 v[126:127], v[44:45], v[208:209]
	v_pk_mul_f32 v[146:147], v[24:25], v[210:211]
	v_cvt_pk_bf16_f32 v208, v116, v117
	v_cvt_pk_bf16_f32 v209, v212, v213
	v_cvt_pk_bf16_f32 v210, v118, v119
	v_cvt_pk_bf16_f32 v211, v214, v215
	v_pk_mul_f32 v[200:201], v[8:9], v[200:201]
	v_pk_mul_f32 v[120:121], v[6:7], v[120:121]
	v_pk_mul_f32 v[202:203], v[12:13], v[202:203]
	v_pk_mul_f32 v[84:85], v[10:11], v[84:85]
	global_store_dwordx4 v[86:87], v[208:211], off offset:-4096
	v_pk_mul_f32 v[204:205], v[16:17], v[204:205]
	v_pk_mul_f32 v[124:125], v[20:21], v[124:125]
	v_cvt_pk_bf16_f32 v208, v120, v121
	v_cvt_pk_bf16_f32 v209, v200, v201
	v_cvt_pk_bf16_f32 v210, v84, v85
	v_cvt_pk_bf16_f32 v211, v202, v203
	v_pk_mul_f32 v[114:115], v[18:19], v[114:115]
	global_store_dwordx4 v[88:89], v[208:211], off offset:1024
	v_pk_mul_f32 v[206:207], v[42:43], v[206:207]
	v_pk_mul_f32 v[128:129], v[22:23], v[128:129]
	v_cvt_pk_bf16_f32 v208, v122, v123
	v_cvt_pk_bf16_f32 v209, v204, v205
	v_cvt_pk_bf16_f32 v210, v114, v115
	v_cvt_pk_bf16_f32 v211, v124, v125
	global_store_dwordx4 v[88:89], v[208:211], off offset:2048
	v_pk_mul_f32 v[132:133], v[28:29], v[132:133]
	v_pk_mul_f32 v[130:131], v[26:27], v[130:131]
	v_cvt_pk_bf16_f32 v208, v206, v207
	v_cvt_pk_bf16_f32 v209, v126, v127
	v_cvt_pk_bf16_f32 v210, v128, v129
	v_cvt_pk_bf16_f32 v211, v146, v147
	v_pk_mul_f32 v[218:219], v[36:37], v[218:219]
	v_pk_mul_f32 v[216:217], v[34:35], v[216:217]
	global_store_dwordx4 v[88:89], v[208:211], off offset:3072
	v_pk_mul_f32 v[220:221], v[32:33], v[220:221]
	v_pk_mul_f32 v[134:135], v[30:31], v[134:135]
	v_cvt_pk_bf16_f32 v208, v130, v131
	v_cvt_pk_bf16_f32 v209, v132, v133
	v_cvt_pk_bf16_f32 v210, v216, v217
	v_cvt_pk_bf16_f32 v211, v218, v219
	v_pk_mul_f32 v[138:139], v[40:41], v[138:139]
	v_pk_mul_f32 v[136:137], v[38:39], v[136:137]
; __device__ __forceinline__ u32x4 pack8(const f32x4 a, const f32x4 b) { u32x4 w; w.x = cvt_pk_bf16(a[0], a[1]); w.y = cvt_pk_bf16(a[2], a[3]); w.z = cvt_pk_bf16(b[0], b[1]); w.w = cvt_pk_bf16(b[2], b[3]); return w; }
; __device__ __forceinline__ void unpack8(const u32x4 w, f32x4& a, f32x4& b) { a = (f32x4){bflo(w.x), bfhi(w.x), bflo(w.y), bfhi(w.y)}; b = (f32x4){bflo(w.z), bfhi(w.z), bflo(w.w), bfhi(w.w)}; }
; __device__ __forceinline__ void load_xrow(Frame& F, int m, f32x4 (&v)[16]) {
;     const v4u* xr = (const v4u*)((const bf16*)(F.ws + WS_XRES) + (size_t)m * D) + F.lane;
;     v4u w[8];
; #pragma unroll
;     for (int j = 0; j < 8; ++j) w[j] = xr[64 * j];
; #pragma unroll
;     for (int j = 0; j < 8; ++j) pg8::unpack8(w[j], v[2 * j], v[2 * j + 1]);
; }
; __device__ __forceinline__ float row_rnorm(const f32x4 (&v)[16]) {
;     float s = 0.f;
; #pragma unroll
;     for (int j = 0; j < 16; ++j) s += (v[j].x * v[j].x + v[j].y * v[j].y) + (v[j].z * v[j].z + v[j].w * v[j].w);
; __device__ __forceinline__ void norm_phase(Frame& F, const float* gain, int nsplit, float scale, const float* samp_base) {
;     ...
;     for (int m = F.gw; m < NPROMPT; m += F.ngw) {
;         f32x4 v[16]; load_xrow(F, m, v);
;         const float r = row_rnorm(v);
;         v4u* o8 = (v4u*)((bf16*)(F.ws + WS_H) + (size_t)m * D) + F.lane;
; #pragma unroll
;         for (int j = 0; j < 8; ++j) o8[64 * j] = pg8::pack8(v[2 * j] * r * gn[2 * j], v[2 * j + 1] * r * gn[2 * j + 1]);
	global_store_dwordx4 v[86:87], v[208:211], off
	v_pk_mul_f32 v[224:225], v[48:49], v[224:225]
	v_pk_mul_f32 v[222:223], v[46:47], v[222:223]
	v_cvt_pk_bf16_f32 v208, v134, v135
	v_cvt_pk_bf16_f32 v209, v220, v221
	v_cvt_pk_bf16_f32 v210, v136, v137
	v_cvt_pk_bf16_f32 v211, v138, v139
	v_pk_mul_f32 v[226:227], v[60:61], v[226:227]
	v_pk_mul_f32 v[140:141], v[58:59], v[140:141]
	global_store_dwordx4 v[86:87], v[208:211], off offset:1024
	v_pk_mul_f32 v[144:145], v[56:57], v[144:145]
	v_pk_mul_f32 v[142:143], v[54:55], v[142:143]
	v_cvt_pk_bf16_f32 v208, v222, v223
	v_cvt_pk_bf16_f32 v209, v224, v225
	v_cvt_pk_bf16_f32 v210, v140, v141
	v_cvt_pk_bf16_f32 v211, v226, v227
	v_pk_mul_f32 v[230:231], v[64:65], v[230:231]
	v_pk_mul_f32 v[228:229], v[62:63], v[228:229]
	global_store_dwordx4 v[86:87], v[208:211], off offset:2048
	s_nop 1
	v_cvt_pk_bf16_f32 v208, v142, v143
	v_cvt_pk_bf16_f32 v209, v144, v145
	v_cvt_pk_bf16_f32 v210, v228, v229
	v_cvt_pk_bf16_f32 v211, v230, v231
	global_store_dwordx4 v[86:87], v[208:211], off offset:3072
	s_add_u32 s98, s98, s2
	s_addc_u32 s99, s99, s3
	s_add_u32 s100, s98, 0x1000
	s_addc_u32 s101, s99, 0
	global_load_dwordx4 v[200:203], v199, s[98:99] offset:1024
	global_load_dwordx4 v[204:207], v199, s[98:99] offset:2048
	global_load_dwordx4 v[208:211], v199, s[98:99] offset:3072
	global_load_dwordx4 v[212:215], v199, s[98:99]
	global_load_dwordx4 v[216:219], v199, s[100:101]
	global_load_dwordx4 v[220:223], v199, s[100:101] offset:1024
	global_load_dwordx4 v[224:227], v199, s[100:101] offset:2048
	global_load_dwordx4 v[228:231], v199, s[100:101] offset:3072
	v_add_co_u32_e32 v84, vcc, s4, v82
	v_add_co_u32_e64 v88, s[0:1], s8, v82
	s_nop 0
	v_addc_co_u32_e32 v85, vcc, 0, v83, vcc
	v_addc_co_u32_e64 v89, s[0:1], 0, v83, s[0:1]
	v_add_co_u32_e64 v86, s[0:1], s9, v82
	s_add_i32 s10, s10, s90
	s_nop 0
	v_addc_co_u32_e64 v87, s[0:1], 0, v83, s[0:1]
	v_lshl_add_u64 v[82:83], v[82:83], 0, s[2:3]
	s_cmpk_lt_i32 s10, 0x2000
	s_waitcnt vmcnt(16)
	v_lshlrev_b32_e32 v120, 16, v74
	v_and_b32_e32 v121, 0xffff0000, v74
	v_lshlrev_b32_e32 v74, 16, v75
	v_lshlrev_b32_e32 v116, 16, v78
	v_and_b32_e32 v117, 0xffff0000, v78
	v_lshlrev_b32_e32 v78, 16, v79
	v_lshlrev_b32_e32 v119, 16, v81
	v_lshlrev_b32_e32 v118, 16, v80
	v_and_b32_e32 v81, 0xffff0000, v81
	v_and_b32_e32 v80, 0xffff0000, v80
	v_and_b32_e32 v79, 0xffff0000, v79
	v_mul_f32_e32 v128, v116, v116
	v_mul_f32_e32 v130, v78, v78
	v_pk_mul_f32 v[132:133], v[80:81], v[80:81]
	v_and_b32_e32 v75, 0xffff0000, v75
	v_mul_f32_e32 v134, v120, v120
	v_mul_f32_e32 v136, v74, v74
	v_mov_b32_e32 v150, v118
	v_mov_b32_e32 v151, v80
	v_mov_b32_e32 v80, v119
	v_pk_fma_f32 v[128:129], v[116:117], v[116:117], v[128:129] op_sel_hi:[1,1,0]
	v_pk_fma_f32 v[130:131], v[78:79], v[78:79], v[130:131] op_sel_hi:[1,1,0]
	v_pk_fma_f32 v[118:119], v[118:119], v[118:119], v[132:133]
	v_lshlrev_b32_e32 v84, 16, v76
	v_and_b32_e32 v85, 0xffff0000, v76
	v_lshlrev_b32_e32 v76, 16, v77
	v_and_b32_e32 v77, 0xffff0000, v77
	v_pk_fma_f32 v[132:133], v[120:121], v[120:121], v[134:135] op_sel_hi:[1,1,0]
	v_pk_fma_f32 v[134:135], v[74:75], v[74:75], v[136:137] op_sel_hi:[1,1,0]
	v_pk_add_f32 v[118:119], v[118:119], v[118:119] op_sel_hi:[0,1]
	v_pk_add_f32 v[128:129], v[128:129], v[130:131]
	v_lshlrev_b32_e32 v123, 16, v71
	v_lshlrev_b32_e32 v122, 16, v70
	v_and_b32_e32 v71, 0xffff0000, v71
	v_and_b32_e32 v70, 0xffff0000, v70
	v_mul_f32_e32 v138, v84, v84
	v_mul_f32_e32 v132, v76, v76
	v_mul_f32_e32 v134, v77, v77
	v_mul_f32_e32 v118, v85, v85
	v_mov_b32_e32 v139, v129
	v_lshlrev_b32_e32 v114, 16, v72
	v_and_b32_e32 v115, 0xffff0000, v72
	v_lshlrev_b32_e32 v72, 16, v66
	v_lshlrev_b32_e32 v124, 16, v73
	v_pk_mul_f32 v[140:141], v[70:71], v[70:71]
	v_pk_add_f32 v[132:133], v[132:133], v[134:135]
	v_pk_add_f32 v[118:119], v[138:139], v[118:119]
	v_and_b32_e32 v125, 0xffff0000, v73
	v_lshlrev_b32_e32 v127, 16, v69
	v_lshlrev_b32_e32 v126, 16, v68
	v_and_b32_e32 v69, 0xffff0000, v69
	v_and_b32_e32 v68, 0xffff0000, v68
	v_mul_f32_e32 v73, v114, v114
	v_mul_f32_e32 v143, v115, v115
	v_mul_f32_e32 v144, v124, v124
	v_mov_b32_e32 v142, v72
	v_mov_b32_e32 v152, v122
	v_mov_b32_e32 v153, v70
	v_mov_b32_e32 v70, v123
	v_pk_fma_f32 v[122:123], v[122:123], v[122:123], v[140:141]
	v_pk_add_f32 v[118:119], v[118:119], v[132:133]
	v_and_b32_e32 v97, 0xffff0000, v66
	v_lshlrev_b32_e32 v66, 16, v67
	v_and_b32_e32 v67, 0xffff0000, v67
	v_pk_mul_f32 v[148:149], v[68:69], v[68:69]
	v_pk_fma_f32 v[136:137], v[124:125], v[124:125], v[144:145] op_sel_hi:[1,1,0]
	v_pk_add_f32 v[140:141], v[72:73], v[142:143]
	v_pk_add_f32 v[122:123], v[122:123], v[122:123] op_sel_hi:[0,1]
	v_pk_add_f32 v[118:119], v[118:119], v[118:119] op_sel_hi:[0,1]
	v_mul_f32_e32 v146, v72, v72
	v_mov_b32_e32 v154, v126
	v_mov_b32_e32 v155, v68
	v_mov_b32_e32 v68, v127
	v_pk_fma_f32 v[126:127], v[126:127], v[126:127], v[148:149]
	v_mul_f32_e32 v136, v97, v97
	v_mov_b32_e32 v147, v141
	v_mul_f32_e32 v122, v66, v66
	v_mul_f32_e32 v118, v67, v67
	v_lshlrev_b32_e32 v156, 16, v98
	v_and_b32_e32 v157, 0xffff0000, v98
	v_lshlrev_b32_e32 v98, 16, v100
	v_lshlrev_b32_e32 v142, 16, v99
	v_pk_add_f32 v[126:127], v[126:127], v[126:127] op_sel_hi:[0,1]
	v_pk_add_f32 v[134:135], v[146:147], v[136:137]
	v_pk_add_f32 v[118:119], v[122:123], v[118:119]
	v_and_b32_e32 v143, 0xffff0000, v99
	v_mul_f32_e32 v99, v156, v156
	v_mul_f32_e32 v131, v157, v157
	v_mul_f32_e32 v126, v142, v142
	v_mov_b32_e32 v130, v98
	v_pk_add_f32 v[118:119], v[134:135], v[118:119]
	s_waitcnt lgkmcnt(0)
; __device__ __forceinline__ u32x4 pack8(const f32x4 a, const f32x4 b) { u32x4 w; w.x = cvt_pk_bf16(a[0], a[1]); w.y = cvt_pk_bf16(a[2], a[3]); w.z = cvt_pk_bf16(b[0], b[1]); w.w = cvt_pk_bf16(b[2], b[3]); return w; }
; __device__ __forceinline__ float row_rnorm(const f32x4 (&v)[16]) {
;     float s = 0.f;
; #pragma unroll
;     for (int j = 0; j < 16; ++j) s += (v[j].x * v[j].x + v[j].y * v[j].y) + (v[j].z * v[j].z + v[j].w * v[j].w);
;     return 1.0f / sqrtf(wave_sum(s) * (1.0f / D) + EPS);
; }
; __device__ __forceinline__ void norm_phase(Frame& F, const float* gain, int nsplit, float scale, const float* samp_base) {
;     (void)nsplit;
;     norm_sample_row<false>(F, gain, scale, samp_base, nullptr);
;     f32x4 gn[16]; load_gain8(gain, F.lane, gn);
;     for (int m = F.gw; m < NPROMPT; m += F.ngw) {
;         f32x4 v[16]; load_xrow(F, m, v);
;         const float r = row_rnorm(v);
;         v4u* o8 = (v4u*)((bf16*)(F.ws + WS_H) + (size_t)m * D) + F.lane;
; #pragma unroll
;         for (int j = 0; j < 8; ++j) o8[64 * j] = pg8::pack8(v[2 * j] * r * gn[2 * j], v[2 * j + 1] * r * gn[2 * j + 1]);
	v_and_b32_e32 v171, 0xffff0000, v100
	v_lshlrev_b32_e32 v100, 16, v101
	v_and_b32_e32 v101, 0xffff0000, v101
	v_pk_fma_f32 v[136:137], v[142:143], v[142:143], v[126:127] op_sel_hi:[1,1,0]
	v_pk_add_f32 v[130:131], v[98:99], v[130:131]
	v_pk_add_f32 v[118:119], v[118:119], v[118:119] op_sel_hi:[0,1]
	v_lshlrev_b32_e32 v145, 16, v103
	v_lshlrev_b32_e32 v144, 16, v102
	v_and_b32_e32 v103, 0xffff0000, v103
	v_and_b32_e32 v102, 0xffff0000, v102
	v_mul_f32_e32 v128, v98, v98
	v_mul_f32_e32 v126, v100, v100
	v_mul_f32_e32 v136, v171, v171
	v_mov_b32_e32 v129, v131
	v_mul_f32_e32 v118, v101, v101
	v_lshlrev_b32_e32 v158, 16, v104
	v_and_b32_e32 v159, 0xffff0000, v104
	v_lshlrev_b32_e32 v104, 16, v106
	v_lshlrev_b32_e32 v148, 16, v105
	v_pk_mul_f32 v[140:141], v[102:103], v[102:103]
	v_pk_add_f32 v[128:129], v[128:129], v[136:137]
	v_pk_add_f32 v[118:119], v[126:127], v[118:119]
	v_and_b32_e32 v149, 0xffff0000, v105
	v_mul_f32_e32 v105, v158, v158
	v_mul_f32_e32 v167, v159, v159
	v_mul_f32_e32 v168, v148, v148
	v_mov_b32_e32 v166, v104
	v_pk_fma_f32 v[140:141], v[144:145], v[144:145], v[140:141]
	v_pk_add_f32 v[118:119], v[128:129], v[118:119]
	v_and_b32_e32 v177, 0xffff0000, v106
	v_lshlrev_b32_e32 v106, 16, v107
	v_and_b32_e32 v107, 0xffff0000, v107
	v_mov_b32_e32 v180, v144
	v_mov_b32_e32 v181, v102
	v_mov_b32_e32 v102, v145
	v_pk_fma_f32 v[144:145], v[148:149], v[148:149], v[168:169] op_sel_hi:[1,1,0]
	v_pk_add_f32 v[146:147], v[104:105], v[166:167]
	v_pk_add_f32 v[130:131], v[140:141], v[140:141] op_sel_hi:[0,1]
	v_pk_add_f32 v[118:119], v[118:119], v[118:119] op_sel_hi:[0,1]
	v_lshlrev_b32_e32 v163, 16, v109
	v_lshlrev_b32_e32 v162, 16, v108
	v_and_b32_e32 v109, 0xffff0000, v109
	v_and_b32_e32 v108, 0xffff0000, v108
	v_mul_f32_e32 v170, v104, v104
	v_mov_b32_e32 v99, v171
	v_mul_f32_e32 v144, v177, v177
	v_mov_b32_e32 v171, v147
	v_mul_f32_e32 v130, v106, v106
	v_mul_f32_e32 v118, v107, v107
	v_lshlrev_b32_e32 v160, 16, v110
	v_and_b32_e32 v161, 0xffff0000, v110
	v_lshlrev_b32_e32 v110, 16, v112
	v_lshlrev_b32_e32 v164, 16, v111
	v_pk_mul_f32 v[172:173], v[108:109], v[108:109]
	v_pk_add_f32 v[132:133], v[170:171], v[144:145]
	v_pk_add_f32 v[118:119], v[130:131], v[118:119]
	v_and_b32_e32 v165, 0xffff0000, v111
	v_mul_f32_e32 v111, v160, v160
	v_mul_f32_e32 v175, v161, v161
	v_mul_f32_e32 v176, v164, v164
	v_mov_b32_e32 v174, v110
	v_mov_b32_e32 v182, v162
	v_mov_b32_e32 v183, v108
	v_mov_b32_e32 v108, v163
	v_pk_fma_f32 v[162:163], v[162:163], v[162:163], v[172:173]
	v_pk_add_f32 v[118:119], v[132:133], v[118:119]
	v_and_b32_e32 v179, 0xffff0000, v112
	v_lshlrev_b32_e32 v112, 16, v113
	v_and_b32_e32 v113, 0xffff0000, v113
	v_pk_fma_f32 v[166:167], v[164:165], v[164:165], v[176:177] op_sel_hi:[1,1,0]
	v_pk_add_f32 v[168:169], v[110:111], v[174:175]
	v_pk_add_f32 v[138:139], v[162:163], v[162:163] op_sel_hi:[0,1]
	v_pk_add_f32 v[118:119], v[118:119], v[118:119] op_sel_hi:[0,1]
	v_mul_f32_e32 v178, v110, v110
	v_mov_b32_e32 v111, v179
	v_mul_f32_e32 v166, v179, v179
	v_mov_b32_e32 v179, v169
	v_mul_f32_e32 v138, v112, v112
	v_mul_f32_e32 v118, v113, v113
	v_pk_add_f32 v[136:137], v[178:179], v[166:167]
	v_pk_add_f32 v[118:119], v[138:139], v[118:119]
	v_mov_b32_e32 v73, v97
	v_pk_add_f32 v[118:119], v[136:137], v[118:119]
	v_mov_b32_e32 v105, v177
	v_add_f32_e32 v97, v118, v119
	ds_bpermute_b32 v118, v1, v97
	s_waitcnt lgkmcnt(0)
	v_add_f32_e32 v97, v97, v118
	ds_bpermute_b32 v118, v90, v97
	s_waitcnt lgkmcnt(0)
	v_add_f32_e32 v97, v97, v118
	ds_bpermute_b32 v118, v91, v97
	s_waitcnt lgkmcnt(0)
	v_add_f32_e32 v97, v97, v118
	ds_bpermute_b32 v118, v92, v97
	s_waitcnt lgkmcnt(0)
	v_add_f32_e32 v97, v97, v118
	ds_bpermute_b32 v118, v93, v97
	s_waitcnt lgkmcnt(0)
	v_add_f32_e32 v97, v97, v118
	ds_bpermute_b32 v118, v94, v97
	s_waitcnt lgkmcnt(0)
	v_add_f32_e32 v97, v97, v118
	v_fmamk_f32 v97, v97, 0x39800000, v95
	v_mul_f32_e32 v118, 0x4f800000, v97
	v_cmp_gt_f32_e32 vcc, s5, v97
	s_nop 1
	v_cndmask_b32_e32 v97, v97, v118, vcc
	v_sqrt_f32_e32 v118, v97
	s_nop 0
	v_add_u32_e32 v119, -1, v118
	v_add_u32_e32 v122, 1, v118
	v_fma_f32 v123, -v119, v118, v97
	v_fma_f32 v126, -v122, v118, v97
	v_cmp_ge_f32_e64 s[0:1], 0, v123
	s_nop 1
	v_cndmask_b32_e64 v118, v118, v119, s[0:1]
	v_cmp_lt_f32_e64 s[0:1], 0, v126
	s_nop 1
	v_cndmask_b32_e64 v118, v118, v122, s[0:1]
	v_mul_f32_e32 v119, 0x37800000, v118
	v_cndmask_b32_e32 v118, v118, v119, vcc
	v_cmp_class_f32_e32 vcc, v97, v96
	s_nop 1
	v_cndmask_b32_e32 v97, v118, v97, vcc
	v_div_scale_f32 v118, s[0:1], v97, v97, 1.0
	v_rcp_f32_e32 v122, v118
	v_div_scale_f32 v119, vcc, 1.0, v97, 1.0
	v_fma_f32 v123, -v118, v122, 1.0
	v_fmac_f32_e32 v122, v123, v122
	v_mul_f32_e32 v123, v119, v122
	v_fma_f32 v126, -v118, v123, v119
	v_fmac_f32_e32 v123, v126, v122
	v_fma_f32 v118, -v118, v123, v119
	v_div_fmas_f32 v118, v118, v122, v123
	v_div_fixup_f32 v118, v118, v97, 1.0
	v_pk_mul_f32 v[116:117], v[118:119], v[116:117] op_sel_hi:[0,1]
	v_pk_mul_f32 v[78:79], v[118:119], v[78:79] op_sel_hi:[0,1]
	v_pk_mul_f32 v[122:123], v[118:119], v[150:151] op_sel_hi:[0,1]
	v_pk_mul_f32 v[80:81], v[118:119], v[80:81] op_sel_hi:[0,1]
	v_pk_mul_f32 v[126:127], v[118:119], v[152:153] op_sel_hi:[0,1]
	v_pk_mul_f32 v[66:67], v[118:119], v[66:67] op_sel_hi:[0,1]
	v_pk_mul_f32 v[68:69], v[118:119], v[68:69] op_sel_hi:[0,1]
	v_pk_mul_f32 v[120:121], v[118:119], v[120:121] op_sel_hi:[0,1]
	v_pk_mul_f32 v[74:75], v[118:119], v[74:75] op_sel_hi:[0,1]
	v_pk_mul_f32 v[84:85], v[118:119], v[84:85] op_sel_hi:[0,1]
	v_pk_mul_f32 v[76:77], v[118:119], v[76:77] op_sel_hi:[0,1]
	v_pk_mul_f32 v[70:71], v[118:119], v[70:71] op_sel_hi:[0,1]
; __device__ __forceinline__ unsigned cvt_pk_bf16(float lo, float hi) { unsigned r; asm volatile("v_cvt_pk_bf16_f32 %0, %1, %2" : "=v"(r) : "v"(lo), "v"(hi)); return r; }
; __device__ __forceinline__ u32x4 pack8(const f32x4 a, const f32x4 b) { u32x4 w; w.x = cvt_pk_bf16(a[0], a[1]); w.y = cvt_pk_bf16(a[2], a[3]); w.z = cvt_pk_bf16(b[0], b[1]); w.w = cvt_pk_bf16(b[2], b[3]); return w; }
; __device__ __forceinline__ void norm_phase(Frame& F, const float* gain, int nsplit, float scale, const float* samp_base) {
;     ...
;     for (int m = F.gw; m < NPROMPT; m += F.ngw) {
;         f32x4 v[16]; load_xrow(F, m, v);
;         const float r = row_rnorm(v);
;         v4u* o8 = (v4u*)((bf16*)(F.ws + WS_H) + (size_t)m * D) + F.lane;
; #pragma unroll
;         for (int j = 0; j < 8; ++j) o8[64 * j] = pg8::pack8(v[2 * j] * r * gn[2 * j], v[2 * j + 1] * r * gn[2 * j + 1]);
;     }
	v_pk_mul_f32 v[114:115], v[118:119], v[114:115] op_sel_hi:[0,1]
	v_pk_mul_f32 v[124:125], v[118:119], v[124:125] op_sel_hi:[0,1]
	v_pk_mul_f32 v[72:73], v[118:119], v[72:73] op_sel_hi:[0,1]
	v_pk_mul_f32 v[128:129], v[118:119], v[154:155] op_sel_hi:[0,1]
	v_pk_mul_f32 v[130:131], v[118:119], v[156:157] op_sel_hi:[0,1]
	v_pk_mul_f32 v[132:133], v[118:119], v[142:143] op_sel_hi:[0,1]
	v_pk_mul_f32 v[98:99], v[118:119], v[98:99] op_sel_hi:[0,1]
	v_pk_mul_f32 v[100:101], v[118:119], v[100:101] op_sel_hi:[0,1]
	v_pk_mul_f32 v[134:135], v[118:119], v[180:181] op_sel_hi:[0,1]
	v_pk_mul_f32 v[102:103], v[118:119], v[102:103] op_sel_hi:[0,1]
	v_pk_mul_f32 v[136:137], v[118:119], v[158:159] op_sel_hi:[0,1]
	v_pk_mul_f32 v[138:139], v[118:119], v[148:149] op_sel_hi:[0,1]
	v_pk_mul_f32 v[104:105], v[118:119], v[104:105] op_sel_hi:[0,1]
	v_pk_mul_f32 v[106:107], v[118:119], v[106:107] op_sel_hi:[0,1]
	v_pk_mul_f32 v[140:141], v[118:119], v[182:183] op_sel_hi:[0,1]
	v_pk_mul_f32 v[108:109], v[118:119], v[108:109] op_sel_hi:[0,1]
	v_pk_mul_f32 v[142:143], v[118:119], v[160:161] op_sel_hi:[0,1]
	v_pk_mul_f32 v[144:145], v[118:119], v[164:165] op_sel_hi:[0,1]
	v_pk_mul_f32 v[110:111], v[118:119], v[110:111] op_sel_hi:[0,1]
	v_pk_mul_f32 v[112:113], v[118:119], v[112:113] op_sel_hi:[0,1]
	v_pk_mul_f32 v[78:79], v[52:53], v[78:79]
	v_pk_mul_f32 v[116:117], v[50:51], v[116:117]
	v_pk_mul_f32 v[80:81], v[4:5], v[80:81]
	v_pk_mul_f32 v[118:119], v[2:3], v[122:123]
	v_pk_mul_f32 v[122:123], v[14:15], v[126:127]
	v_pk_mul_f32 v[126:127], v[44:45], v[66:67]
	v_pk_mul_f32 v[146:147], v[24:25], v[68:69]
	v_cvt_pk_bf16_f32 v66, v116, v117
	v_cvt_pk_bf16_f32 v67, v78, v79
	v_cvt_pk_bf16_f32 v68, v118, v119
	v_cvt_pk_bf16_f32 v69, v80, v81
	v_pk_mul_f32 v[74:75], v[8:9], v[74:75]
	v_pk_mul_f32 v[120:121], v[6:7], v[120:121]
	v_pk_mul_f32 v[76:77], v[12:13], v[76:77]
	v_pk_mul_f32 v[84:85], v[10:11], v[84:85]
	global_store_dwordx4 v[86:87], v[66:69], off offset:-4096
	v_pk_mul_f32 v[70:71], v[16:17], v[70:71]
	v_pk_mul_f32 v[124:125], v[20:21], v[124:125]
	v_cvt_pk_bf16_f32 v66, v120, v121
	v_cvt_pk_bf16_f32 v67, v74, v75
	v_cvt_pk_bf16_f32 v68, v84, v85
	v_cvt_pk_bf16_f32 v69, v76, v77
	v_pk_mul_f32 v[114:115], v[18:19], v[114:115]
	global_store_dwordx4 v[88:89], v[66:69], off offset:1024
	v_pk_mul_f32 v[72:73], v[42:43], v[72:73]
	v_pk_mul_f32 v[128:129], v[22:23], v[128:129]
	v_cvt_pk_bf16_f32 v66, v122, v123
	v_cvt_pk_bf16_f32 v67, v70, v71
	v_cvt_pk_bf16_f32 v68, v114, v115
	v_cvt_pk_bf16_f32 v69, v124, v125
	global_store_dwordx4 v[88:89], v[66:69], off offset:2048
	v_pk_mul_f32 v[132:133], v[28:29], v[132:133]
	v_pk_mul_f32 v[130:131], v[26:27], v[130:131]
	v_cvt_pk_bf16_f32 v66, v72, v73
	v_cvt_pk_bf16_f32 v67, v126, v127
	v_cvt_pk_bf16_f32 v68, v128, v129
	v_cvt_pk_bf16_f32 v69, v146, v147
	v_pk_mul_f32 v[100:101], v[36:37], v[100:101]
	v_pk_mul_f32 v[98:99], v[34:35], v[98:99]
	global_store_dwordx4 v[88:89], v[66:69], off offset:3072
	v_pk_mul_f32 v[102:103], v[32:33], v[102:103]
	v_pk_mul_f32 v[134:135], v[30:31], v[134:135]
	v_cvt_pk_bf16_f32 v66, v130, v131
	v_cvt_pk_bf16_f32 v67, v132, v133
	v_cvt_pk_bf16_f32 v68, v98, v99
	v_cvt_pk_bf16_f32 v69, v100, v101
	v_pk_mul_f32 v[138:139], v[40:41], v[138:139]
	v_pk_mul_f32 v[136:137], v[38:39], v[136:137]
	global_store_dwordx4 v[86:87], v[66:69], off
	v_pk_mul_f32 v[106:107], v[48:49], v[106:107]
	v_pk_mul_f32 v[104:105], v[46:47], v[104:105]
	v_cvt_pk_bf16_f32 v66, v134, v135
	v_cvt_pk_bf16_f32 v67, v102, v103
	v_cvt_pk_bf16_f32 v68, v136, v137
	v_cvt_pk_bf16_f32 v69, v138, v139
	v_pk_mul_f32 v[108:109], v[60:61], v[108:109]
	v_pk_mul_f32 v[140:141], v[58:59], v[140:141]
	global_store_dwordx4 v[86:87], v[66:69], off offset:1024
	v_pk_mul_f32 v[144:145], v[56:57], v[144:145]
	v_pk_mul_f32 v[142:143], v[54:55], v[142:143]
	v_cvt_pk_bf16_f32 v66, v104, v105
	v_cvt_pk_bf16_f32 v67, v106, v107
	v_cvt_pk_bf16_f32 v68, v140, v141
	v_cvt_pk_bf16_f32 v69, v108, v109
	v_pk_mul_f32 v[112:113], v[64:65], v[112:113]
	v_pk_mul_f32 v[110:111], v[62:63], v[110:111]
	global_store_dwordx4 v[86:87], v[66:69], off offset:2048
	s_nop 1
	v_cvt_pk_bf16_f32 v66, v142, v143
	v_cvt_pk_bf16_f32 v67, v144, v145
	v_cvt_pk_bf16_f32 v68, v110, v111
	v_cvt_pk_bf16_f32 v69, v112, v113
	global_store_dwordx4 v[86:87], v[66:69], off offset:3072
	v_add_co_u32_e32 v84, vcc, s4, v82
	v_add_co_u32_e64 v88, s[0:1], s8, v82
	s_nop 0
	v_addc_co_u32_e32 v85, vcc, 0, v83, vcc
	v_addc_co_u32_e64 v89, s[0:1], 0, v83, s[0:1]
	v_add_co_u32_e64 v86, s[0:1], s9, v82
	s_add_i32 s10, s10, s90
	s_nop 0
	v_addc_co_u32_e64 v87, s[0:1], 0, v83, s[0:1]
	v_lshl_add_u64 v[82:83], v[82:83], 0, s[2:3]
	s_cmpk_lt_i32 s10, 0x2000
	s_waitcnt vmcnt(8)
; __device__ __forceinline__ void unpack8(const u32x4 w, f32x4& a, f32x4& b) { a = (f32x4){bflo(w.x), bfhi(w.x), bflo(w.y), bfhi(w.y)}; b = (f32x4){bflo(w.z), bfhi(w.z), bflo(w.w), bfhi(w.w)}; }
; __device__ __forceinline__ void load_xrow(Frame& F, int m, f32x4 (&v)[16]) {
;     const v4u* xr = (const v4u*)((const bf16*)(F.ws + WS_XRES) + (size_t)m * D) + F.lane;
;     v4u w[8];
; #pragma unroll
;     for (int j = 0; j < 8; ++j) w[j] = xr[64 * j];
; #pragma unroll
;     for (int j = 0; j < 8; ++j) pg8::unpack8(w[j], v[2 * j], v[2 * j + 1]);
; }
; __device__ __forceinline__ float row_rnorm(const f32x4 (&v)[16]) {
;     float s = 0.f;
; #pragma unroll
;     for (int j = 0; j < 16; ++j) s += (v[j].x * v[j].x + v[j].y * v[j].y) + (v[j].z * v[j].z + v[j].w * v[j].w);
;     return 1.0f / sqrtf(wave_sum(s) * (1.0f / D) + EPS);
	v_lshlrev_b32_e32 v120, 16, v200
	v_and_b32_e32 v121, 0xffff0000, v200
	v_lshlrev_b32_e32 v200, 16, v201
	v_lshlrev_b32_e32 v116, 16, v212
	v_and_b32_e32 v117, 0xffff0000, v212
	v_lshlrev_b32_e32 v212, 16, v213
	v_lshlrev_b32_e32 v119, 16, v215
	v_lshlrev_b32_e32 v118, 16, v214
	v_and_b32_e32 v215, 0xffff0000, v215
	v_and_b32_e32 v214, 0xffff0000, v214
	v_and_b32_e32 v213, 0xffff0000, v213
	v_mul_f32_e32 v128, v116, v116
	v_mul_f32_e32 v130, v212, v212
	v_pk_mul_f32 v[132:133], v[214:215], v[214:215]
	v_and_b32_e32 v201, 0xffff0000, v201
	v_mul_f32_e32 v134, v120, v120
	v_mul_f32_e32 v136, v200, v200
	v_mov_b32_e32 v150, v118
	v_mov_b32_e32 v151, v214
	v_mov_b32_e32 v214, v119
	v_pk_fma_f32 v[128:129], v[116:117], v[116:117], v[128:129] op_sel_hi:[1,1,0]
	v_pk_fma_f32 v[130:131], v[212:213], v[212:213], v[130:131] op_sel_hi:[1,1,0]
	v_pk_fma_f32 v[118:119], v[118:119], v[118:119], v[132:133]
	v_lshlrev_b32_e32 v84, 16, v202
	v_and_b32_e32 v85, 0xffff0000, v202
	v_lshlrev_b32_e32 v202, 16, v203
	v_and_b32_e32 v203, 0xffff0000, v203
	v_pk_fma_f32 v[132:133], v[120:121], v[120:121], v[134:135] op_sel_hi:[1,1,0]
	v_pk_fma_f32 v[134:135], v[200:201], v[200:201], v[136:137] op_sel_hi:[1,1,0]
	v_pk_add_f32 v[118:119], v[118:119], v[118:119] op_sel_hi:[0,1]
	v_pk_add_f32 v[128:129], v[128:129], v[130:131]
	v_lshlrev_b32_e32 v123, 16, v205
	v_lshlrev_b32_e32 v122, 16, v204
	v_and_b32_e32 v205, 0xffff0000, v205
	v_and_b32_e32 v204, 0xffff0000, v204
	v_mul_f32_e32 v138, v84, v84
	v_mul_f32_e32 v132, v202, v202
	v_mul_f32_e32 v134, v203, v203
	v_mul_f32_e32 v118, v85, v85
	v_mov_b32_e32 v139, v129
	v_lshlrev_b32_e32 v114, 16, v206
	v_and_b32_e32 v115, 0xffff0000, v206
	v_lshlrev_b32_e32 v206, 16, v208
	v_lshlrev_b32_e32 v124, 16, v207
	v_pk_mul_f32 v[140:141], v[204:205], v[204:205]
	v_pk_add_f32 v[132:133], v[132:133], v[134:135]
	v_pk_add_f32 v[118:119], v[138:139], v[118:119]
	v_and_b32_e32 v125, 0xffff0000, v207
	v_lshlrev_b32_e32 v127, 16, v211
	v_lshlrev_b32_e32 v126, 16, v210
	v_and_b32_e32 v211, 0xffff0000, v211
	v_and_b32_e32 v210, 0xffff0000, v210
	v_mul_f32_e32 v207, v114, v114
	v_mul_f32_e32 v143, v115, v115
	v_mul_f32_e32 v144, v124, v124
	v_mov_b32_e32 v142, v206
	v_mov_b32_e32 v152, v122
	v_mov_b32_e32 v153, v204
	v_mov_b32_e32 v204, v123
	v_pk_fma_f32 v[122:123], v[122:123], v[122:123], v[140:141]
	v_pk_add_f32 v[118:119], v[118:119], v[132:133]
	v_and_b32_e32 v97, 0xffff0000, v208
	v_lshlrev_b32_e32 v208, 16, v209
	v_and_b32_e32 v209, 0xffff0000, v209
	v_pk_mul_f32 v[148:149], v[210:211], v[210:211]
	v_pk_fma_f32 v[136:137], v[124:125], v[124:125], v[144:145] op_sel_hi:[1,1,0]
	v_pk_add_f32 v[140:141], v[206:207], v[142:143]
	v_pk_add_f32 v[122:123], v[122:123], v[122:123] op_sel_hi:[0,1]
	v_pk_add_f32 v[118:119], v[118:119], v[118:119] op_sel_hi:[0,1]
	v_mul_f32_e32 v146, v206, v206
	v_mov_b32_e32 v154, v126
	v_mov_b32_e32 v155, v210
	v_mov_b32_e32 v210, v127
	v_pk_fma_f32 v[126:127], v[126:127], v[126:127], v[148:149]
	v_mul_f32_e32 v136, v97, v97
	v_mov_b32_e32 v147, v141
	v_mul_f32_e32 v122, v208, v208
	v_mul_f32_e32 v118, v209, v209
	v_lshlrev_b32_e32 v156, 16, v216
	v_and_b32_e32 v157, 0xffff0000, v216
	v_lshlrev_b32_e32 v216, 16, v218
	v_lshlrev_b32_e32 v142, 16, v217
	v_pk_add_f32 v[126:127], v[126:127], v[126:127] op_sel_hi:[0,1]
	v_pk_add_f32 v[134:135], v[146:147], v[136:137]
	v_pk_add_f32 v[118:119], v[122:123], v[118:119]
	v_and_b32_e32 v143, 0xffff0000, v217
	v_mul_f32_e32 v217, v156, v156
	v_mul_f32_e32 v131, v157, v157
	v_mul_f32_e32 v126, v142, v142
	v_mov_b32_e32 v130, v216
	v_pk_add_f32 v[118:119], v[134:135], v[118:119]
	s_waitcnt lgkmcnt(0)
	v_and_b32_e32 v171, 0xffff0000, v218
	v_lshlrev_b32_e32 v218, 16, v219
	v_and_b32_e32 v219, 0xffff0000, v219
	v_pk_fma_f32 v[136:137], v[142:143], v[142:143], v[126:127] op_sel_hi:[1,1,0]
	v_pk_add_f32 v[130:131], v[216:217], v[130:131]
	v_pk_add_f32 v[118:119], v[118:119], v[118:119] op_sel_hi:[0,1]
	v_lshlrev_b32_e32 v145, 16, v221
	v_lshlrev_b32_e32 v144, 16, v220
	v_and_b32_e32 v221, 0xffff0000, v221
	v_and_b32_e32 v220, 0xffff0000, v220
	v_mul_f32_e32 v128, v216, v216
	v_mul_f32_e32 v126, v218, v218
	v_mul_f32_e32 v136, v171, v171
	v_mov_b32_e32 v129, v131
	v_mul_f32_e32 v118, v219, v219
	v_lshlrev_b32_e32 v158, 16, v222
	v_and_b32_e32 v159, 0xffff0000, v222
	v_lshlrev_b32_e32 v222, 16, v224
	v_lshlrev_b32_e32 v148, 16, v223
	v_pk_mul_f32 v[140:141], v[220:221], v[220:221]
	v_pk_add_f32 v[128:129], v[128:129], v[136:137]
	v_pk_add_f32 v[118:119], v[126:127], v[118:119]
	v_and_b32_e32 v149, 0xffff0000, v223
	v_mul_f32_e32 v223, v158, v158
	v_mul_f32_e32 v167, v159, v159
	v_mul_f32_e32 v168, v148, v148
	v_mov_b32_e32 v166, v222
	v_pk_fma_f32 v[140:141], v[144:145], v[144:145], v[140:141]
	v_pk_add_f32 v[118:119], v[128:129], v[118:119]
	v_and_b32_e32 v177, 0xffff0000, v224
	v_lshlrev_b32_e32 v224, 16, v225
	v_and_b32_e32 v225, 0xffff0000, v225
	v_mov_b32_e32 v180, v144
	v_mov_b32_e32 v181, v220
	v_mov_b32_e32 v220, v145
	v_pk_fma_f32 v[144:145], v[148:149], v[148:149], v[168:169] op_sel_hi:[1,1,0]
	v_pk_add_f32 v[146:147], v[222:223], v[166:167]
	v_pk_add_f32 v[130:131], v[140:141], v[140:141] op_sel_hi:[0,1]
	v_pk_add_f32 v[118:119], v[118:119], v[118:119] op_sel_hi:[0,1]
	v_lshlrev_b32_e32 v163, 16, v227
	v_lshlrev_b32_e32 v162, 16, v226
	v_and_b32_e32 v227, 0xffff0000, v227
	v_and_b32_e32 v226, 0xffff0000, v226
	v_mul_f32_e32 v170, v222, v222
	v_mov_b32_e32 v217, v171
	v_mul_f32_e32 v144, v177, v177
	v_mov_b32_e32 v171, v147
	v_mul_f32_e32 v130, v224, v224
	v_mul_f32_e32 v118, v225, v225
	v_lshlrev_b32_e32 v160, 16, v228
	v_and_b32_e32 v161, 0xffff0000, v228
	v_lshlrev_b32_e32 v228, 16, v230
	v_lshlrev_b32_e32 v164, 16, v229
	v_pk_mul_f32 v[172:173], v[226:227], v[226:227]
	v_pk_add_f32 v[132:133], v[170:171], v[144:145]
	v_pk_add_f32 v[118:119], v[130:131], v[118:119]
	v_and_b32_e32 v165, 0xffff0000, v229
	v_mul_f32_e32 v229, v160, v160
	v_mul_f32_e32 v175, v161, v161
	v_mul_f32_e32 v176, v164, v164
	v_mov_b32_e32 v174, v228
	v_mov_b32_e32 v182, v162
	v_mov_b32_e32 v183, v226
	v_mov_b32_e32 v226, v163
	v_pk_fma_f32 v[162:163], v[162:163], v[162:163], v[172:173]
	v_pk_add_f32 v[118:119], v[132:133], v[118:119]
	v_and_b32_e32 v179, 0xffff0000, v230
	v_lshlrev_b32_e32 v230, 16, v231
	v_and_b32_e32 v231, 0xffff0000, v231
	v_pk_fma_f32 v[166:167], v[164:165], v[164:165], v[176:177] op_sel_hi:[1,1,0]
	v_pk_add_f32 v[168:169], v[228:229], v[174:175]
	v_pk_add_f32 v[138:139], v[162:163], v[162:163] op_sel_hi:[0,1]
	v_pk_add_f32 v[118:119], v[118:119], v[118:119] op_sel_hi:[0,1]
	v_mul_f32_e32 v178, v228, v228
	v_mov_b32_e32 v229, v179
	v_mul_f32_e32 v166, v179, v179
	v_mov_b32_e32 v179, v169
	v_mul_f32_e32 v138, v230, v230
	v_mul_f32_e32 v118, v231, v231
	v_pk_add_f32 v[136:137], v[178:179], v[166:167]
	v_pk_add_f32 v[118:119], v[138:139], v[118:119]
	v_mov_b32_e32 v207, v97
	v_pk_add_f32 v[118:119], v[136:137], v[118:119]
	v_mov_b32_e32 v223, v177
	v_add_f32_e32 v97, v118, v119
	ds_bpermute_b32 v118, v1, v97
	s_waitcnt lgkmcnt(0)
; __device__ __forceinline__ u32x4 pack8(const f32x4 a, const f32x4 b) { u32x4 w; w.x = cvt_pk_bf16(a[0], a[1]); w.y = cvt_pk_bf16(a[2], a[3]); w.z = cvt_pk_bf16(b[0], b[1]); w.w = cvt_pk_bf16(b[2], b[3]); return w; }
; __device__ __forceinline__ float row_rnorm(const f32x4 (&v)[16]) {
;     float s = 0.f;
; #pragma unroll
;     for (int j = 0; j < 16; ++j) s += (v[j].x * v[j].x + v[j].y * v[j].y) + (v[j].z * v[j].z + v[j].w * v[j].w);
;     return 1.0f / sqrtf(wave_sum(s) * (1.0f / D) + EPS);
; }
; __device__ __forceinline__ void norm_phase(Frame& F, const float* gain, int nsplit, float scale, const float* samp_base) {
;     (void)nsplit;
;     norm_sample_row<false>(F, gain, scale, samp_base, nullptr);
;     f32x4 gn[16]; load_gain8(gain, F.lane, gn);
;     for (int m = F.gw; m < NPROMPT; m += F.ngw) {
;         f32x4 v[16]; load_xrow(F, m, v);
;         const float r = row_rnorm(v);
;         v4u* o8 = (v4u*)((bf16*)(F.ws + WS_H) + (size_t)m * D) + F.lane;
; #pragma unroll
;         for (int j = 0; j < 8; ++j) o8[64 * j] = pg8::pack8(v[2 * j] * r * gn[2 * j], v[2 * j + 1] * r * gn[2 * j + 1]);
;     }
	v_add_f32_e32 v97, v97, v118
	ds_bpermute_b32 v118, v90, v97
	s_waitcnt lgkmcnt(0)
	v_add_f32_e32 v97, v97, v118
	ds_bpermute_b32 v118, v91, v97
	s_waitcnt lgkmcnt(0)
	v_add_f32_e32 v97, v97, v118
	ds_bpermute_b32 v118, v92, v97
	s_waitcnt lgkmcnt(0)
	v_add_f32_e32 v97, v97, v118
	ds_bpermute_b32 v118, v93, v97
	s_waitcnt lgkmcnt(0)
	v_add_f32_e32 v97, v97, v118
	ds_bpermute_b32 v118, v94, v97
	s_waitcnt lgkmcnt(0)
	v_add_f32_e32 v97, v97, v118
	v_fmamk_f32 v97, v97, 0x39800000, v95
	v_mul_f32_e32 v118, 0x4f800000, v97
	v_cmp_gt_f32_e32 vcc, s5, v97
	s_nop 1
	v_cndmask_b32_e32 v97, v97, v118, vcc
	v_sqrt_f32_e32 v118, v97
	s_nop 0
	v_add_u32_e32 v119, -1, v118
	v_add_u32_e32 v122, 1, v118
	v_fma_f32 v123, -v119, v118, v97
	v_fma_f32 v126, -v122, v118, v97
	v_cmp_ge_f32_e64 s[0:1], 0, v123
	s_nop 1
	v_cndmask_b32_e64 v118, v118, v119, s[0:1]
	v_cmp_lt_f32_e64 s[0:1], 0, v126
	s_nop 1
	v_cndmask_b32_e64 v118, v118, v122, s[0:1]
	v_mul_f32_e32 v119, 0x37800000, v118
	v_cndmask_b32_e32 v118, v118, v119, vcc
	v_cmp_class_f32_e32 vcc, v97, v96
	s_nop 1
	v_cndmask_b32_e32 v97, v118, v97, vcc
	v_div_scale_f32 v118, s[0:1], v97, v97, 1.0
	v_rcp_f32_e32 v122, v118
	v_div_scale_f32 v119, vcc, 1.0, v97, 1.0
	v_fma_f32 v123, -v118, v122, 1.0
	v_fmac_f32_e32 v122, v123, v122
	v_mul_f32_e32 v123, v119, v122
	v_fma_f32 v126, -v118, v123, v119
	v_fmac_f32_e32 v123, v126, v122
	v_fma_f32 v118, -v118, v123, v119
	v_div_fmas_f32 v118, v118, v122, v123
	v_div_fixup_f32 v118, v118, v97, 1.0
	v_pk_mul_f32 v[116:117], v[118:119], v[116:117] op_sel_hi:[0,1]
	v_pk_mul_f32 v[212:213], v[118:119], v[212:213] op_sel_hi:[0,1]
	v_pk_mul_f32 v[122:123], v[118:119], v[150:151] op_sel_hi:[0,1]
	v_pk_mul_f32 v[214:215], v[118:119], v[214:215] op_sel_hi:[0,1]
	v_pk_mul_f32 v[126:127], v[118:119], v[152:153] op_sel_hi:[0,1]
	v_pk_mul_f32 v[208:209], v[118:119], v[208:209] op_sel_hi:[0,1]
	v_pk_mul_f32 v[210:211], v[118:119], v[210:211] op_sel_hi:[0,1]
	v_pk_mul_f32 v[120:121], v[118:119], v[120:121] op_sel_hi:[0,1]
	v_pk_mul_f32 v[200:201], v[118:119], v[200:201] op_sel_hi:[0,1]
	v_pk_mul_f32 v[84:85], v[118:119], v[84:85] op_sel_hi:[0,1]
	v_pk_mul_f32 v[202:203], v[118:119], v[202:203] op_sel_hi:[0,1]
	v_pk_mul_f32 v[204:205], v[118:119], v[204:205] op_sel_hi:[0,1]
	v_pk_mul_f32 v[114:115], v[118:119], v[114:115] op_sel_hi:[0,1]
	v_pk_mul_f32 v[124:125], v[118:119], v[124:125] op_sel_hi:[0,1]
	v_pk_mul_f32 v[206:207], v[118:119], v[206:207] op_sel_hi:[0,1]
	v_pk_mul_f32 v[128:129], v[118:119], v[154:155] op_sel_hi:[0,1]
	v_pk_mul_f32 v[130:131], v[118:119], v[156:157] op_sel_hi:[0,1]
	v_pk_mul_f32 v[132:133], v[118:119], v[142:143] op_sel_hi:[0,1]
	v_pk_mul_f32 v[216:217], v[118:119], v[216:217] op_sel_hi:[0,1]
	v_pk_mul_f32 v[218:219], v[118:119], v[218:219] op_sel_hi:[0,1]
	v_pk_mul_f32 v[134:135], v[118:119], v[180:181] op_sel_hi:[0,1]
	v_pk_mul_f32 v[220:221], v[118:119], v[220:221] op_sel_hi:[0,1]
	v_pk_mul_f32 v[136:137], v[118:119], v[158:159] op_sel_hi:[0,1]
	v_pk_mul_f32 v[138:139], v[118:119], v[148:149] op_sel_hi:[0,1]
	v_pk_mul_f32 v[222:223], v[118:119], v[222:223] op_sel_hi:[0,1]
	v_pk_mul_f32 v[224:225], v[118:119], v[224:225] op_sel_hi:[0,1]
	v_pk_mul_f32 v[140:141], v[118:119], v[182:183] op_sel_hi:[0,1]
	v_pk_mul_f32 v[226:227], v[118:119], v[226:227] op_sel_hi:[0,1]
	v_pk_mul_f32 v[142:143], v[118:119], v[160:161] op_sel_hi:[0,1]
	v_pk_mul_f32 v[144:145], v[118:119], v[164:165] op_sel_hi:[0,1]
	v_pk_mul_f32 v[228:229], v[118:119], v[228:229] op_sel_hi:[0,1]
	v_pk_mul_f32 v[230:231], v[118:119], v[230:231] op_sel_hi:[0,1]
	v_pk_mul_f32 v[212:213], v[52:53], v[212:213]
	v_pk_mul_f32 v[116:117], v[50:51], v[116:117]
	v_pk_mul_f32 v[214:215], v[4:5], v[214:215]
	v_pk_mul_f32 v[118:119], v[2:3], v[122:123]
	v_pk_mul_f32 v[122:123], v[14:15], v[126:127]
	v_pk_mul_f32 v[126:127], v[44:45], v[208:209]
	v_pk_mul_f32 v[146:147], v[24:25], v[210:211]
	v_cvt_pk_bf16_f32 v208, v116, v117
	v_cvt_pk_bf16_f32 v209, v212, v213
	v_cvt_pk_bf16_f32 v210, v118, v119
	v_cvt_pk_bf16_f32 v211, v214, v215
	v_pk_mul_f32 v[200:201], v[8:9], v[200:201]
	v_pk_mul_f32 v[120:121], v[6:7], v[120:121]
	v_pk_mul_f32 v[202:203], v[12:13], v[202:203]
	v_pk_mul_f32 v[84:85], v[10:11], v[84:85]
	global_store_dwordx4 v[86:87], v[208:211], off offset:-4096
	v_pk_mul_f32 v[204:205], v[16:17], v[204:205]
	v_pk_mul_f32 v[124:125], v[20:21], v[124:125]
	v_cvt_pk_bf16_f32 v208, v120, v121
	v_cvt_pk_bf16_f32 v209, v200, v201
	v_cvt_pk_bf16_f32 v210, v84, v85
	v_cvt_pk_bf16_f32 v211, v202, v203
	v_pk_mul_f32 v[114:115], v[18:19], v[114:115]
	global_store_dwordx4 v[88:89], v[208:211], off offset:1024
	v_pk_mul_f32 v[206:207], v[42:43], v[206:207]
	v_pk_mul_f32 v[128:129], v[22:23], v[128:129]
	v_cvt_pk_bf16_f32 v208, v122, v123
	v_cvt_pk_bf16_f32 v209, v204, v205
	v_cvt_pk_bf16_f32 v210, v114, v115
	v_cvt_pk_bf16_f32 v211, v124, v125
	global_store_dwordx4 v[88:89], v[208:211], off offset:2048
	v_pk_mul_f32 v[132:133], v[28:29], v[132:133]
	v_pk_mul_f32 v[130:131], v[26:27], v[130:131]
	v_cvt_pk_bf16_f32 v208, v206, v207
	v_cvt_pk_bf16_f32 v209, v126, v127
	v_cvt_pk_bf16_f32 v210, v128, v129
	v_cvt_pk_bf16_f32 v211, v146, v147
	v_pk_mul_f32 v[218:219], v[36:37], v[218:219]
	v_pk_mul_f32 v[216:217], v[34:35], v[216:217]
	global_store_dwordx4 v[88:89], v[208:211], off offset:3072
	v_pk_mul_f32 v[220:221], v[32:33], v[220:221]
	v_pk_mul_f32 v[134:135], v[30:31], v[134:135]
	v_cvt_pk_bf16_f32 v208, v130, v131
	v_cvt_pk_bf16_f32 v209, v132, v133
	v_cvt_pk_bf16_f32 v210, v216, v217
	v_cvt_pk_bf16_f32 v211, v218, v219
	v_pk_mul_f32 v[138:139], v[40:41], v[138:139]
	v_pk_mul_f32 v[136:137], v[38:39], v[136:137]
	global_store_dwordx4 v[86:87], v[208:211], off
	v_pk_mul_f32 v[224:225], v[48:49], v[224:225]
	v_pk_mul_f32 v[222:223], v[46:47], v[222:223]
	v_cvt_pk_bf16_f32 v208, v134, v135
	v_cvt_pk_bf16_f32 v209, v220, v221
	v_cvt_pk_bf16_f32 v210, v136, v137
	v_cvt_pk_bf16_f32 v211, v138, v139
	v_pk_mul_f32 v[226:227], v[60:61], v[226:227]
	v_pk_mul_f32 v[140:141], v[58:59], v[140:141]
	global_store_dwordx4 v[86:87], v[208:211], off offset:1024
	v_pk_mul_f32 v[144:145], v[56:57], v[144:145]
	v_pk_mul_f32 v[142:143], v[54:55], v[142:143]
	v_cvt_pk_bf16_f32 v208, v222, v223
	v_cvt_pk_bf16_f32 v209, v224, v225
	v_cvt_pk_bf16_f32 v210, v140, v141
	v_cvt_pk_bf16_f32 v211, v226, v227
	v_pk_mul_f32 v[230:231], v[64:65], v[230:231]
	v_pk_mul_f32 v[228:229], v[62:63], v[228:229]
	global_store_dwordx4 v[86:87], v[208:211], off offset:2048
	s_nop 1
	v_cvt_pk_bf16_f32 v208, v142, v143
	v_cvt_pk_bf16_f32 v209, v144, v145
	v_cvt_pk_bf16_f32 v210, v228, v229
	v_cvt_pk_bf16_f32 v211, v230, v231
	global_store_dwordx4 v[86:87], v[208:211], off offset:3072

; __device__ __forceinline__ void unpack8(const u32x4 w, f32x4& a, f32x4& b) { a = (f32x4){bflo(w.x), bfhi(w.x), bflo(w.y), bfhi(w.y)}; b = (f32x4){bflo(w.z), bfhi(w.z), bflo(w.w), bfhi(w.w)}; }
; __device__ __forceinline__ void load_xrow(Frame& F, int m, f32x4 (&v)[16]) {
;     const v4u* xr = (const v4u*)((const bf16*)(F.ws + WS_XRES) + (size_t)m * D) + F.lane;
;     v4u w[8];
; #pragma unroll
;     for (int j = 0; j < 8; ++j) w[j] = xr[64 * j];
; #pragma unroll
;     for (int j = 0; j < 8; ++j) pg8::unpack8(w[j], v[2 * j], v[2 * j + 1]);
; }
; __device__ __forceinline__ float row_rnorm(const f32x4 (&v)[16]) {
;     float s = 0.f;
; #pragma unroll
;     for (int j = 0; j < 16; ++j) s += (v[j].x * v[j].x + v[j].y * v[j].y) + (v[j].z * v[j].z + v[j].w * v[j].w);
;     return 1.0f / sqrtf(wave_sum(s) * (1.0f / D) + EPS);
; }
; __device__ __forceinline__ void norm_phase(Frame& F, const float* gain, int nsplit, float scale, const float* samp_base) {
;     (void)nsplit;
;     norm_sample_row<false>(F, gain, scale, samp_base, nullptr);
;     f32x4 gn[16]; load_gain8(gain, F.lane, gn);
;     for (int m = F.gw; m < NPROMPT; m += F.ngw) {
;         f32x4 v[16]; load_xrow(F, m, v);
;         const float r = row_rnorm(v);
.LBB0_1242:
	v_lshlrev_b32_e32 v199, 4, v198
	v_readfirstlane_b32 s98, v82
	v_readfirstlane_b32 s99, v83
	s_nop 4
	global_load_dwordx4 v[74:77], v[82:83], off offset:1024
	global_load_dwordx4 v[70:73], v[82:83], off offset:2048
	global_load_dwordx4 v[66:69], v[82:83], off offset:3072
	global_load_dwordx4 v[78:81], v[82:83], off
	v_add_co_u32_e32 v84, vcc, s4, v82
	v_add_co_u32_e64 v88, s[0:1], s8, v82
	s_nop 0
	v_addc_co_u32_e32 v85, vcc, 0, v83, vcc
	global_load_dwordx4 v[98:101], v[84:85], off
	global_load_dwordx4 v[102:105], v[84:85], off offset:1024
	global_load_dwordx4 v[106:109], v[84:85], off offset:2048
	global_load_dwordx4 v[110:113], v[84:85], off offset:3072
	s_add_u32 s98, s98, s2
	s_addc_u32 s99, s99, s3
	s_add_u32 s100, s98, 0x1000
	s_addc_u32 s101, s99, 0
	global_load_dwordx4 v[200:203], v199, s[98:99] offset:1024
	global_load_dwordx4 v[204:207], v199, s[98:99] offset:2048
	global_load_dwordx4 v[208:211], v199, s[98:99] offset:3072
	global_load_dwordx4 v[212:215], v199, s[98:99]
	global_load_dwordx4 v[216:219], v199, s[100:101]
	global_load_dwordx4 v[220:223], v199, s[100:101] offset:1024
	global_load_dwordx4 v[224:227], v199, s[100:101] offset:2048
	global_load_dwordx4 v[228:231], v199, s[100:101] offset:3072
	v_addc_co_u32_e64 v89, s[0:1], 0, v83, s[0:1]
	v_add_co_u32_e64 v86, s[0:1], s9, v82
	s_add_i32 s10, s10, s90
	s_nop 0
	v_addc_co_u32_e64 v87, s[0:1], 0, v83, s[0:1]
	v_lshl_add_u64 v[82:83], v[82:83], 0, s[2:3]
	s_cmpk_lt_i32 s10, 0x2000
	s_waitcnt vmcnt(15)
	v_lshlrev_b32_e32 v120, 16, v74
	v_and_b32_e32 v121, 0xffff0000, v74
	v_lshlrev_b32_e32 v74, 16, v75
	s_waitcnt vmcnt(12)
	v_lshlrev_b32_e32 v116, 16, v78
	v_and_b32_e32 v117, 0xffff0000, v78
	v_lshlrev_b32_e32 v78, 16, v79
	v_lshlrev_b32_e32 v119, 16, v81
	v_lshlrev_b32_e32 v118, 16, v80
	v_and_b32_e32 v81, 0xffff0000, v81
	v_and_b32_e32 v80, 0xffff0000, v80
	v_and_b32_e32 v79, 0xffff0000, v79
	v_mul_f32_e32 v128, v116, v116
	v_mul_f32_e32 v130, v78, v78
	v_pk_mul_f32 v[132:133], v[80:81], v[80:81]
	v_and_b32_e32 v75, 0xffff0000, v75
	v_mul_f32_e32 v134, v120, v120
	v_mul_f32_e32 v136, v74, v74
	v_mov_b32_e32 v150, v118
	v_mov_b32_e32 v151, v80
	v_mov_b32_e32 v80, v119
	v_pk_fma_f32 v[128:129], v[116:117], v[116:117], v[128:129] op_sel_hi:[1,1,0]
	v_pk_fma_f32 v[130:131], v[78:79], v[78:79], v[130:131] op_sel_hi:[1,1,0]
	v_pk_fma_f32 v[118:119], v[118:119], v[118:119], v[132:133]
	v_lshlrev_b32_e32 v84, 16, v76
	v_and_b32_e32 v85, 0xffff0000, v76
	v_lshlrev_b32_e32 v76, 16, v77
	v_and_b32_e32 v77, 0xffff0000, v77
	v_pk_fma_f32 v[132:133], v[120:121], v[120:121], v[134:135] op_sel_hi:[1,1,0]
	v_pk_fma_f32 v[134:135], v[74:75], v[74:75], v[136:137] op_sel_hi:[1,1,0]
	v_pk_add_f32 v[118:119], v[118:119], v[118:119] op_sel_hi:[0,1]
	v_pk_add_f32 v[128:129], v[128:129], v[130:131]
	v_lshlrev_b32_e32 v123, 16, v71
	v_lshlrev_b32_e32 v122, 16, v70
	v_and_b32_e32 v71, 0xffff0000, v71
	v_and_b32_e32 v70, 0xffff0000, v70
	v_mul_f32_e32 v138, v84, v84
	v_mul_f32_e32 v132, v76, v76
	v_mul_f32_e32 v134, v77, v77
	v_mul_f32_e32 v118, v85, v85
	v_mov_b32_e32 v139, v129
	v_lshlrev_b32_e32 v114, 16, v72
	v_and_b32_e32 v115, 0xffff0000, v72
	v_lshlrev_b32_e32 v72, 16, v66
	v_lshlrev_b32_e32 v124, 16, v73
	v_pk_mul_f32 v[140:141], v[70:71], v[70:71]
	v_pk_add_f32 v[132:133], v[132:133], v[134:135]
	v_pk_add_f32 v[118:119], v[138:139], v[118:119]
	v_and_b32_e32 v125, 0xffff0000, v73
	v_lshlrev_b32_e32 v127, 16, v69
	v_lshlrev_b32_e32 v126, 16, v68
	v_and_b32_e32 v69, 0xffff0000, v69
	v_and_b32_e32 v68, 0xffff0000, v68
	v_mul_f32_e32 v73, v114, v114
	v_mul_f32_e32 v143, v115, v115
	v_mul_f32_e32 v144, v124, v124
	v_mov_b32_e32 v142, v72
	v_mov_b32_e32 v152, v122
	v_mov_b32_e32 v153, v70
	v_mov_b32_e32 v70, v123
	v_pk_fma_f32 v[122:123], v[122:123], v[122:123], v[140:141]
	v_pk_add_f32 v[118:119], v[118:119], v[132:133]
	v_and_b32_e32 v97, 0xffff0000, v66
	v_lshlrev_b32_e32 v66, 16, v67
	v_and_b32_e32 v67, 0xffff0000, v67
	v_pk_mul_f32 v[148:149], v[68:69], v[68:69]
	v_pk_fma_f32 v[136:137], v[124:125], v[124:125], v[144:145] op_sel_hi:[1,1,0]
	v_pk_add_f32 v[140:141], v[72:73], v[142:143]
	v_pk_add_f32 v[122:123], v[122:123], v[122:123] op_sel_hi:[0,1]
	v_pk_add_f32 v[118:119], v[118:119], v[118:119] op_sel_hi:[0,1]
	v_mul_f32_e32 v146, v72, v72
	v_mov_b32_e32 v154, v126
	v_mov_b32_e32 v155, v68
	v_mov_b32_e32 v68, v127
	v_pk_fma_f32 v[126:127], v[126:127], v[126:127], v[148:149]
	v_mul_f32_e32 v136, v97, v97
	v_mov_b32_e32 v147, v141
	v_mul_f32_e32 v122, v66, v66
	v_mul_f32_e32 v118, v67, v67
	s_waitcnt vmcnt(11)
	v_lshlrev_b32_e32 v156, 16, v98
	v_and_b32_e32 v157, 0xffff0000, v98
	v_lshlrev_b32_e32 v98, 16, v100
	v_lshlrev_b32_e32 v142, 16, v99
	v_pk_add_f32 v[126:127], v[126:127], v[126:127] op_sel_hi:[0,1]
	v_pk_add_f32 v[134:135], v[146:147], v[136:137]
	v_pk_add_f32 v[118:119], v[122:123], v[118:119]
	v_and_b32_e32 v143, 0xffff0000, v99
	v_mul_f32_e32 v99, v156, v156
	v_mul_f32_e32 v131, v157, v157
	v_mul_f32_e32 v126, v142, v142
	v_mov_b32_e32 v130, v98
	v_pk_add_f32 v[118:119], v[134:135], v[118:119]
	v_and_b32_e32 v171, 0xffff0000, v100
	v_lshlrev_b32_e32 v100, 16, v101
	v_and_b32_e32 v101, 0xffff0000, v101
	v_pk_fma_f32 v[136:137], v[142:143], v[142:143], v[126:127] op_sel_hi:[1,1,0]
	v_pk_add_f32 v[130:131], v[98:99], v[130:131]
	v_pk_add_f32 v[118:119], v[118:119], v[118:119] op_sel_hi:[0,1]
	s_waitcnt vmcnt(10)
	v_lshlrev_b32_e32 v145, 16, v103
	v_lshlrev_b32_e32 v144, 16, v102
	v_and_b32_e32 v103, 0xffff0000, v103
	v_and_b32_e32 v102, 0xffff0000, v102
	v_mul_f32_e32 v128, v98, v98
	v_mul_f32_e32 v126, v100, v100
	v_mul_f32_e32 v136, v171, v171
	v_mov_b32_e32 v129, v131
	v_mul_f32_e32 v118, v101, v101
	v_lshlrev_b32_e32 v158, 16, v104
	v_and_b32_e32 v159, 0xffff0000, v104
	s_waitcnt vmcnt(9)
; __device__ __forceinline__ u32x4 pack8(const f32x4 a, const f32x4 b) { u32x4 w; w.x = cvt_pk_bf16(a[0], a[1]); w.y = cvt_pk_bf16(a[2], a[3]); w.z = cvt_pk_bf16(b[0], b[1]); w.w = cvt_pk_bf16(b[2], b[3]); return w; }
; __device__ __forceinline__ float row_rnorm(const f32x4 (&v)[16]) {
;     float s = 0.f;
; #pragma unroll
;     for (int j = 0; j < 16; ++j) s += (v[j].x * v[j].x + v[j].y * v[j].y) + (v[j].z * v[j].z + v[j].w * v[j].w);
;     return 1.0f / sqrtf(wave_sum(s) * (1.0f / D) + EPS);
; }
; __device__ __forceinline__ void norm_phase(Frame& F, const float* gain, int nsplit, float scale, const float* samp_base) {
;     (void)nsplit;
;     norm_sample_row<false>(F, gain, scale, samp_base, nullptr);
;     f32x4 gn[16]; load_gain8(gain, F.lane, gn);
;     for (int m = F.gw; m < NPROMPT; m += F.ngw) {
;         f32x4 v[16]; load_xrow(F, m, v);
;         const float r = row_rnorm(v);
;         v4u* o8 = (v4u*)((bf16*)(F.ws + WS_H) + (size_t)m * D) + F.lane;
; #pragma unroll
;         for (int j = 0; j < 8; ++j) o8[64 * j] = pg8::pack8(v[2 * j] * r * gn[2 * j], v[2 * j + 1] * r * gn[2 * j + 1]);
	v_lshlrev_b32_e32 v104, 16, v106
	v_lshlrev_b32_e32 v148, 16, v105
	v_pk_mul_f32 v[140:141], v[102:103], v[102:103]
	v_pk_add_f32 v[128:129], v[128:129], v[136:137]
	v_pk_add_f32 v[118:119], v[126:127], v[118:119]
	v_and_b32_e32 v149, 0xffff0000, v105
	v_mul_f32_e32 v105, v158, v158
	v_mul_f32_e32 v167, v159, v159
	v_mul_f32_e32 v168, v148, v148
	v_mov_b32_e32 v166, v104
	v_pk_fma_f32 v[140:141], v[144:145], v[144:145], v[140:141]
	v_pk_add_f32 v[118:119], v[128:129], v[118:119]
	v_and_b32_e32 v177, 0xffff0000, v106
	v_lshlrev_b32_e32 v106, 16, v107
	v_and_b32_e32 v107, 0xffff0000, v107
	v_mov_b32_e32 v180, v144
	v_mov_b32_e32 v181, v102
	v_mov_b32_e32 v102, v145
	v_pk_fma_f32 v[144:145], v[148:149], v[148:149], v[168:169] op_sel_hi:[1,1,0]
	v_pk_add_f32 v[146:147], v[104:105], v[166:167]
	v_pk_add_f32 v[130:131], v[140:141], v[140:141] op_sel_hi:[0,1]
	v_pk_add_f32 v[118:119], v[118:119], v[118:119] op_sel_hi:[0,1]
	v_lshlrev_b32_e32 v163, 16, v109
	v_lshlrev_b32_e32 v162, 16, v108
	v_and_b32_e32 v109, 0xffff0000, v109
	v_and_b32_e32 v108, 0xffff0000, v108
	v_mul_f32_e32 v170, v104, v104
	v_mov_b32_e32 v99, v171
	v_mul_f32_e32 v144, v177, v177
	v_mov_b32_e32 v171, v147
	v_mul_f32_e32 v130, v106, v106
	v_mul_f32_e32 v118, v107, v107
	s_waitcnt vmcnt(8)
	v_lshlrev_b32_e32 v160, 16, v110
	v_and_b32_e32 v161, 0xffff0000, v110
	v_lshlrev_b32_e32 v110, 16, v112
	v_lshlrev_b32_e32 v164, 16, v111
	v_pk_mul_f32 v[172:173], v[108:109], v[108:109]
	v_pk_add_f32 v[132:133], v[170:171], v[144:145]
	v_pk_add_f32 v[118:119], v[130:131], v[118:119]
	v_and_b32_e32 v165, 0xffff0000, v111
	v_mul_f32_e32 v111, v160, v160
	v_mul_f32_e32 v175, v161, v161
	v_mul_f32_e32 v176, v164, v164
	v_mov_b32_e32 v174, v110
	v_mov_b32_e32 v182, v162
	v_mov_b32_e32 v183, v108
	v_mov_b32_e32 v108, v163
	v_pk_fma_f32 v[162:163], v[162:163], v[162:163], v[172:173]
	v_pk_add_f32 v[118:119], v[132:133], v[118:119]
	v_and_b32_e32 v179, 0xffff0000, v112
	v_lshlrev_b32_e32 v112, 16, v113
	v_and_b32_e32 v113, 0xffff0000, v113
	v_pk_fma_f32 v[166:167], v[164:165], v[164:165], v[176:177] op_sel_hi:[1,1,0]
	v_pk_add_f32 v[168:169], v[110:111], v[174:175]
	v_pk_add_f32 v[138:139], v[162:163], v[162:163] op_sel_hi:[0,1]
	v_pk_add_f32 v[118:119], v[118:119], v[118:119] op_sel_hi:[0,1]
	v_mul_f32_e32 v178, v110, v110
	v_mov_b32_e32 v111, v179
	v_mul_f32_e32 v166, v179, v179
	v_mov_b32_e32 v179, v169
	v_mul_f32_e32 v138, v112, v112
	v_mul_f32_e32 v118, v113, v113
	v_pk_add_f32 v[136:137], v[178:179], v[166:167]
	v_pk_add_f32 v[118:119], v[138:139], v[118:119]
	v_mov_b32_e32 v73, v97
	v_pk_add_f32 v[118:119], v[136:137], v[118:119]
	v_mov_b32_e32 v105, v177
	v_add_f32_e32 v97, v118, v119
	ds_bpermute_b32 v118, v1, v97
	s_waitcnt lgkmcnt(0)
	v_add_f32_e32 v97, v97, v118
	ds_bpermute_b32 v118, v90, v97
	s_waitcnt lgkmcnt(0)
	v_add_f32_e32 v97, v97, v118
	ds_bpermute_b32 v118, v91, v97
	s_waitcnt lgkmcnt(0)
	v_add_f32_e32 v97, v97, v118
	ds_bpermute_b32 v118, v92, v97
	s_waitcnt lgkmcnt(0)
	v_add_f32_e32 v97, v97, v118
	ds_bpermute_b32 v118, v93, v97
	s_waitcnt lgkmcnt(0)
	v_add_f32_e32 v97, v97, v118
	ds_bpermute_b32 v118, v94, v97
	s_waitcnt lgkmcnt(0)
	v_add_f32_e32 v97, v97, v118
	v_fmamk_f32 v97, v97, 0x39800000, v95
	v_mul_f32_e32 v118, 0x4f800000, v97
	v_cmp_gt_f32_e32 vcc, s5, v97
	s_nop 1
	v_cndmask_b32_e32 v97, v97, v118, vcc
	v_sqrt_f32_e32 v118, v97
	s_nop 0
	v_add_u32_e32 v119, -1, v118
	v_add_u32_e32 v122, 1, v118
	v_fma_f32 v123, -v119, v118, v97
	v_fma_f32 v126, -v122, v118, v97
	v_cmp_ge_f32_e64 s[0:1], 0, v123
	s_nop 1
	v_cndmask_b32_e64 v118, v118, v119, s[0:1]
	v_cmp_lt_f32_e64 s[0:1], 0, v126
	s_nop 1
	v_cndmask_b32_e64 v118, v118, v122, s[0:1]
	v_mul_f32_e32 v119, 0x37800000, v118
	v_cndmask_b32_e32 v118, v118, v119, vcc
	v_cmp_class_f32_e32 vcc, v97, v96
	s_nop 1
	v_cndmask_b32_e32 v97, v118, v97, vcc
	v_div_scale_f32 v118, s[0:1], v97, v97, 1.0
	v_rcp_f32_e32 v122, v118
	v_div_scale_f32 v119, vcc, 1.0, v97, 1.0
	v_fma_f32 v123, -v118, v122, 1.0
	v_fmac_f32_e32 v122, v123, v122
	v_mul_f32_e32 v123, v119, v122
	v_fma_f32 v126, -v118, v123, v119
	v_fmac_f32_e32 v123, v126, v122
	v_fma_f32 v118, -v118, v123, v119
	v_div_fmas_f32 v118, v118, v122, v123
	v_div_fixup_f32 v118, v118, v97, 1.0
	v_pk_mul_f32 v[116:117], v[118:119], v[116:117] op_sel_hi:[0,1]
	v_pk_mul_f32 v[78:79], v[118:119], v[78:79] op_sel_hi:[0,1]
	v_pk_mul_f32 v[122:123], v[118:119], v[150:151] op_sel_hi:[0,1]
	v_pk_mul_f32 v[80:81], v[118:119], v[80:81] op_sel_hi:[0,1]
	v_pk_mul_f32 v[126:127], v[118:119], v[152:153] op_sel_hi:[0,1]
	v_pk_mul_f32 v[66:67], v[118:119], v[66:67] op_sel_hi:[0,1]
	v_pk_mul_f32 v[68:69], v[118:119], v[68:69] op_sel_hi:[0,1]
	v_pk_mul_f32 v[120:121], v[118:119], v[120:121] op_sel_hi:[0,1]
	v_pk_mul_f32 v[74:75], v[118:119], v[74:75] op_sel_hi:[0,1]
	v_pk_mul_f32 v[84:85], v[118:119], v[84:85] op_sel_hi:[0,1]
	v_pk_mul_f32 v[76:77], v[118:119], v[76:77] op_sel_hi:[0,1]
	v_pk_mul_f32 v[70:71], v[118:119], v[70:71] op_sel_hi:[0,1]
	v_pk_mul_f32 v[114:115], v[118:119], v[114:115] op_sel_hi:[0,1]
	v_pk_mul_f32 v[124:125], v[118:119], v[124:125] op_sel_hi:[0,1]
	v_pk_mul_f32 v[72:73], v[118:119], v[72:73] op_sel_hi:[0,1]
	v_pk_mul_f32 v[128:129], v[118:119], v[154:155] op_sel_hi:[0,1]
	v_pk_mul_f32 v[130:131], v[118:119], v[156:157] op_sel_hi:[0,1]
	v_pk_mul_f32 v[132:133], v[118:119], v[142:143] op_sel_hi:[0,1]
	v_pk_mul_f32 v[98:99], v[118:119], v[98:99] op_sel_hi:[0,1]
	v_pk_mul_f32 v[100:101], v[118:119], v[100:101] op_sel_hi:[0,1]
	v_pk_mul_f32 v[134:135], v[118:119], v[180:181] op_sel_hi:[0,1]
	v_pk_mul_f32 v[102:103], v[118:119], v[102:103] op_sel_hi:[0,1]
; __device__ __forceinline__ u32x4 pack8(const f32x4 a, const f32x4 b) { u32x4 w; w.x = cvt_pk_bf16(a[0], a[1]); w.y = cvt_pk_bf16(a[2], a[3]); w.z = cvt_pk_bf16(b[0], b[1]); w.w = cvt_pk_bf16(b[2], b[3]); return w; }
; __device__ __forceinline__ void unpack8(const u32x4 w, f32x4& a, f32x4& b) { a = (f32x4){bflo(w.x), bfhi(w.x), bflo(w.y), bfhi(w.y)}; b = (f32x4){bflo(w.z), bfhi(w.z), bflo(w.w), bfhi(w.w)}; }
; __device__ __forceinline__ void load_xrow(Frame& F, int m, f32x4 (&v)[16]) {
;     const v4u* xr = (const v4u*)((const bf16*)(F.ws + WS_XRES) + (size_t)m * D) + F.lane;
;     v4u w[8];
; #pragma unroll
;     for (int j = 0; j < 8; ++j) w[j] = xr[64 * j];
; #pragma unroll
;     for (int j = 0; j < 8; ++j) pg8::unpack8(w[j], v[2 * j], v[2 * j + 1]);
; __device__ __forceinline__ void norm_phase(Frame& F, const float* gain, int nsplit, float scale, const float* samp_base) {
;     ...
;     for (int m = F.gw; m < NPROMPT; m += F.ngw) {
;         f32x4 v[16]; load_xrow(F, m, v);
;         const float r = row_rnorm(v);
;         v4u* o8 = (v4u*)((bf16*)(F.ws + WS_H) + (size_t)m * D) + F.lane;
; #pragma unroll
;         for (int j = 0; j < 8; ++j) o8[64 * j] = pg8::pack8(v[2 * j] * r * gn[2 * j], v[2 * j + 1] * r * gn[2 * j + 1]);
;     }
	v_pk_mul_f32 v[136:137], v[118:119], v[158:159] op_sel_hi:[0,1]
	v_pk_mul_f32 v[138:139], v[118:119], v[148:149] op_sel_hi:[0,1]
	v_pk_mul_f32 v[104:105], v[118:119], v[104:105] op_sel_hi:[0,1]
	v_pk_mul_f32 v[106:107], v[118:119], v[106:107] op_sel_hi:[0,1]
	v_pk_mul_f32 v[140:141], v[118:119], v[182:183] op_sel_hi:[0,1]
	v_pk_mul_f32 v[108:109], v[118:119], v[108:109] op_sel_hi:[0,1]
	v_pk_mul_f32 v[142:143], v[118:119], v[160:161] op_sel_hi:[0,1]
	v_pk_mul_f32 v[144:145], v[118:119], v[164:165] op_sel_hi:[0,1]
	v_pk_mul_f32 v[110:111], v[118:119], v[110:111] op_sel_hi:[0,1]
	v_pk_mul_f32 v[112:113], v[118:119], v[112:113] op_sel_hi:[0,1]
	v_pk_mul_f32 v[78:79], v[52:53], v[78:79]
	v_pk_mul_f32 v[116:117], v[50:51], v[116:117]
	v_pk_mul_f32 v[80:81], v[4:5], v[80:81]
	v_pk_mul_f32 v[118:119], v[2:3], v[122:123]
	v_pk_mul_f32 v[122:123], v[14:15], v[126:127]
	v_pk_mul_f32 v[126:127], v[44:45], v[66:67]
	v_pk_mul_f32 v[146:147], v[24:25], v[68:69]
	v_cvt_pk_bf16_f32 v66, v116, v117
	v_cvt_pk_bf16_f32 v67, v78, v79
	v_cvt_pk_bf16_f32 v68, v118, v119
	v_cvt_pk_bf16_f32 v69, v80, v81
	v_pk_mul_f32 v[74:75], v[8:9], v[74:75]
	v_pk_mul_f32 v[120:121], v[6:7], v[120:121]
	v_pk_mul_f32 v[76:77], v[12:13], v[76:77]
	v_pk_mul_f32 v[84:85], v[10:11], v[84:85]
	global_store_dwordx4 v[86:87], v[66:69], off offset:-4096
	v_pk_mul_f32 v[70:71], v[16:17], v[70:71]
	v_pk_mul_f32 v[124:125], v[20:21], v[124:125]
	v_cvt_pk_bf16_f32 v66, v120, v121
	v_cvt_pk_bf16_f32 v67, v74, v75
	v_cvt_pk_bf16_f32 v68, v84, v85
	v_cvt_pk_bf16_f32 v69, v76, v77
	v_pk_mul_f32 v[114:115], v[18:19], v[114:115]
	global_store_dwordx4 v[88:89], v[66:69], off offset:1024
	v_pk_mul_f32 v[72:73], v[42:43], v[72:73]
	v_pk_mul_f32 v[128:129], v[22:23], v[128:129]
	v_cvt_pk_bf16_f32 v66, v122, v123
	v_cvt_pk_bf16_f32 v67, v70, v71
	v_cvt_pk_bf16_f32 v68, v114, v115
	v_cvt_pk_bf16_f32 v69, v124, v125
	global_store_dwordx4 v[88:89], v[66:69], off offset:2048
	v_pk_mul_f32 v[132:133], v[28:29], v[132:133]
	v_pk_mul_f32 v[130:131], v[26:27], v[130:131]
	v_cvt_pk_bf16_f32 v66, v72, v73
	v_cvt_pk_bf16_f32 v67, v126, v127
	v_cvt_pk_bf16_f32 v68, v128, v129
	v_cvt_pk_bf16_f32 v69, v146, v147
	v_pk_mul_f32 v[100:101], v[36:37], v[100:101]
	v_pk_mul_f32 v[98:99], v[34:35], v[98:99]
	global_store_dwordx4 v[88:89], v[66:69], off offset:3072
	v_pk_mul_f32 v[102:103], v[32:33], v[102:103]
	v_pk_mul_f32 v[134:135], v[30:31], v[134:135]
	v_cvt_pk_bf16_f32 v66, v130, v131
	v_cvt_pk_bf16_f32 v67, v132, v133
	v_cvt_pk_bf16_f32 v68, v98, v99
	v_cvt_pk_bf16_f32 v69, v100, v101
	v_pk_mul_f32 v[138:139], v[40:41], v[138:139]
	v_pk_mul_f32 v[136:137], v[38:39], v[136:137]
	global_store_dwordx4 v[86:87], v[66:69], off
	v_pk_mul_f32 v[106:107], v[48:49], v[106:107]
	v_pk_mul_f32 v[104:105], v[46:47], v[104:105]
	v_cvt_pk_bf16_f32 v66, v134, v135
	v_cvt_pk_bf16_f32 v67, v102, v103
	v_cvt_pk_bf16_f32 v68, v136, v137
	v_cvt_pk_bf16_f32 v69, v138, v139
	v_pk_mul_f32 v[108:109], v[60:61], v[108:109]
	v_pk_mul_f32 v[140:141], v[58:59], v[140:141]
	global_store_dwordx4 v[86:87], v[66:69], off offset:1024
	v_pk_mul_f32 v[144:145], v[56:57], v[144:145]
	v_pk_mul_f32 v[142:143], v[54:55], v[142:143]
	v_cvt_pk_bf16_f32 v66, v104, v105
	v_cvt_pk_bf16_f32 v67, v106, v107
	v_cvt_pk_bf16_f32 v68, v140, v141
	v_cvt_pk_bf16_f32 v69, v108, v109
	v_pk_mul_f32 v[112:113], v[64:65], v[112:113]
	v_pk_mul_f32 v[110:111], v[62:63], v[110:111]
	global_store_dwordx4 v[86:87], v[66:69], off offset:2048
	s_nop 1
	v_cvt_pk_bf16_f32 v66, v142, v143
	v_cvt_pk_bf16_f32 v67, v144, v145
	v_cvt_pk_bf16_f32 v68, v110, v111
	v_cvt_pk_bf16_f32 v69, v112, v113
	global_store_dwordx4 v[86:87], v[66:69], off offset:3072
	s_add_u32 s98, s98, s2
	s_addc_u32 s99, s99, s3
	s_add_u32 s100, s98, 0x1000
	s_addc_u32 s101, s99, 0
	global_load_dwordx4 v[74:77], v199, s[98:99] offset:1024
	global_load_dwordx4 v[70:73], v199, s[98:99] offset:2048
	global_load_dwordx4 v[66:69], v199, s[98:99] offset:3072
	global_load_dwordx4 v[78:81], v199, s[98:99]
	global_load_dwordx4 v[98:101], v199, s[100:101]
	global_load_dwordx4 v[102:105], v199, s[100:101] offset:1024
	global_load_dwordx4 v[106:109], v199, s[100:101] offset:2048
	global_load_dwordx4 v[110:113], v199, s[100:101] offset:3072
	v_add_co_u32_e32 v84, vcc, s4, v82
	v_add_co_u32_e64 v88, s[0:1], s8, v82
	s_nop 0
	v_addc_co_u32_e32 v85, vcc, 0, v83, vcc
	v_addc_co_u32_e64 v89, s[0:1], 0, v83, s[0:1]
	v_add_co_u32_e64 v86, s[0:1], s9, v82
	s_add_i32 s10, s10, s90
	s_nop 0
	v_addc_co_u32_e64 v87, s[0:1], 0, v83, s[0:1]
	v_lshl_add_u64 v[82:83], v[82:83], 0, s[2:3]
	s_cmpk_lt_i32 s10, 0x2000
	s_waitcnt vmcnt(23)
	v_lshlrev_b32_e32 v120, 16, v200
	v_and_b32_e32 v121, 0xffff0000, v200
	v_lshlrev_b32_e32 v200, 16, v201
	s_waitcnt vmcnt(20)
; __device__ __forceinline__ void unpack8(const u32x4 w, f32x4& a, f32x4& b) { a = (f32x4){bflo(w.x), bfhi(w.x), bflo(w.y), bfhi(w.y)}; b = (f32x4){bflo(w.z), bfhi(w.z), bflo(w.w), bfhi(w.w)}; }
; __device__ __forceinline__ void load_xrow(Frame& F, int m, f32x4 (&v)[16]) {
;     const v4u* xr = (const v4u*)((const bf16*)(F.ws + WS_XRES) + (size_t)m * D) + F.lane;
;     v4u w[8];
; #pragma unroll
;     for (int j = 0; j < 8; ++j) w[j] = xr[64 * j];
; #pragma unroll
;     for (int j = 0; j < 8; ++j) pg8::unpack8(w[j], v[2 * j], v[2 * j + 1]);
; }
; __device__ __forceinline__ float row_rnorm(const f32x4 (&v)[16]) {
;     float s = 0.f;
; #pragma unroll
;     for (int j = 0; j < 16; ++j) s += (v[j].x * v[j].x + v[j].y * v[j].y) + (v[j].z * v[j].z + v[j].w * v[j].w);
;     return 1.0f / sqrtf(wave_sum(s) * (1.0f / D) + EPS);
	v_lshlrev_b32_e32 v116, 16, v212
	v_and_b32_e32 v117, 0xffff0000, v212
	v_lshlrev_b32_e32 v212, 16, v213
	v_lshlrev_b32_e32 v119, 16, v215
	v_lshlrev_b32_e32 v118, 16, v214
	v_and_b32_e32 v215, 0xffff0000, v215
	v_and_b32_e32 v214, 0xffff0000, v214
	v_and_b32_e32 v213, 0xffff0000, v213
	v_mul_f32_e32 v128, v116, v116
	v_mul_f32_e32 v130, v212, v212
	v_pk_mul_f32 v[132:133], v[214:215], v[214:215]
	v_and_b32_e32 v201, 0xffff0000, v201
	v_mul_f32_e32 v134, v120, v120
	v_mul_f32_e32 v136, v200, v200
	v_mov_b32_e32 v150, v118
	v_mov_b32_e32 v151, v214
	v_mov_b32_e32 v214, v119
	v_pk_fma_f32 v[128:129], v[116:117], v[116:117], v[128:129] op_sel_hi:[1,1,0]
	v_pk_fma_f32 v[130:131], v[212:213], v[212:213], v[130:131] op_sel_hi:[1,1,0]
	v_pk_fma_f32 v[118:119], v[118:119], v[118:119], v[132:133]
	v_lshlrev_b32_e32 v84, 16, v202
	v_and_b32_e32 v85, 0xffff0000, v202
	v_lshlrev_b32_e32 v202, 16, v203
	v_and_b32_e32 v203, 0xffff0000, v203
	v_pk_fma_f32 v[132:133], v[120:121], v[120:121], v[134:135] op_sel_hi:[1,1,0]
	v_pk_fma_f32 v[134:135], v[200:201], v[200:201], v[136:137] op_sel_hi:[1,1,0]
	v_pk_add_f32 v[118:119], v[118:119], v[118:119] op_sel_hi:[0,1]
	v_pk_add_f32 v[128:129], v[128:129], v[130:131]
	v_lshlrev_b32_e32 v123, 16, v205
	v_lshlrev_b32_e32 v122, 16, v204
	v_and_b32_e32 v205, 0xffff0000, v205
	v_and_b32_e32 v204, 0xffff0000, v204
	v_mul_f32_e32 v138, v84, v84
	v_mul_f32_e32 v132, v202, v202
	v_mul_f32_e32 v134, v203, v203
	v_mul_f32_e32 v118, v85, v85
	v_mov_b32_e32 v139, v129
	v_lshlrev_b32_e32 v114, 16, v206
	v_and_b32_e32 v115, 0xffff0000, v206
	v_lshlrev_b32_e32 v206, 16, v208
	v_lshlrev_b32_e32 v124, 16, v207
	v_pk_mul_f32 v[140:141], v[204:205], v[204:205]
	v_pk_add_f32 v[132:133], v[132:133], v[134:135]
	v_pk_add_f32 v[118:119], v[138:139], v[118:119]
	v_and_b32_e32 v125, 0xffff0000, v207
	v_lshlrev_b32_e32 v127, 16, v211
	v_lshlrev_b32_e32 v126, 16, v210
	v_and_b32_e32 v211, 0xffff0000, v211
	v_and_b32_e32 v210, 0xffff0000, v210
	v_mul_f32_e32 v207, v114, v114
	v_mul_f32_e32 v143, v115, v115
	v_mul_f32_e32 v144, v124, v124
	v_mov_b32_e32 v142, v206
	v_mov_b32_e32 v152, v122
	v_mov_b32_e32 v153, v204
	v_mov_b32_e32 v204, v123
	v_pk_fma_f32 v[122:123], v[122:123], v[122:123], v[140:141]
	v_pk_add_f32 v[118:119], v[118:119], v[132:133]
	v_and_b32_e32 v97, 0xffff0000, v208
	v_lshlrev_b32_e32 v208, 16, v209
	v_and_b32_e32 v209, 0xffff0000, v209
	v_pk_mul_f32 v[148:149], v[210:211], v[210:211]
	v_pk_fma_f32 v[136:137], v[124:125], v[124:125], v[144:145] op_sel_hi:[1,1,0]
	v_pk_add_f32 v[140:141], v[206:207], v[142:143]
	v_pk_add_f32 v[122:123], v[122:123], v[122:123] op_sel_hi:[0,1]
	v_pk_add_f32 v[118:119], v[118:119], v[118:119] op_sel_hi:[0,1]
	v_mul_f32_e32 v146, v206, v206
	v_mov_b32_e32 v154, v126
	v_mov_b32_e32 v155, v210
	v_mov_b32_e32 v210, v127
	v_pk_fma_f32 v[126:127], v[126:127], v[126:127], v[148:149]
	v_mul_f32_e32 v136, v97, v97
	v_mov_b32_e32 v147, v141
	v_mul_f32_e32 v122, v208, v208
	v_mul_f32_e32 v118, v209, v209
	s_waitcnt vmcnt(19)
	v_lshlrev_b32_e32 v156, 16, v216
	v_and_b32_e32 v157, 0xffff0000, v216
	v_lshlrev_b32_e32 v216, 16, v218
	v_lshlrev_b32_e32 v142, 16, v217
	v_pk_add_f32 v[126:127], v[126:127], v[126:127] op_sel_hi:[0,1]
	v_pk_add_f32 v[134:135], v[146:147], v[136:137]
	v_pk_add_f32 v[118:119], v[122:123], v[118:119]
	v_and_b32_e32 v143, 0xffff0000, v217
	v_mul_f32_e32 v217, v156, v156
	v_mul_f32_e32 v131, v157, v157
	v_mul_f32_e32 v126, v142, v142
	v_mov_b32_e32 v130, v216
	v_pk_add_f32 v[118:119], v[134:135], v[118:119]
	v_and_b32_e32 v171, 0xffff0000, v218
	v_lshlrev_b32_e32 v218, 16, v219
	v_and_b32_e32 v219, 0xffff0000, v219
	v_pk_fma_f32 v[136:137], v[142:143], v[142:143], v[126:127] op_sel_hi:[1,1,0]
	v_pk_add_f32 v[130:131], v[216:217], v[130:131]
	v_pk_add_f32 v[118:119], v[118:119], v[118:119] op_sel_hi:[0,1]
	s_waitcnt vmcnt(18)
	v_lshlrev_b32_e32 v145, 16, v221
	v_lshlrev_b32_e32 v144, 16, v220
	v_and_b32_e32 v221, 0xffff0000, v221
	v_and_b32_e32 v220, 0xffff0000, v220
	v_mul_f32_e32 v128, v216, v216
	v_mul_f32_e32 v126, v218, v218
	v_mul_f32_e32 v136, v171, v171
	v_mov_b32_e32 v129, v131
	v_mul_f32_e32 v118, v219, v219
	v_lshlrev_b32_e32 v158, 16, v222
	v_and_b32_e32 v159, 0xffff0000, v222
	s_waitcnt vmcnt(17)
	v_lshlrev_b32_e32 v222, 16, v224
	v_lshlrev_b32_e32 v148, 16, v223
	v_pk_mul_f32 v[140:141], v[220:221], v[220:221]
	v_pk_add_f32 v[128:129], v[128:129], v[136:137]
	v_pk_add_f32 v[118:119], v[126:127], v[118:119]
	v_and_b32_e32 v149, 0xffff0000, v223
	v_mul_f32_e32 v223, v158, v158
	v_mul_f32_e32 v167, v159, v159
	v_mul_f32_e32 v168, v148, v148
	v_mov_b32_e32 v166, v222
	v_pk_fma_f32 v[140:141], v[144:145], v[144:145], v[140:141]
	v_pk_add_f32 v[118:119], v[128:129], v[118:119]
	v_and_b32_e32 v177, 0xffff0000, v224
	v_lshlrev_b32_e32 v224, 16, v225
	v_and_b32_e32 v225, 0xffff0000, v225
	v_mov_b32_e32 v180, v144
	v_mov_b32_e32 v181, v220
	v_mov_b32_e32 v220, v145
	v_pk_fma_f32 v[144:145], v[148:149], v[148:149], v[168:169] op_sel_hi:[1,1,0]
	v_pk_add_f32 v[146:147], v[222:223], v[166:167]
	v_pk_add_f32 v[130:131], v[140:141], v[140:141] op_sel_hi:[0,1]
	v_pk_add_f32 v[118:119], v[118:119], v[118:119] op_sel_hi:[0,1]
	v_lshlrev_b32_e32 v163, 16, v227
	v_lshlrev_b32_e32 v162, 16, v226
	v_and_b32_e32 v227, 0xffff0000, v227
	v_and_b32_e32 v226, 0xffff0000, v226
	v_mul_f32_e32 v170, v222, v222
	v_mov_b32_e32 v217, v171
	v_mul_f32_e32 v144, v177, v177
	v_mov_b32_e32 v171, v147
	v_mul_f32_e32 v130, v224, v224
	v_mul_f32_e32 v118, v225, v225
	s_waitcnt vmcnt(16)
; __device__ __forceinline__ u32x4 pack8(const f32x4 a, const f32x4 b) { u32x4 w; w.x = cvt_pk_bf16(a[0], a[1]); w.y = cvt_pk_bf16(a[2], a[3]); w.z = cvt_pk_bf16(b[0], b[1]); w.w = cvt_pk_bf16(b[2], b[3]); return w; }
; __device__ __forceinline__ float row_rnorm(const f32x4 (&v)[16]) {
;     float s = 0.f;
; #pragma unroll
;     for (int j = 0; j < 16; ++j) s += (v[j].x * v[j].x + v[j].y * v[j].y) + (v[j].z * v[j].z + v[j].w * v[j].w);
;     return 1.0f / sqrtf(wave_sum(s) * (1.0f / D) + EPS);
; }
; __device__ __forceinline__ void norm_phase(Frame& F, const float* gain, int nsplit, float scale, const float* samp_base) {
;     (void)nsplit;
;     norm_sample_row<false>(F, gain, scale, samp_base, nullptr);
;     f32x4 gn[16]; load_gain8(gain, F.lane, gn);
;     for (int m = F.gw; m < NPROMPT; m += F.ngw) {
;         f32x4 v[16]; load_xrow(F, m, v);
;         const float r = row_rnorm(v);
;         v4u* o8 = (v4u*)((bf16*)(F.ws + WS_H) + (size_t)m * D) + F.lane;
; #pragma unroll
;         for (int j = 0; j < 8; ++j) o8[64 * j] = pg8::pack8(v[2 * j] * r * gn[2 * j], v[2 * j + 1] * r * gn[2 * j + 1]);
	v_lshlrev_b32_e32 v160, 16, v228
	v_and_b32_e32 v161, 0xffff0000, v228
	v_lshlrev_b32_e32 v228, 16, v230
	v_lshlrev_b32_e32 v164, 16, v229
	v_pk_mul_f32 v[172:173], v[226:227], v[226:227]
	v_pk_add_f32 v[132:133], v[170:171], v[144:145]
	v_pk_add_f32 v[118:119], v[130:131], v[118:119]
	v_and_b32_e32 v165, 0xffff0000, v229
	v_mul_f32_e32 v229, v160, v160
	v_mul_f32_e32 v175, v161, v161
	v_mul_f32_e32 v176, v164, v164
	v_mov_b32_e32 v174, v228
	v_mov_b32_e32 v182, v162
	v_mov_b32_e32 v183, v226
	v_mov_b32_e32 v226, v163
	v_pk_fma_f32 v[162:163], v[162:163], v[162:163], v[172:173]
	v_pk_add_f32 v[118:119], v[132:133], v[118:119]
	v_and_b32_e32 v179, 0xffff0000, v230
	v_lshlrev_b32_e32 v230, 16, v231
	v_and_b32_e32 v231, 0xffff0000, v231
	v_pk_fma_f32 v[166:167], v[164:165], v[164:165], v[176:177] op_sel_hi:[1,1,0]
	v_pk_add_f32 v[168:169], v[228:229], v[174:175]
	v_pk_add_f32 v[138:139], v[162:163], v[162:163] op_sel_hi:[0,1]
	v_pk_add_f32 v[118:119], v[118:119], v[118:119] op_sel_hi:[0,1]
	v_mul_f32_e32 v178, v228, v228
	v_mov_b32_e32 v229, v179
	v_mul_f32_e32 v166, v179, v179
	v_mov_b32_e32 v179, v169
	v_mul_f32_e32 v138, v230, v230
	v_mul_f32_e32 v118, v231, v231
	v_pk_add_f32 v[136:137], v[178:179], v[166:167]
	v_pk_add_f32 v[118:119], v[138:139], v[118:119]
	v_mov_b32_e32 v207, v97
	v_pk_add_f32 v[118:119], v[136:137], v[118:119]
	v_mov_b32_e32 v223, v177
	v_add_f32_e32 v97, v118, v119
	ds_bpermute_b32 v118, v1, v97
	s_waitcnt lgkmcnt(0)
	v_add_f32_e32 v97, v97, v118
	ds_bpermute_b32 v118, v90, v97
	s_waitcnt lgkmcnt(0)
	v_add_f32_e32 v97, v97, v118
	ds_bpermute_b32 v118, v91, v97
	s_waitcnt lgkmcnt(0)
	v_add_f32_e32 v97, v97, v118
	ds_bpermute_b32 v118, v92, v97
	s_waitcnt lgkmcnt(0)
	v_add_f32_e32 v97, v97, v118
	ds_bpermute_b32 v118, v93, v97
	s_waitcnt lgkmcnt(0)
	v_add_f32_e32 v97, v97, v118
	ds_bpermute_b32 v118, v94, v97
	s_waitcnt lgkmcnt(0)
	v_add_f32_e32 v97, v97, v118
	v_fmamk_f32 v97, v97, 0x39800000, v95
	v_mul_f32_e32 v118, 0x4f800000, v97
	v_cmp_gt_f32_e32 vcc, s5, v97
	s_nop 1
	v_cndmask_b32_e32 v97, v97, v118, vcc
	v_sqrt_f32_e32 v118, v97
	s_nop 0
	v_add_u32_e32 v119, -1, v118
	v_add_u32_e32 v122, 1, v118
	v_fma_f32 v123, -v119, v118, v97
	v_fma_f32 v126, -v122, v118, v97
	v_cmp_ge_f32_e64 s[0:1], 0, v123
	s_nop 1
	v_cndmask_b32_e64 v118, v118, v119, s[0:1]
	v_cmp_lt_f32_e64 s[0:1], 0, v126
	s_nop 1
	v_cndmask_b32_e64 v118, v118, v122, s[0:1]
	v_mul_f32_e32 v119, 0x37800000, v118
	v_cndmask_b32_e32 v118, v118, v119, vcc
	v_cmp_class_f32_e32 vcc, v97, v96
	s_nop 1
	v_cndmask_b32_e32 v97, v118, v97, vcc
	v_div_scale_f32 v118, s[0:1], v97, v97, 1.0
	v_rcp_f32_e32 v122, v118
	v_div_scale_f32 v119, vcc, 1.0, v97, 1.0
	v_fma_f32 v123, -v118, v122, 1.0
	v_fmac_f32_e32 v122, v123, v122
	v_mul_f32_e32 v123, v119, v122
	v_fma_f32 v126, -v118, v123, v119
	v_fmac_f32_e32 v123, v126, v122
	v_fma_f32 v118, -v118, v123, v119
	v_div_fmas_f32 v118, v118, v122, v123
	v_div_fixup_f32 v118, v118, v97, 1.0
	v_pk_mul_f32 v[116:117], v[118:119], v[116:117] op_sel_hi:[0,1]
	v_pk_mul_f32 v[212:213], v[118:119], v[212:213] op_sel_hi:[0,1]
	v_pk_mul_f32 v[122:123], v[118:119], v[150:151] op_sel_hi:[0,1]
	v_pk_mul_f32 v[214:215], v[118:119], v[214:215] op_sel_hi:[0,1]
	v_pk_mul_f32 v[126:127], v[118:119], v[152:153] op_sel_hi:[0,1]
	v_pk_mul_f32 v[208:209], v[118:119], v[208:209] op_sel_hi:[0,1]
	v_pk_mul_f32 v[210:211], v[118:119], v[210:211] op_sel_hi:[0,1]
	v_pk_mul_f32 v[120:121], v[118:119], v[120:121] op_sel_hi:[0,1]
	v_pk_mul_f32 v[200:201], v[118:119], v[200:201] op_sel_hi:[0,1]
	v_pk_mul_f32 v[84:85], v[118:119], v[84:85] op_sel_hi:[0,1]
	v_pk_mul_f32 v[202:203], v[118:119], v[202:203] op_sel_hi:[0,1]
	v_pk_mul_f32 v[204:205], v[118:119], v[204:205] op_sel_hi:[0,1]
	v_pk_mul_f32 v[114:115], v[118:119], v[114:115] op_sel_hi:[0,1]
	v_pk_mul_f32 v[124:125], v[118:119], v[124:125] op_sel_hi:[0,1]
	v_pk_mul_f32 v[206:207], v[118:119], v[206:207] op_sel_hi:[0,1]
	v_pk_mul_f32 v[128:129], v[118:119], v[154:155] op_sel_hi:[0,1]
	v_pk_mul_f32 v[130:131], v[118:119], v[156:157] op_sel_hi:[0,1]
	v_pk_mul_f32 v[132:133], v[118:119], v[142:143] op_sel_hi:[0,1]
	v_pk_mul_f32 v[216:217], v[118:119], v[216:217] op_sel_hi:[0,1]
	v_pk_mul_f32 v[218:219], v[118:119], v[218:219] op_sel_hi:[0,1]
	v_pk_mul_f32 v[134:135], v[118:119], v[180:181] op_sel_hi:[0,1]
	v_pk_mul_f32 v[220:221], v[118:119], v[220:221] op_sel_hi:[0,1]
	v_pk_mul_f32 v[136:137], v[118:119], v[158:159] op_sel_hi:[0,1]
	v_pk_mul_f32 v[138:139], v[118:119], v[148:149] op_sel_hi:[0,1]
	v_pk_mul_f32 v[222:223], v[118:119], v[222:223] op_sel_hi:[0,1]
	v_pk_mul_f32 v[224:225], v[118:119], v[224:225] op_sel_hi:[0,1]
	v_pk_mul_f32 v[140:141], v[118:119], v[182:183] op_sel_hi:[0,1]
	v_pk_mul_f32 v[226:227], v[118:119], v[226:227] op_sel_hi:[0,1]
	v_pk_mul_f32 v[142:143], v[118:119], v[160:161] op_sel_hi:[0,1]
	v_pk_mul_f32 v[144:145], v[118:119], v[164:165] op_sel_hi:[0,1]
	v_pk_mul_f32 v[228:229], v[118:119], v[228:229] op_sel_hi:[0,1]
	v_pk_mul_f32 v[230:231], v[118:119], v[230:231] op_sel_hi:[0,1]
	v_pk_mul_f32 v[212:213], v[52:53], v[212:213]
	v_pk_mul_f32 v[116:117], v[50:51], v[116:117]
	v_pk_mul_f32 v[214:215], v[4:5], v[214:215]
	v_pk_mul_f32 v[118:119], v[2:3], v[122:123]
	v_pk_mul_f32 v[122:123], v[14:15], v[126:127]
	v_pk_mul_f32 v[126:127], v[44:45], v[208:209]
	v_pk_mul_f32 v[146:147], v[24:25], v[210:211]
	v_cvt_pk_bf16_f32 v208, v116, v117
	v_cvt_pk_bf16_f32 v209, v212, v213
	v_cvt_pk_bf16_f32 v210, v118, v119
	v_cvt_pk_bf16_f32 v211, v214, v215
	v_pk_mul_f32 v[200:201], v[8:9], v[200:201]
	v_pk_mul_f32 v[120:121], v[6:7], v[120:121]
	v_pk_mul_f32 v[202:203], v[12:13], v[202:203]
; __device__ __forceinline__ u32x4 pack8(const f32x4 a, const f32x4 b) { u32x4 w; w.x = cvt_pk_bf16(a[0], a[1]); w.y = cvt_pk_bf16(a[2], a[3]); w.z = cvt_pk_bf16(b[0], b[1]); w.w = cvt_pk_bf16(b[2], b[3]); return w; }
; __device__ __forceinline__ void unpack8(const u32x4 w, f32x4& a, f32x4& b) { a = (f32x4){bflo(w.x), bfhi(w.x), bflo(w.y), bfhi(w.y)}; b = (f32x4){bflo(w.z), bfhi(w.z), bflo(w.w), bfhi(w.w)}; }
; __device__ __forceinline__ void load_xrow(Frame& F, int m, f32x4 (&v)[16]) {
;     const v4u* xr = (const v4u*)((const bf16*)(F.ws + WS_XRES) + (size_t)m * D) + F.lane;
;     v4u w[8];
; #pragma unroll
;     for (int j = 0; j < 8; ++j) w[j] = xr[64 * j];
; #pragma unroll
;     for (int j = 0; j < 8; ++j) pg8::unpack8(w[j], v[2 * j], v[2 * j + 1]);
; __device__ __forceinline__ void norm_phase(Frame& F, const float* gain, int nsplit, float scale, const float* samp_base) {
;     ...
;     for (int m = F.gw; m < NPROMPT; m += F.ngw) {
;         f32x4 v[16]; load_xrow(F, m, v);
;         const float r = row_rnorm(v);
;         v4u* o8 = (v4u*)((bf16*)(F.ws + WS_H) + (size_t)m * D) + F.lane;
; #pragma unroll
;         for (int j = 0; j < 8; ++j) o8[64 * j] = pg8::pack8(v[2 * j] * r * gn[2 * j], v[2 * j + 1] * r * gn[2 * j + 1]);
;     }
	v_pk_mul_f32 v[84:85], v[10:11], v[84:85]
	global_store_dwordx4 v[86:87], v[208:211], off offset:-4096
	v_pk_mul_f32 v[204:205], v[16:17], v[204:205]
	v_pk_mul_f32 v[124:125], v[20:21], v[124:125]
	v_cvt_pk_bf16_f32 v208, v120, v121
	v_cvt_pk_bf16_f32 v209, v200, v201
	v_cvt_pk_bf16_f32 v210, v84, v85
	v_cvt_pk_bf16_f32 v211, v202, v203
	v_pk_mul_f32 v[114:115], v[18:19], v[114:115]
	global_store_dwordx4 v[88:89], v[208:211], off offset:1024
	v_pk_mul_f32 v[206:207], v[42:43], v[206:207]
	v_pk_mul_f32 v[128:129], v[22:23], v[128:129]
	v_cvt_pk_bf16_f32 v208, v122, v123
	v_cvt_pk_bf16_f32 v209, v204, v205
	v_cvt_pk_bf16_f32 v210, v114, v115
	v_cvt_pk_bf16_f32 v211, v124, v125
	global_store_dwordx4 v[88:89], v[208:211], off offset:2048
	v_pk_mul_f32 v[132:133], v[28:29], v[132:133]
	v_pk_mul_f32 v[130:131], v[26:27], v[130:131]
	v_cvt_pk_bf16_f32 v208, v206, v207
	v_cvt_pk_bf16_f32 v209, v126, v127
	v_cvt_pk_bf16_f32 v210, v128, v129
	v_cvt_pk_bf16_f32 v211, v146, v147
	v_pk_mul_f32 v[218:219], v[36:37], v[218:219]
	v_pk_mul_f32 v[216:217], v[34:35], v[216:217]
	global_store_dwordx4 v[88:89], v[208:211], off offset:3072
	v_pk_mul_f32 v[220:221], v[32:33], v[220:221]
	v_pk_mul_f32 v[134:135], v[30:31], v[134:135]
	v_cvt_pk_bf16_f32 v208, v130, v131
	v_cvt_pk_bf16_f32 v209, v132, v133
	v_cvt_pk_bf16_f32 v210, v216, v217
	v_cvt_pk_bf16_f32 v211, v218, v219
	v_pk_mul_f32 v[138:139], v[40:41], v[138:139]
	v_pk_mul_f32 v[136:137], v[38:39], v[136:137]
	global_store_dwordx4 v[86:87], v[208:211], off
	v_pk_mul_f32 v[224:225], v[48:49], v[224:225]
	v_pk_mul_f32 v[222:223], v[46:47], v[222:223]
	v_cvt_pk_bf16_f32 v208, v134, v135
	v_cvt_pk_bf16_f32 v209, v220, v221
	v_cvt_pk_bf16_f32 v210, v136, v137
	v_cvt_pk_bf16_f32 v211, v138, v139
	v_pk_mul_f32 v[226:227], v[60:61], v[226:227]
	v_pk_mul_f32 v[140:141], v[58:59], v[140:141]
	global_store_dwordx4 v[86:87], v[208:211], off offset:1024
	v_pk_mul_f32 v[144:145], v[56:57], v[144:145]
	v_pk_mul_f32 v[142:143], v[54:55], v[142:143]
	v_cvt_pk_bf16_f32 v208, v222, v223
	v_cvt_pk_bf16_f32 v209, v224, v225
	v_cvt_pk_bf16_f32 v210, v140, v141
	v_cvt_pk_bf16_f32 v211, v226, v227
	v_pk_mul_f32 v[230:231], v[64:65], v[230:231]
	v_pk_mul_f32 v[228:229], v[62:63], v[228:229]
	global_store_dwordx4 v[86:87], v[208:211], off offset:2048
	s_nop 1
	v_cvt_pk_bf16_f32 v208, v142, v143
	v_cvt_pk_bf16_f32 v209, v144, v145
	v_cvt_pk_bf16_f32 v210, v228, v229
	v_cvt_pk_bf16_f32 v211, v230, v231
	global_store_dwordx4 v[86:87], v[208:211], off offset:3072
	s_add_u32 s98, s98, s2
	s_addc_u32 s99, s99, s3
	s_add_u32 s100, s98, 0x1000
	s_addc_u32 s101, s99, 0
	global_load_dwordx4 v[200:203], v199, s[98:99] offset:1024
	global_load_dwordx4 v[204:207], v199, s[98:99] offset:2048
	global_load_dwordx4 v[208:211], v199, s[98:99] offset:3072
	global_load_dwordx4 v[212:215], v199, s[98:99]
	global_load_dwordx4 v[216:219], v199, s[100:101]
	global_load_dwordx4 v[220:223], v199, s[100:101] offset:1024
	global_load_dwordx4 v[224:227], v199, s[100:101] offset:2048
	global_load_dwordx4 v[228:231], v199, s[100:101] offset:3072
	v_add_co_u32_e32 v84, vcc, s4, v82
	v_add_co_u32_e64 v88, s[0:1], s8, v82
	s_nop 0
	v_addc_co_u32_e32 v85, vcc, 0, v83, vcc
	v_addc_co_u32_e64 v89, s[0:1], 0, v83, s[0:1]
	v_add_co_u32_e64 v86, s[0:1], s9, v82
	s_add_i32 s10, s10, s90
	s_nop 0
	v_addc_co_u32_e64 v87, s[0:1], 0, v83, s[0:1]
	v_lshl_add_u64 v[82:83], v[82:83], 0, s[2:3]
	s_cmpk_lt_i32 s10, 0x2000
	s_waitcnt vmcnt(23)
	v_lshlrev_b32_e32 v120, 16, v74
	v_and_b32_e32 v121, 0xffff0000, v74
	v_lshlrev_b32_e32 v74, 16, v75
	s_waitcnt vmcnt(20)
	v_lshlrev_b32_e32 v116, 16, v78
	v_and_b32_e32 v117, 0xffff0000, v78
	v_lshlrev_b32_e32 v78, 16, v79
	v_lshlrev_b32_e32 v119, 16, v81
	v_lshlrev_b32_e32 v118, 16, v80
	v_and_b32_e32 v81, 0xffff0000, v81
	v_and_b32_e32 v80, 0xffff0000, v80
	v_and_b32_e32 v79, 0xffff0000, v79
	v_mul_f32_e32 v128, v116, v116
	v_mul_f32_e32 v130, v78, v78
	v_pk_mul_f32 v[132:133], v[80:81], v[80:81]
	v_and_b32_e32 v75, 0xffff0000, v75
	v_mul_f32_e32 v134, v120, v120
	v_mul_f32_e32 v136, v74, v74
	v_mov_b32_e32 v150, v118
	v_mov_b32_e32 v151, v80
	v_mov_b32_e32 v80, v119
	v_pk_fma_f32 v[128:129], v[116:117], v[116:117], v[128:129] op_sel_hi:[1,1,0]
	v_pk_fma_f32 v[130:131], v[78:79], v[78:79], v[130:131] op_sel_hi:[1,1,0]
	v_pk_fma_f32 v[118:119], v[118:119], v[118:119], v[132:133]
	v_lshlrev_b32_e32 v84, 16, v76
	v_and_b32_e32 v85, 0xffff0000, v76
	v_lshlrev_b32_e32 v76, 16, v77
	v_and_b32_e32 v77, 0xffff0000, v77
	v_pk_fma_f32 v[132:133], v[120:121], v[120:121], v[134:135] op_sel_hi:[1,1,0]
	v_pk_fma_f32 v[134:135], v[74:75], v[74:75], v[136:137] op_sel_hi:[1,1,0]
	v_pk_add_f32 v[118:119], v[118:119], v[118:119] op_sel_hi:[0,1]
	v_pk_add_f32 v[128:129], v[128:129], v[130:131]
	v_lshlrev_b32_e32 v123, 16, v71
	v_lshlrev_b32_e32 v122, 16, v70
	v_and_b32_e32 v71, 0xffff0000, v71
	v_and_b32_e32 v70, 0xffff0000, v70
	v_mul_f32_e32 v138, v84, v84
	v_mul_f32_e32 v132, v76, v76
	v_mul_f32_e32 v134, v77, v77
	v_mul_f32_e32 v118, v85, v85
	v_mov_b32_e32 v139, v129
	v_lshlrev_b32_e32 v114, 16, v72
	v_and_b32_e32 v115, 0xffff0000, v72
	v_lshlrev_b32_e32 v72, 16, v66
	v_lshlrev_b32_e32 v124, 16, v73
	v_pk_mul_f32 v[140:141], v[70:71], v[70:71]
	v_pk_add_f32 v[132:133], v[132:133], v[134:135]
	v_pk_add_f32 v[118:119], v[138:139], v[118:119]
	v_and_b32_e32 v125, 0xffff0000, v73
	v_lshlrev_b32_e32 v127, 16, v69
	v_lshlrev_b32_e32 v126, 16, v68
	v_and_b32_e32 v69, 0xffff0000, v69
	v_and_b32_e32 v68, 0xffff0000, v68
	v_mul_f32_e32 v73, v114, v114
	v_mul_f32_e32 v143, v115, v115
	v_mul_f32_e32 v144, v124, v124
	v_mov_b32_e32 v142, v72
	v_mov_b32_e32 v152, v122
	v_mov_b32_e32 v153, v70
	v_mov_b32_e32 v70, v123
	v_pk_fma_f32 v[122:123], v[122:123], v[122:123], v[140:141]
	v_pk_add_f32 v[118:119], v[118:119], v[132:133]
	v_and_b32_e32 v97, 0xffff0000, v66
	v_lshlrev_b32_e32 v66, 16, v67
	v_and_b32_e32 v67, 0xffff0000, v67
	v_pk_mul_f32 v[148:149], v[68:69], v[68:69]
	v_pk_fma_f32 v[136:137], v[124:125], v[124:125], v[144:145] op_sel_hi:[1,1,0]
	v_pk_add_f32 v[140:141], v[72:73], v[142:143]
	v_pk_add_f32 v[122:123], v[122:123], v[122:123] op_sel_hi:[0,1]
	v_pk_add_f32 v[118:119], v[118:119], v[118:119] op_sel_hi:[0,1]
	v_mul_f32_e32 v146, v72, v72
	v_mov_b32_e32 v154, v126
	v_mov_b32_e32 v155, v68
	v_mov_b32_e32 v68, v127
	v_pk_fma_f32 v[126:127], v[126:127], v[126:127], v[148:149]
	v_mul_f32_e32 v136, v97, v97
	v_mov_b32_e32 v147, v141
	v_mul_f32_e32 v122, v66, v66
	v_mul_f32_e32 v118, v67, v67
	s_waitcnt vmcnt(19)
; __device__ __forceinline__ void unpack8(const u32x4 w, f32x4& a, f32x4& b) { a = (f32x4){bflo(w.x), bfhi(w.x), bflo(w.y), bfhi(w.y)}; b = (f32x4){bflo(w.z), bfhi(w.z), bflo(w.w), bfhi(w.w)}; }
; __device__ __forceinline__ float wave_sum(float v) {
; #pragma unroll
;     for (int o = 1; o < 64; o <<= 1) v += __shfl_xor(v, o);
;     return v;
; }
; __device__ __forceinline__ void load_xrow(Frame& F, int m, f32x4 (&v)[16]) {
;     const v4u* xr = (const v4u*)((const bf16*)(F.ws + WS_XRES) + (size_t)m * D) + F.lane;
;     v4u w[8];
; #pragma unroll
;     for (int j = 0; j < 8; ++j) w[j] = xr[64 * j];
; #pragma unroll
;     for (int j = 0; j < 8; ++j) pg8::unpack8(w[j], v[2 * j], v[2 * j + 1]);
; }
; __device__ __forceinline__ float row_rnorm(const f32x4 (&v)[16]) {
;     float s = 0.f;
; #pragma unroll
;     for (int j = 0; j < 16; ++j) s += (v[j].x * v[j].x + v[j].y * v[j].y) + (v[j].z * v[j].z + v[j].w * v[j].w);
;     return 1.0f / sqrtf(wave_sum(s) * (1.0f / D) + EPS);
	v_lshlrev_b32_e32 v156, 16, v98
	v_and_b32_e32 v157, 0xffff0000, v98
	v_lshlrev_b32_e32 v98, 16, v100
	v_lshlrev_b32_e32 v142, 16, v99
	v_pk_add_f32 v[126:127], v[126:127], v[126:127] op_sel_hi:[0,1]
	v_pk_add_f32 v[134:135], v[146:147], v[136:137]
	v_pk_add_f32 v[118:119], v[122:123], v[118:119]
	v_and_b32_e32 v143, 0xffff0000, v99
	v_mul_f32_e32 v99, v156, v156
	v_mul_f32_e32 v131, v157, v157
	v_mul_f32_e32 v126, v142, v142
	v_mov_b32_e32 v130, v98
	v_pk_add_f32 v[118:119], v[134:135], v[118:119]
	v_and_b32_e32 v171, 0xffff0000, v100
	v_lshlrev_b32_e32 v100, 16, v101
	v_and_b32_e32 v101, 0xffff0000, v101
	v_pk_fma_f32 v[136:137], v[142:143], v[142:143], v[126:127] op_sel_hi:[1,1,0]
	v_pk_add_f32 v[130:131], v[98:99], v[130:131]
	v_pk_add_f32 v[118:119], v[118:119], v[118:119] op_sel_hi:[0,1]
	s_waitcnt vmcnt(18)
	v_lshlrev_b32_e32 v145, 16, v103
	v_lshlrev_b32_e32 v144, 16, v102
	v_and_b32_e32 v103, 0xffff0000, v103
	v_and_b32_e32 v102, 0xffff0000, v102
	v_mul_f32_e32 v128, v98, v98
	v_mul_f32_e32 v126, v100, v100
	v_mul_f32_e32 v136, v171, v171
	v_mov_b32_e32 v129, v131
	v_mul_f32_e32 v118, v101, v101
	v_lshlrev_b32_e32 v158, 16, v104
	v_and_b32_e32 v159, 0xffff0000, v104
	s_waitcnt vmcnt(17)
	v_lshlrev_b32_e32 v104, 16, v106
	v_lshlrev_b32_e32 v148, 16, v105
	v_pk_mul_f32 v[140:141], v[102:103], v[102:103]
	v_pk_add_f32 v[128:129], v[128:129], v[136:137]
	v_pk_add_f32 v[118:119], v[126:127], v[118:119]
	v_and_b32_e32 v149, 0xffff0000, v105
	v_mul_f32_e32 v105, v158, v158
	v_mul_f32_e32 v167, v159, v159
	v_mul_f32_e32 v168, v148, v148
	v_mov_b32_e32 v166, v104
	v_pk_fma_f32 v[140:141], v[144:145], v[144:145], v[140:141]
	v_pk_add_f32 v[118:119], v[128:129], v[118:119]
	v_and_b32_e32 v177, 0xffff0000, v106
	v_lshlrev_b32_e32 v106, 16, v107
	v_and_b32_e32 v107, 0xffff0000, v107
	v_mov_b32_e32 v180, v144
	v_mov_b32_e32 v181, v102
	v_mov_b32_e32 v102, v145
	v_pk_fma_f32 v[144:145], v[148:149], v[148:149], v[168:169] op_sel_hi:[1,1,0]
	v_pk_add_f32 v[146:147], v[104:105], v[166:167]
	v_pk_add_f32 v[130:131], v[140:141], v[140:141] op_sel_hi:[0,1]
	v_pk_add_f32 v[118:119], v[118:119], v[118:119] op_sel_hi:[0,1]
	v_lshlrev_b32_e32 v163, 16, v109
	v_lshlrev_b32_e32 v162, 16, v108
	v_and_b32_e32 v109, 0xffff0000, v109
	v_and_b32_e32 v108, 0xffff0000, v108
	v_mul_f32_e32 v170, v104, v104
	v_mov_b32_e32 v99, v171
	v_mul_f32_e32 v144, v177, v177
	v_mov_b32_e32 v171, v147
	v_mul_f32_e32 v130, v106, v106
	v_mul_f32_e32 v118, v107, v107
	s_waitcnt vmcnt(16)
	v_lshlrev_b32_e32 v160, 16, v110
	v_and_b32_e32 v161, 0xffff0000, v110
	v_lshlrev_b32_e32 v110, 16, v112
	v_lshlrev_b32_e32 v164, 16, v111
	v_pk_mul_f32 v[172:173], v[108:109], v[108:109]
	v_pk_add_f32 v[132:133], v[170:171], v[144:145]
	v_pk_add_f32 v[118:119], v[130:131], v[118:119]
	v_and_b32_e32 v165, 0xffff0000, v111
	v_mul_f32_e32 v111, v160, v160
	v_mul_f32_e32 v175, v161, v161
	v_mul_f32_e32 v176, v164, v164
	v_mov_b32_e32 v174, v110
	v_mov_b32_e32 v182, v162
	v_mov_b32_e32 v183, v108
	v_mov_b32_e32 v108, v163
	v_pk_fma_f32 v[162:163], v[162:163], v[162:163], v[172:173]
	v_pk_add_f32 v[118:119], v[132:133], v[118:119]
	v_and_b32_e32 v179, 0xffff0000, v112
	v_lshlrev_b32_e32 v112, 16, v113
	v_and_b32_e32 v113, 0xffff0000, v113
	v_pk_fma_f32 v[166:167], v[164:165], v[164:165], v[176:177] op_sel_hi:[1,1,0]
	v_pk_add_f32 v[168:169], v[110:111], v[174:175]
	v_pk_add_f32 v[138:139], v[162:163], v[162:163] op_sel_hi:[0,1]
	v_pk_add_f32 v[118:119], v[118:119], v[118:119] op_sel_hi:[0,1]
	v_mul_f32_e32 v178, v110, v110
	v_mov_b32_e32 v111, v179
	v_mul_f32_e32 v166, v179, v179
	v_mov_b32_e32 v179, v169
	v_mul_f32_e32 v138, v112, v112
	v_mul_f32_e32 v118, v113, v113
	v_pk_add_f32 v[136:137], v[178:179], v[166:167]
	v_pk_add_f32 v[118:119], v[138:139], v[118:119]
	v_mov_b32_e32 v73, v97
	v_pk_add_f32 v[118:119], v[136:137], v[118:119]
	v_mov_b32_e32 v105, v177
	v_add_f32_e32 v97, v118, v119
	ds_bpermute_b32 v118, v1, v97
	s_waitcnt lgkmcnt(0)
	v_add_f32_e32 v97, v97, v118
	ds_bpermute_b32 v118, v90, v97
	s_waitcnt lgkmcnt(0)
	v_add_f32_e32 v97, v97, v118
	ds_bpermute_b32 v118, v91, v97
	s_waitcnt lgkmcnt(0)
	v_add_f32_e32 v97, v97, v118
	ds_bpermute_b32 v118, v92, v97
	s_waitcnt lgkmcnt(0)
	v_add_f32_e32 v97, v97, v118
	ds_bpermute_b32 v118, v93, v97
	s_waitcnt lgkmcnt(0)
	v_add_f32_e32 v97, v97, v118
	ds_bpermute_b32 v118, v94, v97
	s_waitcnt lgkmcnt(0)
; __device__ __forceinline__ u32x4 pack8(const f32x4 a, const f32x4 b) { u32x4 w; w.x = cvt_pk_bf16(a[0], a[1]); w.y = cvt_pk_bf16(a[2], a[3]); w.z = cvt_pk_bf16(b[0], b[1]); w.w = cvt_pk_bf16(b[2], b[3]); return w; }
; __device__ __forceinline__ float row_rnorm(const f32x4 (&v)[16]) {
;     ...
;     return 1.0f / sqrtf(wave_sum(s) * (1.0f / D) + EPS);
; }
; __device__ __forceinline__ void norm_phase(Frame& F, const float* gain, int nsplit, float scale, const float* samp_base) {
;     (void)nsplit;
;     norm_sample_row<false>(F, gain, scale, samp_base, nullptr);
;     f32x4 gn[16]; load_gain8(gain, F.lane, gn);
;     for (int m = F.gw; m < NPROMPT; m += F.ngw) {
;         f32x4 v[16]; load_xrow(F, m, v);
;         const float r = row_rnorm(v);
;         v4u* o8 = (v4u*)((bf16*)(F.ws + WS_H) + (size_t)m * D) + F.lane;
; #pragma unroll
;         for (int j = 0; j < 8; ++j) o8[64 * j] = pg8::pack8(v[2 * j] * r * gn[2 * j], v[2 * j + 1] * r * gn[2 * j + 1]);
;     }
	v_add_f32_e32 v97, v97, v118
	v_fmamk_f32 v97, v97, 0x39800000, v95
	v_mul_f32_e32 v118, 0x4f800000, v97
	v_cmp_gt_f32_e32 vcc, s5, v97
	s_nop 1
	v_cndmask_b32_e32 v97, v97, v118, vcc
	v_sqrt_f32_e32 v118, v97
	s_nop 0
	v_add_u32_e32 v119, -1, v118
	v_add_u32_e32 v122, 1, v118
	v_fma_f32 v123, -v119, v118, v97
	v_fma_f32 v126, -v122, v118, v97
	v_cmp_ge_f32_e64 s[0:1], 0, v123
	s_nop 1
	v_cndmask_b32_e64 v118, v118, v119, s[0:1]
	v_cmp_lt_f32_e64 s[0:1], 0, v126
	s_nop 1
	v_cndmask_b32_e64 v118, v118, v122, s[0:1]
	v_mul_f32_e32 v119, 0x37800000, v118
	v_cndmask_b32_e32 v118, v118, v119, vcc
	v_cmp_class_f32_e32 vcc, v97, v96
	s_nop 1
	v_cndmask_b32_e32 v97, v118, v97, vcc
	v_div_scale_f32 v118, s[0:1], v97, v97, 1.0
	v_rcp_f32_e32 v122, v118
	v_div_scale_f32 v119, vcc, 1.0, v97, 1.0
	v_fma_f32 v123, -v118, v122, 1.0
	v_fmac_f32_e32 v122, v123, v122
	v_mul_f32_e32 v123, v119, v122
	v_fma_f32 v126, -v118, v123, v119
	v_fmac_f32_e32 v123, v126, v122
	v_fma_f32 v118, -v118, v123, v119
	v_div_fmas_f32 v118, v118, v122, v123
	v_div_fixup_f32 v118, v118, v97, 1.0
	v_pk_mul_f32 v[116:117], v[118:119], v[116:117] op_sel_hi:[0,1]
	v_pk_mul_f32 v[78:79], v[118:119], v[78:79] op_sel_hi:[0,1]
	v_pk_mul_f32 v[122:123], v[118:119], v[150:151] op_sel_hi:[0,1]
	v_pk_mul_f32 v[80:81], v[118:119], v[80:81] op_sel_hi:[0,1]
	v_pk_mul_f32 v[126:127], v[118:119], v[152:153] op_sel_hi:[0,1]
	v_pk_mul_f32 v[66:67], v[118:119], v[66:67] op_sel_hi:[0,1]
	v_pk_mul_f32 v[68:69], v[118:119], v[68:69] op_sel_hi:[0,1]
	v_pk_mul_f32 v[120:121], v[118:119], v[120:121] op_sel_hi:[0,1]
	v_pk_mul_f32 v[74:75], v[118:119], v[74:75] op_sel_hi:[0,1]
	v_pk_mul_f32 v[84:85], v[118:119], v[84:85] op_sel_hi:[0,1]
	v_pk_mul_f32 v[76:77], v[118:119], v[76:77] op_sel_hi:[0,1]
	v_pk_mul_f32 v[70:71], v[118:119], v[70:71] op_sel_hi:[0,1]
	v_pk_mul_f32 v[114:115], v[118:119], v[114:115] op_sel_hi:[0,1]
	v_pk_mul_f32 v[124:125], v[118:119], v[124:125] op_sel_hi:[0,1]
	v_pk_mul_f32 v[72:73], v[118:119], v[72:73] op_sel_hi:[0,1]
	v_pk_mul_f32 v[128:129], v[118:119], v[154:155] op_sel_hi:[0,1]
	v_pk_mul_f32 v[130:131], v[118:119], v[156:157] op_sel_hi:[0,1]
	v_pk_mul_f32 v[132:133], v[118:119], v[142:143] op_sel_hi:[0,1]
	v_pk_mul_f32 v[98:99], v[118:119], v[98:99] op_sel_hi:[0,1]
	v_pk_mul_f32 v[100:101], v[118:119], v[100:101] op_sel_hi:[0,1]
	v_pk_mul_f32 v[134:135], v[118:119], v[180:181] op_sel_hi:[0,1]
	v_pk_mul_f32 v[102:103], v[118:119], v[102:103] op_sel_hi:[0,1]
	v_pk_mul_f32 v[136:137], v[118:119], v[158:159] op_sel_hi:[0,1]
	v_pk_mul_f32 v[138:139], v[118:119], v[148:149] op_sel_hi:[0,1]
	v_pk_mul_f32 v[104:105], v[118:119], v[104:105] op_sel_hi:[0,1]
	v_pk_mul_f32 v[106:107], v[118:119], v[106:107] op_sel_hi:[0,1]
	v_pk_mul_f32 v[140:141], v[118:119], v[182:183] op_sel_hi:[0,1]
	v_pk_mul_f32 v[108:109], v[118:119], v[108:109] op_sel_hi:[0,1]
	v_pk_mul_f32 v[142:143], v[118:119], v[160:161] op_sel_hi:[0,1]
	v_pk_mul_f32 v[144:145], v[118:119], v[164:165] op_sel_hi:[0,1]
	v_pk_mul_f32 v[110:111], v[118:119], v[110:111] op_sel_hi:[0,1]
	v_pk_mul_f32 v[112:113], v[118:119], v[112:113] op_sel_hi:[0,1]
	v_pk_mul_f32 v[78:79], v[52:53], v[78:79]
	v_pk_mul_f32 v[116:117], v[50:51], v[116:117]
	v_pk_mul_f32 v[80:81], v[4:5], v[80:81]
	v_pk_mul_f32 v[118:119], v[2:3], v[122:123]
	v_pk_mul_f32 v[122:123], v[14:15], v[126:127]
	v_pk_mul_f32 v[126:127], v[44:45], v[66:67]
	v_pk_mul_f32 v[146:147], v[24:25], v[68:69]
	v_cvt_pk_bf16_f32 v66, v116, v117
	v_cvt_pk_bf16_f32 v67, v78, v79
	v_cvt_pk_bf16_f32 v68, v118, v119
	v_cvt_pk_bf16_f32 v69, v80, v81
	v_pk_mul_f32 v[74:75], v[8:9], v[74:75]
	v_pk_mul_f32 v[120:121], v[6:7], v[120:121]
	v_pk_mul_f32 v[76:77], v[12:13], v[76:77]
	v_pk_mul_f32 v[84:85], v[10:11], v[84:85]
	global_store_dwordx4 v[86:87], v[66:69], off offset:-4096
	v_pk_mul_f32 v[70:71], v[16:17], v[70:71]
	v_pk_mul_f32 v[124:125], v[20:21], v[124:125]
	v_cvt_pk_bf16_f32 v66, v120, v121
	v_cvt_pk_bf16_f32 v67, v74, v75
	v_cvt_pk_bf16_f32 v68, v84, v85
	v_cvt_pk_bf16_f32 v69, v76, v77
	v_pk_mul_f32 v[114:115], v[18:19], v[114:115]
	global_store_dwordx4 v[88:89], v[66:69], off offset:1024
	v_pk_mul_f32 v[72:73], v[42:43], v[72:73]
	v_pk_mul_f32 v[128:129], v[22:23], v[128:129]
	v_cvt_pk_bf16_f32 v66, v122, v123
	v_cvt_pk_bf16_f32 v67, v70, v71
	v_cvt_pk_bf16_f32 v68, v114, v115
	v_cvt_pk_bf16_f32 v69, v124, v125
	global_store_dwordx4 v[88:89], v[66:69], off offset:2048
	v_pk_mul_f32 v[132:133], v[28:29], v[132:133]
	v_pk_mul_f32 v[130:131], v[26:27], v[130:131]
	v_cvt_pk_bf16_f32 v66, v72, v73
	v_cvt_pk_bf16_f32 v67, v126, v127
	v_cvt_pk_bf16_f32 v68, v128, v129
	v_cvt_pk_bf16_f32 v69, v146, v147
	v_pk_mul_f32 v[100:101], v[36:37], v[100:101]
	v_pk_mul_f32 v[98:99], v[34:35], v[98:99]
	global_store_dwordx4 v[88:89], v[66:69], off offset:3072
	v_pk_mul_f32 v[102:103], v[32:33], v[102:103]
	v_pk_mul_f32 v[134:135], v[30:31], v[134:135]
	v_cvt_pk_bf16_f32 v66, v130, v131
	v_cvt_pk_bf16_f32 v67, v132, v133
	v_cvt_pk_bf16_f32 v68, v98, v99
	v_cvt_pk_bf16_f32 v69, v100, v101
	v_pk_mul_f32 v[138:139], v[40:41], v[138:139]
	v_pk_mul_f32 v[136:137], v[38:39], v[136:137]
	global_store_dwordx4 v[86:87], v[66:69], off
	v_pk_mul_f32 v[106:107], v[48:49], v[106:107]
	v_pk_mul_f32 v[104:105], v[46:47], v[104:105]
	v_cvt_pk_bf16_f32 v66, v134, v135
	v_cvt_pk_bf16_f32 v67, v102, v103
	v_cvt_pk_bf16_f32 v68, v136, v137
	v_cvt_pk_bf16_f32 v69, v138, v139
	v_pk_mul_f32 v[108:109], v[60:61], v[108:109]
	v_pk_mul_f32 v[140:141], v[58:59], v[140:141]
	global_store_dwordx4 v[86:87], v[66:69], off offset:1024
	v_pk_mul_f32 v[144:145], v[56:57], v[144:145]
	v_pk_mul_f32 v[142:143], v[54:55], v[142:143]
	v_cvt_pk_bf16_f32 v66, v104, v105
	v_cvt_pk_bf16_f32 v67, v106, v107
	v_cvt_pk_bf16_f32 v68, v140, v141
	v_cvt_pk_bf16_f32 v69, v108, v109
	v_pk_mul_f32 v[112:113], v[64:65], v[112:113]
	v_pk_mul_f32 v[110:111], v[62:63], v[110:111]
	global_store_dwordx4 v[86:87], v[66:69], off offset:2048
	s_nop 1
	v_cvt_pk_bf16_f32 v66, v142, v143
	v_cvt_pk_bf16_f32 v67, v144, v145
	v_cvt_pk_bf16_f32 v68, v110, v111
	v_cvt_pk_bf16_f32 v69, v112, v113
	global_store_dwordx4 v[86:87], v[66:69], off offset:3072
	v_add_co_u32_e32 v84, vcc, s4, v82
	v_add_co_u32_e64 v88, s[0:1], s8, v82
	s_nop 0
	v_addc_co_u32_e32 v85, vcc, 0, v83, vcc
	v_addc_co_u32_e64 v89, s[0:1], 0, v83, s[0:1]
	v_add_co_u32_e64 v86, s[0:1], s9, v82
	s_add_i32 s10, s10, s90
	s_nop 0
	v_addc_co_u32_e64 v87, s[0:1], 0, v83, s[0:1]
	v_lshl_add_u64 v[82:83], v[82:83], 0, s[2:3]
	s_cmpk_lt_i32 s10, 0x2000
	s_waitcnt vmcnt(15)
; __device__ __forceinline__ void unpack8(const u32x4 w, f32x4& a, f32x4& b) { a = (f32x4){bflo(w.x), bfhi(w.x), bflo(w.y), bfhi(w.y)}; b = (f32x4){bflo(w.z), bfhi(w.z), bflo(w.w), bfhi(w.w)}; }
; __device__ __forceinline__ void load_xrow(Frame& F, int m, f32x4 (&v)[16]) {
;     const v4u* xr = (const v4u*)((const bf16*)(F.ws + WS_XRES) + (size_t)m * D) + F.lane;
;     v4u w[8];
; #pragma unroll
;     for (int j = 0; j < 8; ++j) w[j] = xr[64 * j];
; #pragma unroll
;     for (int j = 0; j < 8; ++j) pg8::unpack8(w[j], v[2 * j], v[2 * j + 1]);
; }
; __device__ __forceinline__ float row_rnorm(const f32x4 (&v)[16]) {
;     float s = 0.f;
; #pragma unroll
;     for (int j = 0; j < 16; ++j) s += (v[j].x * v[j].x + v[j].y * v[j].y) + (v[j].z * v[j].z + v[j].w * v[j].w);
;     return 1.0f / sqrtf(wave_sum(s) * (1.0f / D) + EPS);
	v_lshlrev_b32_e32 v120, 16, v200
	v_and_b32_e32 v121, 0xffff0000, v200
	v_lshlrev_b32_e32 v200, 16, v201
	s_waitcnt vmcnt(12)
	v_lshlrev_b32_e32 v116, 16, v212
	v_and_b32_e32 v117, 0xffff0000, v212
	v_lshlrev_b32_e32 v212, 16, v213
	v_lshlrev_b32_e32 v119, 16, v215
	v_lshlrev_b32_e32 v118, 16, v214
	v_and_b32_e32 v215, 0xffff0000, v215
	v_and_b32_e32 v214, 0xffff0000, v214
	v_and_b32_e32 v213, 0xffff0000, v213
	v_mul_f32_e32 v128, v116, v116
	v_mul_f32_e32 v130, v212, v212
	v_pk_mul_f32 v[132:133], v[214:215], v[214:215]
	v_and_b32_e32 v201, 0xffff0000, v201
	v_mul_f32_e32 v134, v120, v120
	v_mul_f32_e32 v136, v200, v200
	v_mov_b32_e32 v150, v118
	v_mov_b32_e32 v151, v214
	v_mov_b32_e32 v214, v119
	v_pk_fma_f32 v[128:129], v[116:117], v[116:117], v[128:129] op_sel_hi:[1,1,0]
	v_pk_fma_f32 v[130:131], v[212:213], v[212:213], v[130:131] op_sel_hi:[1,1,0]
	v_pk_fma_f32 v[118:119], v[118:119], v[118:119], v[132:133]
	v_lshlrev_b32_e32 v84, 16, v202
	v_and_b32_e32 v85, 0xffff0000, v202
	v_lshlrev_b32_e32 v202, 16, v203
	v_and_b32_e32 v203, 0xffff0000, v203
	v_pk_fma_f32 v[132:133], v[120:121], v[120:121], v[134:135] op_sel_hi:[1,1,0]
	v_pk_fma_f32 v[134:135], v[200:201], v[200:201], v[136:137] op_sel_hi:[1,1,0]
	v_pk_add_f32 v[118:119], v[118:119], v[118:119] op_sel_hi:[0,1]
	v_pk_add_f32 v[128:129], v[128:129], v[130:131]
	v_lshlrev_b32_e32 v123, 16, v205
	v_lshlrev_b32_e32 v122, 16, v204
	v_and_b32_e32 v205, 0xffff0000, v205
	v_and_b32_e32 v204, 0xffff0000, v204
	v_mul_f32_e32 v138, v84, v84
	v_mul_f32_e32 v132, v202, v202
	v_mul_f32_e32 v134, v203, v203
	v_mul_f32_e32 v118, v85, v85
	v_mov_b32_e32 v139, v129
	v_lshlrev_b32_e32 v114, 16, v206
	v_and_b32_e32 v115, 0xffff0000, v206
	v_lshlrev_b32_e32 v206, 16, v208
	v_lshlrev_b32_e32 v124, 16, v207
	v_pk_mul_f32 v[140:141], v[204:205], v[204:205]
	v_pk_add_f32 v[132:133], v[132:133], v[134:135]
	v_pk_add_f32 v[118:119], v[138:139], v[118:119]
	v_and_b32_e32 v125, 0xffff0000, v207
	v_lshlrev_b32_e32 v127, 16, v211
	v_lshlrev_b32_e32 v126, 16, v210
	v_and_b32_e32 v211, 0xffff0000, v211
	v_and_b32_e32 v210, 0xffff0000, v210
	v_mul_f32_e32 v207, v114, v114
	v_mul_f32_e32 v143, v115, v115
	v_mul_f32_e32 v144, v124, v124
	v_mov_b32_e32 v142, v206
	v_mov_b32_e32 v152, v122
	v_mov_b32_e32 v153, v204
	v_mov_b32_e32 v204, v123
	v_pk_fma_f32 v[122:123], v[122:123], v[122:123], v[140:141]
	v_pk_add_f32 v[118:119], v[118:119], v[132:133]
	v_and_b32_e32 v97, 0xffff0000, v208
	v_lshlrev_b32_e32 v208, 16, v209
	v_and_b32_e32 v209, 0xffff0000, v209
	v_pk_mul_f32 v[148:149], v[210:211], v[210:211]
	v_pk_fma_f32 v[136:137], v[124:125], v[124:125], v[144:145] op_sel_hi:[1,1,0]
	v_pk_add_f32 v[140:141], v[206:207], v[142:143]
	v_pk_add_f32 v[122:123], v[122:123], v[122:123] op_sel_hi:[0,1]
	v_pk_add_f32 v[118:119], v[118:119], v[118:119] op_sel_hi:[0,1]
	v_mul_f32_e32 v146, v206, v206
	v_mov_b32_e32 v154, v126
	v_mov_b32_e32 v155, v210
	v_mov_b32_e32 v210, v127
	v_pk_fma_f32 v[126:127], v[126:127], v[126:127], v[148:149]
	v_mul_f32_e32 v136, v97, v97
	v_mov_b32_e32 v147, v141
	v_mul_f32_e32 v122, v208, v208
	v_mul_f32_e32 v118, v209, v209
	s_waitcnt vmcnt(11)
	v_lshlrev_b32_e32 v156, 16, v216
	v_and_b32_e32 v157, 0xffff0000, v216
	v_lshlrev_b32_e32 v216, 16, v218
	v_lshlrev_b32_e32 v142, 16, v217
	v_pk_add_f32 v[126:127], v[126:127], v[126:127] op_sel_hi:[0,1]
	v_pk_add_f32 v[134:135], v[146:147], v[136:137]
	v_pk_add_f32 v[118:119], v[122:123], v[118:119]
	v_and_b32_e32 v143, 0xffff0000, v217
	v_mul_f32_e32 v217, v156, v156
	v_mul_f32_e32 v131, v157, v157
	v_mul_f32_e32 v126, v142, v142
	v_mov_b32_e32 v130, v216
	v_pk_add_f32 v[118:119], v[134:135], v[118:119]
	v_and_b32_e32 v171, 0xffff0000, v218
	v_lshlrev_b32_e32 v218, 16, v219
	v_and_b32_e32 v219, 0xffff0000, v219
	v_pk_fma_f32 v[136:137], v[142:143], v[142:143], v[126:127] op_sel_hi:[1,1,0]
	v_pk_add_f32 v[130:131], v[216:217], v[130:131]
	v_pk_add_f32 v[118:119], v[118:119], v[118:119] op_sel_hi:[0,1]
	s_waitcnt vmcnt(10)
	v_lshlrev_b32_e32 v145, 16, v221
	v_lshlrev_b32_e32 v144, 16, v220
	v_and_b32_e32 v221, 0xffff0000, v221
	v_and_b32_e32 v220, 0xffff0000, v220
	v_mul_f32_e32 v128, v216, v216
	v_mul_f32_e32 v126, v218, v218
	v_mul_f32_e32 v136, v171, v171
	v_mov_b32_e32 v129, v131
	v_mul_f32_e32 v118, v219, v219
	v_lshlrev_b32_e32 v158, 16, v222
	v_and_b32_e32 v159, 0xffff0000, v222
	s_waitcnt vmcnt(9)
	v_lshlrev_b32_e32 v222, 16, v224
	v_lshlrev_b32_e32 v148, 16, v223
	v_pk_mul_f32 v[140:141], v[220:221], v[220:221]
	v_pk_add_f32 v[128:129], v[128:129], v[136:137]
	v_pk_add_f32 v[118:119], v[126:127], v[118:119]
	v_and_b32_e32 v149, 0xffff0000, v223
	v_mul_f32_e32 v223, v158, v158
	v_mul_f32_e32 v167, v159, v159
	v_mul_f32_e32 v168, v148, v148
	v_mov_b32_e32 v166, v222
	v_pk_fma_f32 v[140:141], v[144:145], v[144:145], v[140:141]
	v_pk_add_f32 v[118:119], v[128:129], v[118:119]
	v_and_b32_e32 v177, 0xffff0000, v224
	v_lshlrev_b32_e32 v224, 16, v225
	v_and_b32_e32 v225, 0xffff0000, v225
	v_mov_b32_e32 v180, v144
	v_mov_b32_e32 v181, v220
	v_mov_b32_e32 v220, v145
	v_pk_fma_f32 v[144:145], v[148:149], v[148:149], v[168:169] op_sel_hi:[1,1,0]
	v_pk_add_f32 v[146:147], v[222:223], v[166:167]
	v_pk_add_f32 v[130:131], v[140:141], v[140:141] op_sel_hi:[0,1]
	v_pk_add_f32 v[118:119], v[118:119], v[118:119] op_sel_hi:[0,1]
	v_lshlrev_b32_e32 v163, 16, v227
	v_lshlrev_b32_e32 v162, 16, v226
	v_and_b32_e32 v227, 0xffff0000, v227
	v_and_b32_e32 v226, 0xffff0000, v226
	v_mul_f32_e32 v170, v222, v222
	v_mov_b32_e32 v217, v171
	v_mul_f32_e32 v144, v177, v177
	v_mov_b32_e32 v171, v147
	v_mul_f32_e32 v130, v224, v224
	v_mul_f32_e32 v118, v225, v225
	s_waitcnt vmcnt(8)
; __device__ __forceinline__ float wave_sum(float v) {
; #pragma unroll
;     for (int o = 1; o < 64; o <<= 1) v += __shfl_xor(v, o);
;     return v;
; }
; __device__ __forceinline__ float row_rnorm(const f32x4 (&v)[16]) {
;     float s = 0.f;
; #pragma unroll
;     for (int j = 0; j < 16; ++j) s += (v[j].x * v[j].x + v[j].y * v[j].y) + (v[j].z * v[j].z + v[j].w * v[j].w);
;     return 1.0f / sqrtf(wave_sum(s) * (1.0f / D) + EPS);
	v_lshlrev_b32_e32 v160, 16, v228
	v_and_b32_e32 v161, 0xffff0000, v228
	v_lshlrev_b32_e32 v228, 16, v230
	v_lshlrev_b32_e32 v164, 16, v229
	v_pk_mul_f32 v[172:173], v[226:227], v[226:227]
	v_pk_add_f32 v[132:133], v[170:171], v[144:145]
	v_pk_add_f32 v[118:119], v[130:131], v[118:119]
	v_and_b32_e32 v165, 0xffff0000, v229
	v_mul_f32_e32 v229, v160, v160
	v_mul_f32_e32 v175, v161, v161
	v_mul_f32_e32 v176, v164, v164
	v_mov_b32_e32 v174, v228
	v_mov_b32_e32 v182, v162
	v_mov_b32_e32 v183, v226
	v_mov_b32_e32 v226, v163
	v_pk_fma_f32 v[162:163], v[162:163], v[162:163], v[172:173]
	v_pk_add_f32 v[118:119], v[132:133], v[118:119]
	v_and_b32_e32 v179, 0xffff0000, v230
	v_lshlrev_b32_e32 v230, 16, v231
	v_and_b32_e32 v231, 0xffff0000, v231
	v_pk_fma_f32 v[166:167], v[164:165], v[164:165], v[176:177] op_sel_hi:[1,1,0]
	v_pk_add_f32 v[168:169], v[228:229], v[174:175]
	v_pk_add_f32 v[138:139], v[162:163], v[162:163] op_sel_hi:[0,1]
	v_pk_add_f32 v[118:119], v[118:119], v[118:119] op_sel_hi:[0,1]
	v_mul_f32_e32 v178, v228, v228
	v_mov_b32_e32 v229, v179
	v_mul_f32_e32 v166, v179, v179
	v_mov_b32_e32 v179, v169
	v_mul_f32_e32 v138, v230, v230
	v_mul_f32_e32 v118, v231, v231
	v_pk_add_f32 v[136:137], v[178:179], v[166:167]
	v_pk_add_f32 v[118:119], v[138:139], v[118:119]
	v_mov_b32_e32 v207, v97
	v_pk_add_f32 v[118:119], v[136:137], v[118:119]
	v_mov_b32_e32 v223, v177
	v_add_f32_e32 v97, v118, v119
	ds_bpermute_b32 v118, v1, v97
	s_waitcnt lgkmcnt(0)
	v_add_f32_e32 v97, v97, v118
	ds_bpermute_b32 v118, v90, v97
	s_waitcnt lgkmcnt(0)
	v_add_f32_e32 v97, v97, v118
	ds_bpermute_b32 v118, v91, v97
	s_waitcnt lgkmcnt(0)
	v_add_f32_e32 v97, v97, v118
	ds_bpermute_b32 v118, v92, v97
	s_waitcnt lgkmcnt(0)
	v_add_f32_e32 v97, v97, v118
	ds_bpermute_b32 v118, v93, v97
	s_waitcnt lgkmcnt(0)
	v_add_f32_e32 v97, v97, v118
	ds_bpermute_b32 v118, v94, v97
	s_waitcnt lgkmcnt(0)
; __device__ __forceinline__ u32x4 pack8(const f32x4 a, const f32x4 b) { u32x4 w; w.x = cvt_pk_bf16(a[0], a[1]); w.y = cvt_pk_bf16(a[2], a[3]); w.z = cvt_pk_bf16(b[0], b[1]); w.w = cvt_pk_bf16(b[2], b[3]); return w; }
; __device__ __forceinline__ float row_rnorm(const f32x4 (&v)[16]) {
;     ...
;     return 1.0f / sqrtf(wave_sum(s) * (1.0f / D) + EPS);
; }
; __device__ __forceinline__ void norm_phase(Frame& F, const float* gain, int nsplit, float scale, const float* samp_base) {
;     (void)nsplit;
;     norm_sample_row<false>(F, gain, scale, samp_base, nullptr);
;     f32x4 gn[16]; load_gain8(gain, F.lane, gn);
;     for (int m = F.gw; m < NPROMPT; m += F.ngw) {
;         f32x4 v[16]; load_xrow(F, m, v);
;         const float r = row_rnorm(v);
;         v4u* o8 = (v4u*)((bf16*)(F.ws + WS_H) + (size_t)m * D) + F.lane;
; #pragma unroll
;         for (int j = 0; j < 8; ++j) o8[64 * j] = pg8::pack8(v[2 * j] * r * gn[2 * j], v[2 * j + 1] * r * gn[2 * j + 1]);
;     }
	v_add_f32_e32 v97, v97, v118
	v_fmamk_f32 v97, v97, 0x39800000, v95
	v_mul_f32_e32 v118, 0x4f800000, v97
	v_cmp_gt_f32_e32 vcc, s5, v97
	s_nop 1
	v_cndmask_b32_e32 v97, v97, v118, vcc
	v_sqrt_f32_e32 v118, v97
	s_nop 0
	v_add_u32_e32 v119, -1, v118
	v_add_u32_e32 v122, 1, v118
	v_fma_f32 v123, -v119, v118, v97
	v_fma_f32 v126, -v122, v118, v97
	v_cmp_ge_f32_e64 s[0:1], 0, v123
	s_nop 1
	v_cndmask_b32_e64 v118, v118, v119, s[0:1]
	v_cmp_lt_f32_e64 s[0:1], 0, v126
	s_nop 1
	v_cndmask_b32_e64 v118, v118, v122, s[0:1]
	v_mul_f32_e32 v119, 0x37800000, v118
	v_cndmask_b32_e32 v118, v118, v119, vcc
	v_cmp_class_f32_e32 vcc, v97, v96
	s_nop 1
	v_cndmask_b32_e32 v97, v118, v97, vcc
	v_div_scale_f32 v118, s[0:1], v97, v97, 1.0
	v_rcp_f32_e32 v122, v118
	v_div_scale_f32 v119, vcc, 1.0, v97, 1.0
	v_fma_f32 v123, -v118, v122, 1.0
	v_fmac_f32_e32 v122, v123, v122
	v_mul_f32_e32 v123, v119, v122
	v_fma_f32 v126, -v118, v123, v119
	v_fmac_f32_e32 v123, v126, v122
	v_fma_f32 v118, -v118, v123, v119
	v_div_fmas_f32 v118, v118, v122, v123
	v_div_fixup_f32 v118, v118, v97, 1.0
	v_pk_mul_f32 v[116:117], v[118:119], v[116:117] op_sel_hi:[0,1]
	v_pk_mul_f32 v[212:213], v[118:119], v[212:213] op_sel_hi:[0,1]
	v_pk_mul_f32 v[122:123], v[118:119], v[150:151] op_sel_hi:[0,1]
	v_pk_mul_f32 v[214:215], v[118:119], v[214:215] op_sel_hi:[0,1]
	v_pk_mul_f32 v[126:127], v[118:119], v[152:153] op_sel_hi:[0,1]
	v_pk_mul_f32 v[208:209], v[118:119], v[208:209] op_sel_hi:[0,1]
	v_pk_mul_f32 v[210:211], v[118:119], v[210:211] op_sel_hi:[0,1]
	v_pk_mul_f32 v[120:121], v[118:119], v[120:121] op_sel_hi:[0,1]
	v_pk_mul_f32 v[200:201], v[118:119], v[200:201] op_sel_hi:[0,1]
	v_pk_mul_f32 v[84:85], v[118:119], v[84:85] op_sel_hi:[0,1]
	v_pk_mul_f32 v[202:203], v[118:119], v[202:203] op_sel_hi:[0,1]
	v_pk_mul_f32 v[204:205], v[118:119], v[204:205] op_sel_hi:[0,1]
	v_pk_mul_f32 v[114:115], v[118:119], v[114:115] op_sel_hi:[0,1]
	v_pk_mul_f32 v[124:125], v[118:119], v[124:125] op_sel_hi:[0,1]
	v_pk_mul_f32 v[206:207], v[118:119], v[206:207] op_sel_hi:[0,1]
	v_pk_mul_f32 v[128:129], v[118:119], v[154:155] op_sel_hi:[0,1]
	v_pk_mul_f32 v[130:131], v[118:119], v[156:157] op_sel_hi:[0,1]
	v_pk_mul_f32 v[132:133], v[118:119], v[142:143] op_sel_hi:[0,1]
	v_pk_mul_f32 v[216:217], v[118:119], v[216:217] op_sel_hi:[0,1]
	v_pk_mul_f32 v[218:219], v[118:119], v[218:219] op_sel_hi:[0,1]
	v_pk_mul_f32 v[134:135], v[118:119], v[180:181] op_sel_hi:[0,1]
	v_pk_mul_f32 v[220:221], v[118:119], v[220:221] op_sel_hi:[0,1]
	v_pk_mul_f32 v[136:137], v[118:119], v[158:159] op_sel_hi:[0,1]
	v_pk_mul_f32 v[138:139], v[118:119], v[148:149] op_sel_hi:[0,1]
	v_pk_mul_f32 v[222:223], v[118:119], v[222:223] op_sel_hi:[0,1]
	v_pk_mul_f32 v[224:225], v[118:119], v[224:225] op_sel_hi:[0,1]
	v_pk_mul_f32 v[140:141], v[118:119], v[182:183] op_sel_hi:[0,1]
	v_pk_mul_f32 v[226:227], v[118:119], v[226:227] op_sel_hi:[0,1]
	v_pk_mul_f32 v[142:143], v[118:119], v[160:161] op_sel_hi:[0,1]
	v_pk_mul_f32 v[144:145], v[118:119], v[164:165] op_sel_hi:[0,1]
	v_pk_mul_f32 v[228:229], v[118:119], v[228:229] op_sel_hi:[0,1]
	v_pk_mul_f32 v[230:231], v[118:119], v[230:231] op_sel_hi:[0,1]
	v_pk_mul_f32 v[212:213], v[52:53], v[212:213]
	v_pk_mul_f32 v[116:117], v[50:51], v[116:117]
	v_pk_mul_f32 v[214:215], v[4:5], v[214:215]
	v_pk_mul_f32 v[118:119], v[2:3], v[122:123]
	v_pk_mul_f32 v[122:123], v[14:15], v[126:127]
	v_pk_mul_f32 v[126:127], v[44:45], v[208:209]
	v_pk_mul_f32 v[146:147], v[24:25], v[210:211]
	v_cvt_pk_bf16_f32 v208, v116, v117
	v_cvt_pk_bf16_f32 v209, v212, v213
	v_cvt_pk_bf16_f32 v210, v118, v119
	v_cvt_pk_bf16_f32 v211, v214, v215
	v_pk_mul_f32 v[200:201], v[8:9], v[200:201]
	v_pk_mul_f32 v[120:121], v[6:7], v[120:121]
	v_pk_mul_f32 v[202:203], v[12:13], v[202:203]
	v_pk_mul_f32 v[84:85], v[10:11], v[84:85]
	global_store_dwordx4 v[86:87], v[208:211], off offset:-4096
	v_pk_mul_f32 v[204:205], v[16:17], v[204:205]
	v_pk_mul_f32 v[124:125], v[20:21], v[124:125]
	v_cvt_pk_bf16_f32 v208, v120, v121
	v_cvt_pk_bf16_f32 v209, v200, v201
	v_cvt_pk_bf16_f32 v210, v84, v85
	v_cvt_pk_bf16_f32 v211, v202, v203
	v_pk_mul_f32 v[114:115], v[18:19], v[114:115]
	global_store_dwordx4 v[88:89], v[208:211], off offset:1024
	v_pk_mul_f32 v[206:207], v[42:43], v[206:207]
	v_pk_mul_f32 v[128:129], v[22:23], v[128:129]
	v_cvt_pk_bf16_f32 v208, v122, v123
	v_cvt_pk_bf16_f32 v209, v204, v205
	v_cvt_pk_bf16_f32 v210, v114, v115
	v_cvt_pk_bf16_f32 v211, v124, v125
	global_store_dwordx4 v[88:89], v[208:211], off offset:2048
	v_pk_mul_f32 v[132:133], v[28:29], v[132:133]
	v_pk_mul_f32 v[130:131], v[26:27], v[130:131]
	v_cvt_pk_bf16_f32 v208, v206, v207
	v_cvt_pk_bf16_f32 v209, v126, v127
	v_cvt_pk_bf16_f32 v210, v128, v129
	v_cvt_pk_bf16_f32 v211, v146, v147
	v_pk_mul_f32 v[218:219], v[36:37], v[218:219]
	v_pk_mul_f32 v[216:217], v[34:35], v[216:217]
	global_store_dwordx4 v[88:89], v[208:211], off offset:3072
	v_pk_mul_f32 v[220:221], v[32:33], v[220:221]
	v_pk_mul_f32 v[134:135], v[30:31], v[134:135]
	v_cvt_pk_bf16_f32 v208, v130, v131
	v_cvt_pk_bf16_f32 v209, v132, v133
	v_cvt_pk_bf16_f32 v210, v216, v217
	v_cvt_pk_bf16_f32 v211, v218, v219
	v_pk_mul_f32 v[138:139], v[40:41], v[138:139]
	v_pk_mul_f32 v[136:137], v[38:39], v[136:137]
	global_store_dwordx4 v[86:87], v[208:211], off
	v_pk_mul_f32 v[224:225], v[48:49], v[224:225]
	v_pk_mul_f32 v[222:223], v[46:47], v[222:223]
	v_cvt_pk_bf16_f32 v208, v134, v135
	v_cvt_pk_bf16_f32 v209, v220, v221
	v_cvt_pk_bf16_f32 v210, v136, v137
	v_cvt_pk_bf16_f32 v211, v138, v139
	v_pk_mul_f32 v[226:227], v[60:61], v[226:227]
	v_pk_mul_f32 v[140:141], v[58:59], v[140:141]
	global_store_dwordx4 v[86:87], v[208:211], off offset:1024
	v_pk_mul_f32 v[144:145], v[56:57], v[144:145]
	v_pk_mul_f32 v[142:143], v[54:55], v[142:143]
	v_cvt_pk_bf16_f32 v208, v222, v223
	v_cvt_pk_bf16_f32 v209, v224, v225
	v_cvt_pk_bf16_f32 v210, v140, v141
	v_cvt_pk_bf16_f32 v211, v226, v227
	v_pk_mul_f32 v[230:231], v[64:65], v[230:231]
	v_pk_mul_f32 v[228:229], v[62:63], v[228:229]
	global_store_dwordx4 v[86:87], v[208:211], off offset:2048
	s_nop 1
	v_cvt_pk_bf16_f32 v208, v142, v143
	v_cvt_pk_bf16_f32 v209, v144, v145
	v_cvt_pk_bf16_f32 v210, v228, v229
	v_cvt_pk_bf16_f32 v211, v230, v231
	global_store_dwordx4 v[86:87], v[208:211], off offset:3072

; __device__ __forceinline__ void unpack8(const u32x4 w, f32x4& a, f32x4& b) { a = (f32x4){bflo(w.x), bfhi(w.x), bflo(w.y), bfhi(w.y)}; b = (f32x4){bflo(w.z), bfhi(w.z), bflo(w.w), bfhi(w.w)}; }
; __device__ __forceinline__ void load_xrow(Frame& F, int m, f32x4 (&v)[16]) {
;     const v4u* xr = (const v4u*)((const bf16*)(F.ws + WS_XRES) + (size_t)m * D) + F.lane;
;     v4u w[8];
; #pragma unroll
;     for (int j = 0; j < 8; ++j) w[j] = xr[64 * j];
; #pragma unroll
;     for (int j = 0; j < 8; ++j) pg8::unpack8(w[j], v[2 * j], v[2 * j + 1]);
; __device__ __forceinline__ void final_norm_phase(Frame& F, const Args& A, int nsplit, float scale) {
;     (void)nsplit;
;     norm_sample_row<true>(F, A.in[28], scale, nullptr, F.out);
;     f32x4 gn[16]; load_gain8(A.in[28], F.lane, gn);
;     for (int m = F.gw; m < NPROMPT; m += F.ngw) {
;         f32x4 v[16]; load_xrow(F, m, v);
.LBB0_1508:
	v_lshlrev_b32_e32 v199, 4, v198
	v_readfirstlane_b32 s98, v80
	v_readfirstlane_b32 s99, v81
	s_nop 4
	global_load_dwordx4 v[72:75], v[80:81], off offset:1024
	global_load_dwordx4 v[68:71], v[80:81], off offset:2048
	global_load_dwordx4 v[64:67], v[80:81], off offset:3072
	global_load_dwordx4 v[76:79], v[80:81], off
	v_add_co_u32_e32 v84, vcc, s6, v80
	v_add_co_u32_e64 v86, s[0:1], s6, v82
	s_nop 0
	v_addc_co_u32_e32 v85, vcc, 0, v81, vcc
	global_load_dwordx4 v[100:103], v[84:85], off
	global_load_dwordx4 v[104:107], v[84:85], off offset:1024
	global_load_dwordx4 v[108:111], v[84:85], off offset:2048
	global_load_dwordx4 v[112:115], v[84:85], off offset:3072
	s_add_u32 s98, s98, s2
	s_addc_u32 s99, s99, s3
	s_add_u32 s100, s98, 0x1000
	s_addc_u32 s101, s99, 0
	global_load_dwordx4 v[200:203], v199, s[98:99] offset:1024
	global_load_dwordx4 v[204:207], v199, s[98:99] offset:2048
	global_load_dwordx4 v[208:211], v199, s[98:99] offset:3072
	global_load_dwordx4 v[212:215], v199, s[98:99]
	global_load_dwordx4 v[216:219], v199, s[100:101]
	global_load_dwordx4 v[220:223], v199, s[100:101] offset:1024
	global_load_dwordx4 v[224:227], v199, s[100:101] offset:2048
	global_load_dwordx4 v[228:231], v199, s[100:101] offset:3072
	v_addc_co_u32_e64 v87, s[0:1], 0, v83, s[0:1]
	v_add_co_u32_e64 v88, s[0:1], s7, v82
	s_add_i32 s88, s88, s90
	s_nop 0
	v_addc_co_u32_e64 v89, s[0:1], 0, v83, s[0:1]
	v_add_co_u32_e64 v90, s[0:1], s8, v82
	v_lshl_add_u64 v[80:81], v[80:81], 0, s[2:3]
	s_nop 0
	v_addc_co_u32_e64 v91, s[0:1], 0, v83, s[0:1]
	s_cmpk_lt_i32 s88, 0x2000
	s_waitcnt vmcnt(15)
	v_lshlrev_b32_e32 v122, 16, v72
	v_and_b32_e32 v123, 0xffff0000, v72
	v_lshlrev_b32_e32 v72, 16, v73
	s_waitcnt vmcnt(12)
	v_lshlrev_b32_e32 v118, 16, v76
	v_and_b32_e32 v119, 0xffff0000, v76
	v_lshlrev_b32_e32 v76, 16, v77
	v_lshlrev_b32_e32 v121, 16, v79
	v_lshlrev_b32_e32 v120, 16, v78
	v_and_b32_e32 v79, 0xffff0000, v79
	v_and_b32_e32 v78, 0xffff0000, v78
	v_and_b32_e32 v77, 0xffff0000, v77
	v_lshlrev_b32_e32 v126, 16, v71
	v_mul_f32_e32 v130, v118, v118
	v_mul_f32_e32 v132, v76, v76
	v_pk_mul_f32 v[134:135], v[78:79], v[78:79]
	v_lshlrev_b32_e32 v116, 16, v70
	v_and_b32_e32 v117, 0xffff0000, v70
	v_lshlrev_b32_e32 v70, 16, v64
	v_and_b32_e32 v73, 0xffff0000, v73
	v_lshlrev_b32_e32 v125, 16, v69
	v_lshlrev_b32_e32 v124, 16, v68
	v_and_b32_e32 v69, 0xffff0000, v69
	v_and_b32_e32 v68, 0xffff0000, v68
	v_and_b32_e32 v127, 0xffff0000, v71
	v_mul_f32_e32 v136, v122, v122
	v_mul_f32_e32 v138, v72, v72
	v_mul_f32_e32 v146, v126, v126
	v_mov_b32_e32 v152, v120
	v_mov_b32_e32 v153, v78
	v_mov_b32_e32 v78, v121
	v_pk_fma_f32 v[130:131], v[118:119], v[118:119], v[130:131] op_sel_hi:[1,1,0]
	v_pk_fma_f32 v[132:133], v[76:77], v[76:77], v[132:133] op_sel_hi:[1,1,0]
	v_pk_fma_f32 v[120:121], v[120:121], v[120:121], v[134:135]
	v_lshlrev_b32_e32 v84, 16, v74
	v_and_b32_e32 v85, 0xffff0000, v74
	v_lshlrev_b32_e32 v74, 16, v75
	v_and_b32_e32 v75, 0xffff0000, v75
	v_and_b32_e32 v141, 0xffff0000, v64
	v_pk_mul_f32 v[142:143], v[68:69], v[68:69]
	v_mul_f32_e32 v71, v116, v116
	v_mul_f32_e32 v145, v117, v117
	v_mov_b32_e32 v144, v70
	v_pk_fma_f32 v[134:135], v[122:123], v[122:123], v[136:137] op_sel_hi:[1,1,0]
	v_pk_fma_f32 v[136:137], v[72:73], v[72:73], v[138:139] op_sel_hi:[1,1,0]
	v_pk_fma_f32 v[138:139], v[126:127], v[126:127], v[146:147] op_sel_hi:[1,1,0]
	v_pk_add_f32 v[120:121], v[120:121], v[120:121] op_sel_hi:[0,1]
	v_pk_add_f32 v[130:131], v[130:131], v[132:133]
	v_mul_f32_e32 v140, v84, v84
	v_mov_b32_e32 v154, v124
	v_mov_b32_e32 v155, v68
	v_mov_b32_e32 v68, v125
	v_pk_fma_f32 v[124:125], v[124:125], v[124:125], v[142:143]
	v_pk_add_f32 v[142:143], v[70:71], v[144:145]
	v_mov_b32_e32 v71, v141
	v_mul_f32_e32 v134, v74, v74
	v_mul_f32_e32 v136, v75, v75
	v_mul_f32_e32 v138, v141, v141
	v_mul_f32_e32 v120, v85, v85
	v_mov_b32_e32 v141, v131
	v_pk_add_f32 v[134:135], v[134:135], v[136:137]
	v_pk_add_f32 v[120:121], v[140:141], v[120:121]
	v_lshlrev_b32_e32 v129, 16, v67
	v_lshlrev_b32_e32 v128, 16, v66
	v_and_b32_e32 v67, 0xffff0000, v67
	v_and_b32_e32 v66, 0xffff0000, v66
	v_pk_add_f32 v[120:121], v[120:121], v[134:135]
	v_lshlrev_b32_e32 v64, 16, v65
	v_and_b32_e32 v65, 0xffff0000, v65
	v_pk_mul_f32 v[150:151], v[66:67], v[66:67]
	v_pk_add_f32 v[124:125], v[124:125], v[124:125] op_sel_hi:[0,1]
	v_pk_add_f32 v[120:121], v[120:121], v[120:121] op_sel_hi:[0,1]
	v_mul_f32_e32 v148, v70, v70
	v_mov_b32_e32 v156, v128
	v_mov_b32_e32 v157, v66
	v_mov_b32_e32 v66, v129
	v_pk_fma_f32 v[128:129], v[128:129], v[128:129], v[150:151]
	v_mov_b32_e32 v149, v143
	v_mul_f32_e32 v124, v64, v64
	v_mul_f32_e32 v120, v65, v65
	s_waitcnt vmcnt(11)
	v_lshlrev_b32_e32 v158, 16, v100
	v_and_b32_e32 v159, 0xffff0000, v100
	v_lshlrev_b32_e32 v100, 16, v102
	v_lshlrev_b32_e32 v144, 16, v101
	v_pk_add_f32 v[128:129], v[128:129], v[128:129] op_sel_hi:[0,1]
	v_pk_add_f32 v[136:137], v[148:149], v[138:139]
	v_pk_add_f32 v[120:121], v[124:125], v[120:121]
	v_and_b32_e32 v145, 0xffff0000, v101
	v_mul_f32_e32 v101, v158, v158
	v_mul_f32_e32 v133, v159, v159
	v_mul_f32_e32 v128, v144, v144
	v_mov_b32_e32 v132, v100
	v_pk_add_f32 v[120:121], v[136:137], v[120:121]
	v_and_b32_e32 v173, 0xffff0000, v102
	v_lshlrev_b32_e32 v102, 16, v103
	v_and_b32_e32 v103, 0xffff0000, v103
	v_pk_fma_f32 v[138:139], v[144:145], v[144:145], v[128:129] op_sel_hi:[1,1,0]
	v_pk_add_f32 v[132:133], v[100:101], v[132:133]
	v_pk_add_f32 v[120:121], v[120:121], v[120:121] op_sel_hi:[0,1]
	s_waitcnt vmcnt(10)
; __device__ __forceinline__ void final_norm_phase(Frame& F, const Args& A, int nsplit, float scale) {
;     (void)nsplit;
;     norm_sample_row<true>(F, A.in[28], scale, nullptr, F.out);
;     f32x4 gn[16]; load_gain8(A.in[28], F.lane, gn);
;     for (int m = F.gw; m < NPROMPT; m += F.ngw) {
;         f32x4 v[16]; load_xrow(F, m, v);
;         const float r = row_rnorm(v);
; #pragma unroll
;         for (int j = 0; j < 8; ++j) { f32x4* o = (f32x4*)(F.out + (size_t)m * D + 8 * (64 * j + F.lane)); o[0] = v[2 * j] * r * gn[2 * j]; o[1] = v[2 * j + 1] * r * gn[2 * j + 1]; }
	v_lshlrev_b32_e32 v147, 16, v105
	v_lshlrev_b32_e32 v146, 16, v104
	v_and_b32_e32 v105, 0xffff0000, v105
	v_and_b32_e32 v104, 0xffff0000, v104
	v_mul_f32_e32 v130, v100, v100
	v_mul_f32_e32 v128, v102, v102
	v_mul_f32_e32 v138, v173, v173
	v_mov_b32_e32 v131, v133
	v_mul_f32_e32 v120, v103, v103
	v_lshlrev_b32_e32 v160, 16, v106
	v_and_b32_e32 v161, 0xffff0000, v106
	s_waitcnt vmcnt(9)
	v_lshlrev_b32_e32 v106, 16, v108
	v_lshlrev_b32_e32 v150, 16, v107
	v_pk_mul_f32 v[142:143], v[104:105], v[104:105]
	v_pk_add_f32 v[130:131], v[130:131], v[138:139]
	v_pk_add_f32 v[120:121], v[128:129], v[120:121]
	v_and_b32_e32 v151, 0xffff0000, v107
	v_mul_f32_e32 v107, v160, v160
	v_mul_f32_e32 v169, v161, v161
	v_mul_f32_e32 v170, v150, v150
	v_mov_b32_e32 v168, v106
	v_pk_fma_f32 v[142:143], v[146:147], v[146:147], v[142:143]
	v_pk_add_f32 v[120:121], v[130:131], v[120:121]
	v_and_b32_e32 v179, 0xffff0000, v108
	v_lshlrev_b32_e32 v108, 16, v109
	v_and_b32_e32 v109, 0xffff0000, v109
	v_mov_b32_e32 v182, v146
	v_mov_b32_e32 v183, v104
	v_mov_b32_e32 v104, v147
	v_pk_fma_f32 v[146:147], v[150:151], v[150:151], v[170:171] op_sel_hi:[1,1,0]
	v_pk_add_f32 v[148:149], v[106:107], v[168:169]
	v_pk_add_f32 v[132:133], v[142:143], v[142:143] op_sel_hi:[0,1]
	v_pk_add_f32 v[120:121], v[120:121], v[120:121] op_sel_hi:[0,1]
	v_lshlrev_b32_e32 v165, 16, v111
	v_lshlrev_b32_e32 v164, 16, v110
	v_and_b32_e32 v111, 0xffff0000, v111
	v_and_b32_e32 v110, 0xffff0000, v110
	v_mul_f32_e32 v172, v106, v106
	v_mov_b32_e32 v101, v173
	v_mul_f32_e32 v146, v179, v179
	v_mov_b32_e32 v173, v149
	v_mul_f32_e32 v132, v108, v108
	v_mul_f32_e32 v120, v109, v109
	s_waitcnt vmcnt(8)
	v_lshlrev_b32_e32 v162, 16, v112
	v_and_b32_e32 v163, 0xffff0000, v112
	v_lshlrev_b32_e32 v112, 16, v114
	v_lshlrev_b32_e32 v166, 16, v113
	v_pk_mul_f32 v[174:175], v[110:111], v[110:111]
	v_pk_add_f32 v[134:135], v[172:173], v[146:147]
	v_pk_add_f32 v[120:121], v[132:133], v[120:121]
	v_and_b32_e32 v167, 0xffff0000, v113
	v_mul_f32_e32 v113, v162, v162
	v_mul_f32_e32 v177, v163, v163
	v_mul_f32_e32 v178, v166, v166
	v_mov_b32_e32 v176, v112
	v_mov_b32_e32 v184, v164
	v_mov_b32_e32 v185, v110
	v_mov_b32_e32 v110, v165
	v_pk_fma_f32 v[164:165], v[164:165], v[164:165], v[174:175]
	v_pk_add_f32 v[120:121], v[134:135], v[120:121]
	v_and_b32_e32 v181, 0xffff0000, v114
	v_lshlrev_b32_e32 v114, 16, v115
	v_and_b32_e32 v115, 0xffff0000, v115
	v_pk_fma_f32 v[168:169], v[166:167], v[166:167], v[178:179] op_sel_hi:[1,1,0]
	v_pk_add_f32 v[170:171], v[112:113], v[176:177]
	v_pk_add_f32 v[140:141], v[164:165], v[164:165] op_sel_hi:[0,1]
	v_pk_add_f32 v[120:121], v[120:121], v[120:121] op_sel_hi:[0,1]
	v_mul_f32_e32 v180, v112, v112
	v_mov_b32_e32 v113, v181
	v_mul_f32_e32 v168, v181, v181
	v_mov_b32_e32 v181, v171
	v_mul_f32_e32 v140, v114, v114
	v_mul_f32_e32 v120, v115, v115
	v_pk_add_f32 v[138:139], v[180:181], v[168:169]
	v_pk_add_f32 v[120:121], v[140:141], v[120:121]
	v_mov_b32_e32 v107, v179
	v_pk_add_f32 v[120:121], v[138:139], v[120:121]
	s_nop 0
	v_add_f32_e32 v120, v120, v121
	ds_bpermute_b32 v121, v92, v120
	s_waitcnt lgkmcnt(0)
	v_add_f32_e32 v120, v120, v121
	ds_bpermute_b32 v121, v93, v120
	s_waitcnt lgkmcnt(0)
	v_add_f32_e32 v120, v120, v121
	ds_bpermute_b32 v121, v94, v120
	s_waitcnt lgkmcnt(0)
	v_add_f32_e32 v120, v120, v121
	ds_bpermute_b32 v121, v95, v120
	s_waitcnt lgkmcnt(0)
	v_add_f32_e32 v120, v120, v121
	ds_bpermute_b32 v121, v96, v120
	s_waitcnt lgkmcnt(0)
	v_add_f32_e32 v120, v120, v121
	ds_bpermute_b32 v121, v97, v120
	s_waitcnt lgkmcnt(0)
	v_add_f32_e32 v120, v120, v121
	v_fmamk_f32 v120, v120, 0x39800000, v98
	v_mul_f32_e32 v121, 0x4f800000, v120
	v_cmp_gt_f32_e32 vcc, s9, v120
	s_nop 1
	v_cndmask_b32_e32 v120, v120, v121, vcc
	v_sqrt_f32_e32 v121, v120
	s_nop 0
	v_add_u32_e32 v124, -1, v121
	v_add_u32_e32 v125, 1, v121
	v_fma_f32 v128, -v124, v121, v120
	v_fma_f32 v129, -v125, v121, v120
	v_cmp_ge_f32_e64 s[0:1], 0, v128
	s_nop 1
	v_cndmask_b32_e64 v121, v121, v124, s[0:1]
	v_cmp_lt_f32_e64 s[0:1], 0, v129
	s_nop 1
	v_cndmask_b32_e64 v121, v121, v125, s[0:1]
	v_mul_f32_e32 v124, 0x37800000, v121
	v_cndmask_b32_e32 v121, v121, v124, vcc
	v_cmp_class_f32_e32 vcc, v120, v99
	s_nop 1
	v_cndmask_b32_e32 v120, v121, v120, vcc
	v_div_scale_f32 v121, s[0:1], v120, v120, 1.0
	v_rcp_f32_e32 v125, v121
	v_div_scale_f32 v124, vcc, 1.0, v120, 1.0
	v_fma_f32 v128, -v121, v125, 1.0
	v_fmac_f32_e32 v125, v128, v125
	v_mul_f32_e32 v128, v124, v125
	v_fma_f32 v129, -v121, v128, v124
	v_fmac_f32_e32 v128, v129, v125
	v_fma_f32 v121, -v121, v128, v124
	v_div_fmas_f32 v121, v121, v125, v128
	v_div_fixup_f32 v120, v121, v120, 1.0
	v_pk_mul_f32 v[118:119], v[120:121], v[118:119] op_sel_hi:[0,1]
	v_pk_mul_f32 v[76:77], v[120:121], v[76:77] op_sel_hi:[0,1]
	v_pk_mul_f32 v[124:125], v[120:121], v[152:153] op_sel_hi:[0,1]
	v_pk_mul_f32 v[78:79], v[120:121], v[78:79] op_sel_hi:[0,1]
	v_pk_mul_f32 v[122:123], v[120:121], v[122:123] op_sel_hi:[0,1]
	v_pk_mul_f32 v[72:73], v[120:121], v[72:73] op_sel_hi:[0,1]
	v_pk_mul_f32 v[84:85], v[120:121], v[84:85] op_sel_hi:[0,1]
	v_pk_mul_f32 v[128:129], v[120:121], v[74:75] op_sel_hi:[0,1]
	v_pk_mul_f32 v[130:131], v[120:121], v[154:155] op_sel_hi:[0,1]
	v_pk_mul_f32 v[132:133], v[120:121], v[68:69] op_sel_hi:[0,1]
	v_pk_mul_f32 v[116:117], v[120:121], v[116:117] op_sel_hi:[0,1]
	v_pk_mul_f32 v[126:127], v[120:121], v[126:127] op_sel_hi:[0,1]
	v_pk_mul_f32 v[134:135], v[120:121], v[70:71] op_sel_hi:[0,1]
	v_pk_mul_f32 v[136:137], v[120:121], v[64:65] op_sel_hi:[0,1]
	v_pk_mul_f32 v[138:139], v[120:121], v[156:157] op_sel_hi:[0,1]
	v_pk_mul_f32 v[140:141], v[120:121], v[66:67] op_sel_hi:[0,1]
; __device__ __forceinline__ void unpack8(const u32x4 w, f32x4& a, f32x4& b) { a = (f32x4){bflo(w.x), bfhi(w.x), bflo(w.y), bfhi(w.y)}; b = (f32x4){bflo(w.z), bfhi(w.z), bflo(w.w), bfhi(w.w)}; }
; __device__ __forceinline__ void load_xrow(Frame& F, int m, f32x4 (&v)[16]) {
;     const v4u* xr = (const v4u*)((const bf16*)(F.ws + WS_XRES) + (size_t)m * D) + F.lane;
;     v4u w[8];
; #pragma unroll
;     for (int j = 0; j < 8; ++j) w[j] = xr[64 * j];
; #pragma unroll
;     for (int j = 0; j < 8; ++j) pg8::unpack8(w[j], v[2 * j], v[2 * j + 1]);
; __device__ __forceinline__ void final_norm_phase(Frame& F, const Args& A, int nsplit, float scale) {
;     ...
;     for (int m = F.gw; m < NPROMPT; m += F.ngw) {
;         f32x4 v[16]; load_xrow(F, m, v);
;         const float r = row_rnorm(v);
; #pragma unroll
;         for (int j = 0; j < 8; ++j) { f32x4* o = (f32x4*)(F.out + (size_t)m * D + 8 * (64 * j + F.lane)); o[0] = v[2 * j] * r * gn[2 * j]; o[1] = v[2 * j + 1] * r * gn[2 * j + 1]; }
	v_pk_mul_f32 v[142:143], v[120:121], v[158:159] op_sel_hi:[0,1]
	v_pk_mul_f32 v[144:145], v[120:121], v[144:145] op_sel_hi:[0,1]
	v_pk_mul_f32 v[146:147], v[120:121], v[100:101] op_sel_hi:[0,1]
	v_pk_mul_f32 v[148:149], v[120:121], v[102:103] op_sel_hi:[0,1]
	v_pk_mul_f32 v[152:153], v[120:121], v[182:183] op_sel_hi:[0,1]
	v_pk_mul_f32 v[154:155], v[120:121], v[104:105] op_sel_hi:[0,1]
	v_pk_mul_f32 v[156:157], v[120:121], v[160:161] op_sel_hi:[0,1]
	v_pk_mul_f32 v[150:151], v[120:121], v[150:151] op_sel_hi:[0,1]
	v_pk_mul_f32 v[158:159], v[120:121], v[106:107] op_sel_hi:[0,1]
	v_pk_mul_f32 v[160:161], v[120:121], v[108:109] op_sel_hi:[0,1]
	v_pk_mul_f32 v[164:165], v[120:121], v[184:185] op_sel_hi:[0,1]
	v_pk_mul_f32 v[168:169], v[120:121], v[110:111] op_sel_hi:[0,1]
	v_pk_mul_f32 v[162:163], v[120:121], v[162:163] op_sel_hi:[0,1]
	v_pk_mul_f32 v[166:167], v[120:121], v[166:167] op_sel_hi:[0,1]
	v_pk_mul_f32 v[170:171], v[120:121], v[112:113] op_sel_hi:[0,1]
	v_pk_mul_f32 v[172:173], v[120:121], v[114:115] op_sel_hi:[0,1]
	v_pk_mul_f32 v[66:67], v[6:7], v[76:77]
	v_pk_mul_f32 v[64:65], v[4:5], v[118:119]
	v_pk_mul_f32 v[70:71], v[2:3], v[78:79]
	v_pk_mul_f32 v[68:69], v[0:1], v[124:125]
	v_pk_mul_f32 v[74:75], v[14:15], v[72:73]
	v_pk_mul_f32 v[72:73], v[12:13], v[122:123]
	v_pk_mul_f32 v[78:79], v[10:11], v[128:129]
	v_pk_mul_f32 v[76:77], v[8:9], v[84:85]
	v_pk_mul_f32 v[102:103], v[22:23], v[132:133]
	v_pk_mul_f32 v[100:101], v[20:21], v[130:131]
	v_pk_mul_f32 v[106:107], v[18:19], v[126:127]
	v_pk_mul_f32 v[104:105], v[16:17], v[116:117]
	v_pk_mul_f32 v[110:111], v[30:31], v[136:137]
	v_pk_mul_f32 v[108:109], v[28:29], v[134:135]
	v_pk_mul_f32 v[114:115], v[26:27], v[140:141]
	v_pk_mul_f32 v[112:113], v[24:25], v[138:139]
	v_pk_mul_f32 v[118:119], v[38:39], v[144:145]
	v_pk_mul_f32 v[116:117], v[36:37], v[142:143]
	v_pk_mul_f32 v[122:123], v[34:35], v[148:149]
	v_pk_mul_f32 v[120:121], v[32:33], v[146:147]
	v_pk_mul_f32 v[126:127], v[46:47], v[154:155]
	v_pk_mul_f32 v[124:125], v[44:45], v[152:153]
	v_pk_mul_f32 v[130:131], v[42:43], v[150:151]
	v_pk_mul_f32 v[128:129], v[40:41], v[156:157]
	v_pk_mul_f32 v[134:135], v[54:55], v[160:161]
	v_pk_mul_f32 v[132:133], v[52:53], v[158:159]
	v_pk_mul_f32 v[138:139], v[50:51], v[168:169]
	v_pk_mul_f32 v[136:137], v[48:49], v[164:165]
	v_pk_mul_f32 v[142:143], v[62:63], v[166:167]
	v_pk_mul_f32 v[140:141], v[60:61], v[162:163]
	v_pk_mul_f32 v[146:147], v[58:59], v[172:173]
	v_pk_mul_f32 v[144:145], v[56:57], v[170:171]
	global_store_dwordx4 v[82:83], v[64:67], off
	global_store_dwordx4 v[82:83], v[68:71], off offset:16
	global_store_dwordx4 v[82:83], v[72:75], off offset:2048
	global_store_dwordx4 v[82:83], v[76:79], off offset:2064
	global_store_dwordx4 v[88:89], v[100:103], off offset:-4096
	global_store_dwordx4 v[86:87], v[104:107], off offset:16
	global_store_dwordx4 v[86:87], v[108:111], off offset:2048
	global_store_dwordx4 v[86:87], v[112:115], off offset:2064
	global_store_dwordx4 v[88:89], v[116:119], off
	global_store_dwordx4 v[88:89], v[120:123], off offset:16
	global_store_dwordx4 v[88:89], v[124:127], off offset:2048
	global_store_dwordx4 v[88:89], v[128:131], off offset:2064
	global_store_dwordx4 v[90:91], v[132:135], off
	global_store_dwordx4 v[90:91], v[136:139], off offset:16
	global_store_dwordx4 v[90:91], v[140:143], off offset:2048
	global_store_dwordx4 v[90:91], v[144:147], off offset:2064
	v_lshl_add_u64 v[82:83], v[82:83], 0, s[4:5]
	s_add_u32 s98, s98, s2
	s_addc_u32 s99, s99, s3
	s_add_u32 s100, s98, 0x1000
	s_addc_u32 s101, s99, 0
	global_load_dwordx4 v[72:75], v199, s[98:99] offset:1024
	global_load_dwordx4 v[68:71], v199, s[98:99] offset:2048
	global_load_dwordx4 v[64:67], v199, s[98:99] offset:3072
	global_load_dwordx4 v[76:79], v199, s[98:99]
	global_load_dwordx4 v[100:103], v199, s[100:101]
	global_load_dwordx4 v[104:107], v199, s[100:101] offset:1024
	global_load_dwordx4 v[108:111], v199, s[100:101] offset:2048
	global_load_dwordx4 v[112:115], v199, s[100:101] offset:3072
	v_add_co_u32_e32 v84, vcc, s6, v80
	v_add_co_u32_e64 v86, s[0:1], s6, v82
	s_nop 0
	v_addc_co_u32_e32 v85, vcc, 0, v81, vcc
	v_addc_co_u32_e64 v87, s[0:1], 0, v83, s[0:1]
	v_add_co_u32_e64 v88, s[0:1], s7, v82
	s_add_i32 s88, s88, s90
	s_nop 0
	v_addc_co_u32_e64 v89, s[0:1], 0, v83, s[0:1]
	v_add_co_u32_e64 v90, s[0:1], s8, v82
	v_lshl_add_u64 v[80:81], v[80:81], 0, s[2:3]
	s_nop 0
	v_addc_co_u32_e64 v91, s[0:1], 0, v83, s[0:1]
	s_cmpk_lt_i32 s88, 0x2000
	s_waitcnt vmcnt(31)
	v_lshlrev_b32_e32 v122, 16, v200
	v_and_b32_e32 v123, 0xffff0000, v200
	v_lshlrev_b32_e32 v200, 16, v201
	s_waitcnt vmcnt(28)
; __device__ __forceinline__ void unpack8(const u32x4 w, f32x4& a, f32x4& b) { a = (f32x4){bflo(w.x), bfhi(w.x), bflo(w.y), bfhi(w.y)}; b = (f32x4){bflo(w.z), bfhi(w.z), bflo(w.w), bfhi(w.w)}; }
; __device__ __forceinline__ void load_xrow(Frame& F, int m, f32x4 (&v)[16]) {
;     const v4u* xr = (const v4u*)((const bf16*)(F.ws + WS_XRES) + (size_t)m * D) + F.lane;
;     v4u w[8];
; #pragma unroll
;     for (int j = 0; j < 8; ++j) w[j] = xr[64 * j];
; #pragma unroll
;     for (int j = 0; j < 8; ++j) pg8::unpack8(w[j], v[2 * j], v[2 * j + 1]);
; }
; __device__ __forceinline__ float row_rnorm(const f32x4 (&v)[16]) {
;     float s = 0.f;
; #pragma unroll
;     for (int j = 0; j < 16; ++j) s += (v[j].x * v[j].x + v[j].y * v[j].y) + (v[j].z * v[j].z + v[j].w * v[j].w);
;     return 1.0f / sqrtf(wave_sum(s) * (1.0f / D) + EPS);
	v_lshlrev_b32_e32 v118, 16, v212
	v_and_b32_e32 v119, 0xffff0000, v212
	v_lshlrev_b32_e32 v212, 16, v213
	v_lshlrev_b32_e32 v121, 16, v215
	v_lshlrev_b32_e32 v120, 16, v214
	v_and_b32_e32 v215, 0xffff0000, v215
	v_and_b32_e32 v214, 0xffff0000, v214
	v_and_b32_e32 v213, 0xffff0000, v213
	v_lshlrev_b32_e32 v126, 16, v207
	v_mul_f32_e32 v130, v118, v118
	v_mul_f32_e32 v132, v212, v212
	v_pk_mul_f32 v[134:135], v[214:215], v[214:215]
	v_lshlrev_b32_e32 v116, 16, v206
	v_and_b32_e32 v117, 0xffff0000, v206
	v_lshlrev_b32_e32 v206, 16, v208
	v_and_b32_e32 v201, 0xffff0000, v201
	v_lshlrev_b32_e32 v125, 16, v205
	v_lshlrev_b32_e32 v124, 16, v204
	v_and_b32_e32 v205, 0xffff0000, v205
	v_and_b32_e32 v204, 0xffff0000, v204
	v_and_b32_e32 v127, 0xffff0000, v207
	v_mul_f32_e32 v136, v122, v122
	v_mul_f32_e32 v138, v200, v200
	v_mul_f32_e32 v146, v126, v126
	v_mov_b32_e32 v152, v120
	v_mov_b32_e32 v153, v214
	v_mov_b32_e32 v214, v121
	v_pk_fma_f32 v[130:131], v[118:119], v[118:119], v[130:131] op_sel_hi:[1,1,0]
	v_pk_fma_f32 v[132:133], v[212:213], v[212:213], v[132:133] op_sel_hi:[1,1,0]
	v_pk_fma_f32 v[120:121], v[120:121], v[120:121], v[134:135]
	v_lshlrev_b32_e32 v84, 16, v202
	v_and_b32_e32 v85, 0xffff0000, v202
	v_lshlrev_b32_e32 v202, 16, v203
	v_and_b32_e32 v203, 0xffff0000, v203
	v_and_b32_e32 v141, 0xffff0000, v208
	v_pk_mul_f32 v[142:143], v[204:205], v[204:205]
	v_mul_f32_e32 v207, v116, v116
	v_mul_f32_e32 v145, v117, v117
	v_mov_b32_e32 v144, v206
	v_pk_fma_f32 v[134:135], v[122:123], v[122:123], v[136:137] op_sel_hi:[1,1,0]
	v_pk_fma_f32 v[136:137], v[200:201], v[200:201], v[138:139] op_sel_hi:[1,1,0]
	v_pk_fma_f32 v[138:139], v[126:127], v[126:127], v[146:147] op_sel_hi:[1,1,0]
	v_pk_add_f32 v[120:121], v[120:121], v[120:121] op_sel_hi:[0,1]
	v_pk_add_f32 v[130:131], v[130:131], v[132:133]
	v_mul_f32_e32 v140, v84, v84
	v_mov_b32_e32 v154, v124
	v_mov_b32_e32 v155, v204
	v_mov_b32_e32 v204, v125
	v_pk_fma_f32 v[124:125], v[124:125], v[124:125], v[142:143]
	v_pk_add_f32 v[142:143], v[206:207], v[144:145]
	v_mov_b32_e32 v207, v141
	v_mul_f32_e32 v134, v202, v202
	v_mul_f32_e32 v136, v203, v203
	v_mul_f32_e32 v138, v141, v141
	v_mul_f32_e32 v120, v85, v85
	v_mov_b32_e32 v141, v131
	v_pk_add_f32 v[134:135], v[134:135], v[136:137]
	v_pk_add_f32 v[120:121], v[140:141], v[120:121]
	v_lshlrev_b32_e32 v129, 16, v211
	v_lshlrev_b32_e32 v128, 16, v210
	v_and_b32_e32 v211, 0xffff0000, v211
	v_and_b32_e32 v210, 0xffff0000, v210
	v_pk_add_f32 v[120:121], v[120:121], v[134:135]
	v_lshlrev_b32_e32 v208, 16, v209
	v_and_b32_e32 v209, 0xffff0000, v209
	v_pk_mul_f32 v[150:151], v[210:211], v[210:211]
	v_pk_add_f32 v[124:125], v[124:125], v[124:125] op_sel_hi:[0,1]
	v_pk_add_f32 v[120:121], v[120:121], v[120:121] op_sel_hi:[0,1]
	v_mul_f32_e32 v148, v206, v206
	v_mov_b32_e32 v156, v128
	v_mov_b32_e32 v157, v210
	v_mov_b32_e32 v210, v129
	v_pk_fma_f32 v[128:129], v[128:129], v[128:129], v[150:151]
	v_mov_b32_e32 v149, v143
	v_mul_f32_e32 v124, v208, v208
	v_mul_f32_e32 v120, v209, v209
	s_waitcnt vmcnt(27)
	v_lshlrev_b32_e32 v158, 16, v216
	v_and_b32_e32 v159, 0xffff0000, v216
	v_lshlrev_b32_e32 v216, 16, v218
	v_lshlrev_b32_e32 v144, 16, v217
	v_pk_add_f32 v[128:129], v[128:129], v[128:129] op_sel_hi:[0,1]
	v_pk_add_f32 v[136:137], v[148:149], v[138:139]
	v_pk_add_f32 v[120:121], v[124:125], v[120:121]
	v_and_b32_e32 v145, 0xffff0000, v217
	v_mul_f32_e32 v217, v158, v158
	v_mul_f32_e32 v133, v159, v159
	v_mul_f32_e32 v128, v144, v144
	v_mov_b32_e32 v132, v216
	v_pk_add_f32 v[120:121], v[136:137], v[120:121]
	v_and_b32_e32 v173, 0xffff0000, v218
	v_lshlrev_b32_e32 v218, 16, v219
	v_and_b32_e32 v219, 0xffff0000, v219
	v_pk_fma_f32 v[138:139], v[144:145], v[144:145], v[128:129] op_sel_hi:[1,1,0]
	v_pk_add_f32 v[132:133], v[216:217], v[132:133]
	v_pk_add_f32 v[120:121], v[120:121], v[120:121] op_sel_hi:[0,1]
	s_waitcnt vmcnt(26)
	v_lshlrev_b32_e32 v147, 16, v221
	v_lshlrev_b32_e32 v146, 16, v220
	v_and_b32_e32 v221, 0xffff0000, v221
	v_and_b32_e32 v220, 0xffff0000, v220
	v_mul_f32_e32 v130, v216, v216
	v_mul_f32_e32 v128, v218, v218
	v_mul_f32_e32 v138, v173, v173
	v_mov_b32_e32 v131, v133
	v_mul_f32_e32 v120, v219, v219
	v_lshlrev_b32_e32 v160, 16, v222
	v_and_b32_e32 v161, 0xffff0000, v222
	s_waitcnt vmcnt(25)
	v_lshlrev_b32_e32 v222, 16, v224
	v_lshlrev_b32_e32 v150, 16, v223
	v_pk_mul_f32 v[142:143], v[220:221], v[220:221]
	v_pk_add_f32 v[130:131], v[130:131], v[138:139]
	v_pk_add_f32 v[120:121], v[128:129], v[120:121]
	v_and_b32_e32 v151, 0xffff0000, v223
	v_mul_f32_e32 v223, v160, v160
	v_mul_f32_e32 v169, v161, v161
	v_mul_f32_e32 v170, v150, v150
	v_mov_b32_e32 v168, v222
	v_pk_fma_f32 v[142:143], v[146:147], v[146:147], v[142:143]
	v_pk_add_f32 v[120:121], v[130:131], v[120:121]
	v_and_b32_e32 v179, 0xffff0000, v224
	v_lshlrev_b32_e32 v224, 16, v225
	v_and_b32_e32 v225, 0xffff0000, v225
	v_mov_b32_e32 v182, v146
	v_mov_b32_e32 v183, v220
	v_mov_b32_e32 v220, v147
	v_pk_fma_f32 v[146:147], v[150:151], v[150:151], v[170:171] op_sel_hi:[1,1,0]
	v_pk_add_f32 v[148:149], v[222:223], v[168:169]
	v_pk_add_f32 v[132:133], v[142:143], v[142:143] op_sel_hi:[0,1]
	v_pk_add_f32 v[120:121], v[120:121], v[120:121] op_sel_hi:[0,1]
	v_lshlrev_b32_e32 v165, 16, v227
	v_lshlrev_b32_e32 v164, 16, v226
	v_and_b32_e32 v227, 0xffff0000, v227
	v_and_b32_e32 v226, 0xffff0000, v226
	v_mul_f32_e32 v172, v222, v222
	v_mov_b32_e32 v217, v173
	v_mul_f32_e32 v146, v179, v179
	v_mov_b32_e32 v173, v149
	v_mul_f32_e32 v132, v224, v224
	v_mul_f32_e32 v120, v225, v225
	s_waitcnt vmcnt(24)
; __device__ __forceinline__ u32x4 pack8(const f32x4 a, const f32x4 b) { u32x4 w; w.x = cvt_pk_bf16(a[0], a[1]); w.y = cvt_pk_bf16(a[2], a[3]); w.z = cvt_pk_bf16(b[0], b[1]); w.w = cvt_pk_bf16(b[2], b[3]); return w; }
; __device__ __forceinline__ float row_rnorm(const f32x4 (&v)[16]) {
;     float s = 0.f;
; #pragma unroll
;     for (int j = 0; j < 16; ++j) s += (v[j].x * v[j].x + v[j].y * v[j].y) + (v[j].z * v[j].z + v[j].w * v[j].w);
;     return 1.0f / sqrtf(wave_sum(s) * (1.0f / D) + EPS);
; }
; __device__ __forceinline__ void norm_phase(Frame& F, const float* gain, int nsplit, float scale, const float* samp_base) {
;     (void)nsplit;
;     norm_sample_row<false>(F, gain, scale, samp_base, nullptr);
;     f32x4 gn[16]; load_gain8(gain, F.lane, gn);
;     for (int m = F.gw; m < NPROMPT; m += F.ngw) {
;         f32x4 v[16]; load_xrow(F, m, v);
;         const float r = row_rnorm(v);
;         v4u* o8 = (v4u*)((bf16*)(F.ws + WS_H) + (size_t)m * D) + F.lane;
; #pragma unroll
;         for (int j = 0; j < 8; ++j) o8[64 * j] = pg8::pack8(v[2 * j] * r * gn[2 * j], v[2 * j + 1] * r * gn[2 * j + 1]);
;     }
; }
; __device__ __forceinline__ void final_norm_phase(Frame& F, const Args& A, int nsplit, float scale) {
;     (void)nsplit;
;     norm_sample_row<true>(F, A.in[28], scale, nullptr, F.out);
;     f32x4 gn[16]; load_gain8(A.in[28], F.lane, gn);
;     for (int m = F.gw; m < NPROMPT; m += F.ngw) {
;         f32x4 v[16]; load_xrow(F, m, v);
;         const float r = row_rnorm(v);
; #pragma unroll
;         for (int j = 0; j < 8; ++j) { f32x4* o = (f32x4*)(F.out + (size_t)m * D + 8 * (64 * j + F.lane)); o[0] = v[2 * j] * r * gn[2 * j]; o[1] = v[2 * j + 1] * r * gn[2 * j + 1]; }
	v_lshlrev_b32_e32 v162, 16, v228
	v_and_b32_e32 v163, 0xffff0000, v228
	v_lshlrev_b32_e32 v228, 16, v230
	v_lshlrev_b32_e32 v166, 16, v229
	v_pk_mul_f32 v[174:175], v[226:227], v[226:227]
	v_pk_add_f32 v[134:135], v[172:173], v[146:147]
	v_pk_add_f32 v[120:121], v[132:133], v[120:121]
	v_and_b32_e32 v167, 0xffff0000, v229
	v_mul_f32_e32 v229, v162, v162
	v_mul_f32_e32 v177, v163, v163
	v_mul_f32_e32 v178, v166, v166
	v_mov_b32_e32 v176, v228
	v_mov_b32_e32 v184, v164
	v_mov_b32_e32 v185, v226
	v_mov_b32_e32 v226, v165
	v_pk_fma_f32 v[164:165], v[164:165], v[164:165], v[174:175]
	v_pk_add_f32 v[120:121], v[134:135], v[120:121]
	v_and_b32_e32 v181, 0xffff0000, v230
	v_lshlrev_b32_e32 v230, 16, v231
	v_and_b32_e32 v231, 0xffff0000, v231
	v_pk_fma_f32 v[168:169], v[166:167], v[166:167], v[178:179] op_sel_hi:[1,1,0]
	v_pk_add_f32 v[170:171], v[228:229], v[176:177]
	v_pk_add_f32 v[140:141], v[164:165], v[164:165] op_sel_hi:[0,1]
	v_pk_add_f32 v[120:121], v[120:121], v[120:121] op_sel_hi:[0,1]
	v_mul_f32_e32 v180, v228, v228
	v_mov_b32_e32 v229, v181
	v_mul_f32_e32 v168, v181, v181
	v_mov_b32_e32 v181, v171
	v_mul_f32_e32 v140, v230, v230
	v_mul_f32_e32 v120, v231, v231
	v_pk_add_f32 v[138:139], v[180:181], v[168:169]
	v_pk_add_f32 v[120:121], v[140:141], v[120:121]
	v_mov_b32_e32 v223, v179
	v_pk_add_f32 v[120:121], v[138:139], v[120:121]
	s_nop 0
	v_add_f32_e32 v120, v120, v121
	ds_bpermute_b32 v121, v92, v120
	s_waitcnt lgkmcnt(0)
	v_add_f32_e32 v120, v120, v121
	ds_bpermute_b32 v121, v93, v120
	s_waitcnt lgkmcnt(0)
	v_add_f32_e32 v120, v120, v121
	ds_bpermute_b32 v121, v94, v120
	s_waitcnt lgkmcnt(0)
	v_add_f32_e32 v120, v120, v121
	ds_bpermute_b32 v121, v95, v120
	s_waitcnt lgkmcnt(0)
	v_add_f32_e32 v120, v120, v121
	ds_bpermute_b32 v121, v96, v120
	s_waitcnt lgkmcnt(0)
	v_add_f32_e32 v120, v120, v121
	ds_bpermute_b32 v121, v97, v120
	s_waitcnt lgkmcnt(0)
	v_add_f32_e32 v120, v120, v121
	v_fmamk_f32 v120, v120, 0x39800000, v98
	v_mul_f32_e32 v121, 0x4f800000, v120
	v_cmp_gt_f32_e32 vcc, s9, v120
	s_nop 1
	v_cndmask_b32_e32 v120, v120, v121, vcc
	v_sqrt_f32_e32 v121, v120
	s_nop 0
	v_add_u32_e32 v124, -1, v121
	v_add_u32_e32 v125, 1, v121
	v_fma_f32 v128, -v124, v121, v120
	v_fma_f32 v129, -v125, v121, v120
	v_cmp_ge_f32_e64 s[0:1], 0, v128
	s_nop 1
	v_cndmask_b32_e64 v121, v121, v124, s[0:1]
	v_cmp_lt_f32_e64 s[0:1], 0, v129
	s_nop 1
	v_cndmask_b32_e64 v121, v121, v125, s[0:1]
	v_mul_f32_e32 v124, 0x37800000, v121
	v_cndmask_b32_e32 v121, v121, v124, vcc
	v_cmp_class_f32_e32 vcc, v120, v99
	s_nop 1
	v_cndmask_b32_e32 v120, v121, v120, vcc
	v_div_scale_f32 v121, s[0:1], v120, v120, 1.0
	v_rcp_f32_e32 v125, v121
	v_div_scale_f32 v124, vcc, 1.0, v120, 1.0
	v_fma_f32 v128, -v121, v125, 1.0
	v_fmac_f32_e32 v125, v128, v125
	v_mul_f32_e32 v128, v124, v125
	v_fma_f32 v129, -v121, v128, v124
	v_fmac_f32_e32 v128, v129, v125
	v_fma_f32 v121, -v121, v128, v124
	v_div_fmas_f32 v121, v121, v125, v128
	v_div_fixup_f32 v120, v121, v120, 1.0
	v_pk_mul_f32 v[118:119], v[120:121], v[118:119] op_sel_hi:[0,1]
	v_pk_mul_f32 v[212:213], v[120:121], v[212:213] op_sel_hi:[0,1]
	v_pk_mul_f32 v[124:125], v[120:121], v[152:153] op_sel_hi:[0,1]
	v_pk_mul_f32 v[214:215], v[120:121], v[214:215] op_sel_hi:[0,1]
	v_pk_mul_f32 v[122:123], v[120:121], v[122:123] op_sel_hi:[0,1]
	v_pk_mul_f32 v[200:201], v[120:121], v[200:201] op_sel_hi:[0,1]
	v_pk_mul_f32 v[84:85], v[120:121], v[84:85] op_sel_hi:[0,1]
	v_pk_mul_f32 v[128:129], v[120:121], v[202:203] op_sel_hi:[0,1]
	v_pk_mul_f32 v[130:131], v[120:121], v[154:155] op_sel_hi:[0,1]
	v_pk_mul_f32 v[132:133], v[120:121], v[204:205] op_sel_hi:[0,1]
	v_pk_mul_f32 v[116:117], v[120:121], v[116:117] op_sel_hi:[0,1]
	v_pk_mul_f32 v[126:127], v[120:121], v[126:127] op_sel_hi:[0,1]
	v_pk_mul_f32 v[134:135], v[120:121], v[206:207] op_sel_hi:[0,1]
	v_pk_mul_f32 v[136:137], v[120:121], v[208:209] op_sel_hi:[0,1]
	v_pk_mul_f32 v[138:139], v[120:121], v[156:157] op_sel_hi:[0,1]
	v_pk_mul_f32 v[140:141], v[120:121], v[210:211] op_sel_hi:[0,1]
	v_pk_mul_f32 v[142:143], v[120:121], v[158:159] op_sel_hi:[0,1]
	v_pk_mul_f32 v[144:145], v[120:121], v[144:145] op_sel_hi:[0,1]
	v_pk_mul_f32 v[146:147], v[120:121], v[216:217] op_sel_hi:[0,1]
	v_pk_mul_f32 v[148:149], v[120:121], v[218:219] op_sel_hi:[0,1]
	v_pk_mul_f32 v[152:153], v[120:121], v[182:183] op_sel_hi:[0,1]
	v_pk_mul_f32 v[154:155], v[120:121], v[220:221] op_sel_hi:[0,1]
	v_pk_mul_f32 v[156:157], v[120:121], v[160:161] op_sel_hi:[0,1]
	v_pk_mul_f32 v[150:151], v[120:121], v[150:151] op_sel_hi:[0,1]
	v_pk_mul_f32 v[158:159], v[120:121], v[222:223] op_sel_hi:[0,1]
	v_pk_mul_f32 v[160:161], v[120:121], v[224:225] op_sel_hi:[0,1]
	v_pk_mul_f32 v[164:165], v[120:121], v[184:185] op_sel_hi:[0,1]
	v_pk_mul_f32 v[168:169], v[120:121], v[226:227] op_sel_hi:[0,1]
	v_pk_mul_f32 v[162:163], v[120:121], v[162:163] op_sel_hi:[0,1]
	v_pk_mul_f32 v[166:167], v[120:121], v[166:167] op_sel_hi:[0,1]
	v_pk_mul_f32 v[170:171], v[120:121], v[228:229] op_sel_hi:[0,1]
	v_pk_mul_f32 v[172:173], v[120:121], v[230:231] op_sel_hi:[0,1]
	v_pk_mul_f32 v[210:211], v[6:7], v[212:213]
	v_pk_mul_f32 v[208:209], v[4:5], v[118:119]
	v_pk_mul_f32 v[206:207], v[2:3], v[214:215]
	v_pk_mul_f32 v[204:205], v[0:1], v[124:125]
	v_pk_mul_f32 v[202:203], v[14:15], v[200:201]
	v_pk_mul_f32 v[200:201], v[12:13], v[122:123]
	v_pk_mul_f32 v[214:215], v[10:11], v[128:129]
	v_pk_mul_f32 v[212:213], v[8:9], v[84:85]
	v_pk_mul_f32 v[218:219], v[22:23], v[132:133]
	v_pk_mul_f32 v[216:217], v[20:21], v[130:131]
	v_pk_mul_f32 v[222:223], v[18:19], v[126:127]
	v_pk_mul_f32 v[220:221], v[16:17], v[116:117]
	v_pk_mul_f32 v[226:227], v[30:31], v[136:137]
; __device__ __forceinline__ void unpack8(const u32x4 w, f32x4& a, f32x4& b) { a = (f32x4){bflo(w.x), bfhi(w.x), bflo(w.y), bfhi(w.y)}; b = (f32x4){bflo(w.z), bfhi(w.z), bflo(w.w), bfhi(w.w)}; }
; __device__ __forceinline__ void load_xrow(Frame& F, int m, f32x4 (&v)[16]) {
;     const v4u* xr = (const v4u*)((const bf16*)(F.ws + WS_XRES) + (size_t)m * D) + F.lane;
;     v4u w[8];
; #pragma unroll
;     for (int j = 0; j < 8; ++j) w[j] = xr[64 * j];
; #pragma unroll
;     for (int j = 0; j < 8; ++j) pg8::unpack8(w[j], v[2 * j], v[2 * j + 1]);
; __device__ __forceinline__ void final_norm_phase(Frame& F, const Args& A, int nsplit, float scale) {
;     ...
;     for (int m = F.gw; m < NPROMPT; m += F.ngw) {
;         f32x4 v[16]; load_xrow(F, m, v);
;         const float r = row_rnorm(v);
; #pragma unroll
;         for (int j = 0; j < 8; ++j) { f32x4* o = (f32x4*)(F.out + (size_t)m * D + 8 * (64 * j + F.lane)); o[0] = v[2 * j] * r * gn[2 * j]; o[1] = v[2 * j + 1] * r * gn[2 * j + 1]; }
	v_pk_mul_f32 v[224:225], v[28:29], v[134:135]
	v_pk_mul_f32 v[230:231], v[26:27], v[140:141]
	v_pk_mul_f32 v[228:229], v[24:25], v[138:139]
	v_pk_mul_f32 v[118:119], v[38:39], v[144:145]
	v_pk_mul_f32 v[116:117], v[36:37], v[142:143]
	v_pk_mul_f32 v[122:123], v[34:35], v[148:149]
	v_pk_mul_f32 v[120:121], v[32:33], v[146:147]
	v_pk_mul_f32 v[126:127], v[46:47], v[154:155]
	v_pk_mul_f32 v[124:125], v[44:45], v[152:153]
	v_pk_mul_f32 v[130:131], v[42:43], v[150:151]
	v_pk_mul_f32 v[128:129], v[40:41], v[156:157]
	v_pk_mul_f32 v[134:135], v[54:55], v[160:161]
	v_pk_mul_f32 v[132:133], v[52:53], v[158:159]
	v_pk_mul_f32 v[138:139], v[50:51], v[168:169]
	v_pk_mul_f32 v[136:137], v[48:49], v[164:165]
	v_pk_mul_f32 v[142:143], v[62:63], v[166:167]
	v_pk_mul_f32 v[140:141], v[60:61], v[162:163]
	v_pk_mul_f32 v[146:147], v[58:59], v[172:173]
	v_pk_mul_f32 v[144:145], v[56:57], v[170:171]
	global_store_dwordx4 v[82:83], v[208:211], off
	global_store_dwordx4 v[82:83], v[204:207], off offset:16
	global_store_dwordx4 v[82:83], v[200:203], off offset:2048
	global_store_dwordx4 v[82:83], v[212:215], off offset:2064
	global_store_dwordx4 v[88:89], v[216:219], off offset:-4096
	global_store_dwordx4 v[86:87], v[220:223], off offset:16
	global_store_dwordx4 v[86:87], v[224:227], off offset:2048
	global_store_dwordx4 v[86:87], v[228:231], off offset:2064
	global_store_dwordx4 v[88:89], v[116:119], off
	global_store_dwordx4 v[88:89], v[120:123], off offset:16
	global_store_dwordx4 v[88:89], v[124:127], off offset:2048
	global_store_dwordx4 v[88:89], v[128:131], off offset:2064
	global_store_dwordx4 v[90:91], v[132:135], off
	global_store_dwordx4 v[90:91], v[136:139], off offset:16
	global_store_dwordx4 v[90:91], v[140:143], off offset:2048
	global_store_dwordx4 v[90:91], v[144:147], off offset:2064
	v_lshl_add_u64 v[82:83], v[82:83], 0, s[4:5]
	s_add_u32 s98, s98, s2
	s_addc_u32 s99, s99, s3
	s_add_u32 s100, s98, 0x1000
	s_addc_u32 s101, s99, 0
	global_load_dwordx4 v[200:203], v199, s[98:99] offset:1024
	global_load_dwordx4 v[204:207], v199, s[98:99] offset:2048
	global_load_dwordx4 v[208:211], v199, s[98:99] offset:3072
	global_load_dwordx4 v[212:215], v199, s[98:99]
	global_load_dwordx4 v[216:219], v199, s[100:101]
	global_load_dwordx4 v[220:223], v199, s[100:101] offset:1024
	global_load_dwordx4 v[224:227], v199, s[100:101] offset:2048
	global_load_dwordx4 v[228:231], v199, s[100:101] offset:3072
	v_add_co_u32_e32 v84, vcc, s6, v80
	v_add_co_u32_e64 v86, s[0:1], s6, v82
	s_nop 0
	v_addc_co_u32_e32 v85, vcc, 0, v81, vcc
	v_addc_co_u32_e64 v87, s[0:1], 0, v83, s[0:1]
	v_add_co_u32_e64 v88, s[0:1], s7, v82
	s_add_i32 s88, s88, s90
	s_nop 0
	v_addc_co_u32_e64 v89, s[0:1], 0, v83, s[0:1]
	v_add_co_u32_e64 v90, s[0:1], s8, v82
	v_lshl_add_u64 v[80:81], v[80:81], 0, s[2:3]
	s_nop 0
	v_addc_co_u32_e64 v91, s[0:1], 0, v83, s[0:1]
	s_cmpk_lt_i32 s88, 0x2000
	s_waitcnt vmcnt(31)
	v_lshlrev_b32_e32 v122, 16, v72
	v_and_b32_e32 v123, 0xffff0000, v72
	v_lshlrev_b32_e32 v72, 16, v73
	s_waitcnt vmcnt(28)
	v_lshlrev_b32_e32 v118, 16, v76
	v_and_b32_e32 v119, 0xffff0000, v76
	v_lshlrev_b32_e32 v76, 16, v77
	v_lshlrev_b32_e32 v121, 16, v79
	v_lshlrev_b32_e32 v120, 16, v78
	v_and_b32_e32 v79, 0xffff0000, v79
	v_and_b32_e32 v78, 0xffff0000, v78
	v_and_b32_e32 v77, 0xffff0000, v77
	v_lshlrev_b32_e32 v126, 16, v71
	v_mul_f32_e32 v130, v118, v118
	v_mul_f32_e32 v132, v76, v76
	v_pk_mul_f32 v[134:135], v[78:79], v[78:79]
	v_lshlrev_b32_e32 v116, 16, v70
	v_and_b32_e32 v117, 0xffff0000, v70
	v_lshlrev_b32_e32 v70, 16, v64
	v_and_b32_e32 v73, 0xffff0000, v73
	v_lshlrev_b32_e32 v125, 16, v69
	v_lshlrev_b32_e32 v124, 16, v68
	v_and_b32_e32 v69, 0xffff0000, v69
	v_and_b32_e32 v68, 0xffff0000, v68
	v_and_b32_e32 v127, 0xffff0000, v71
	v_mul_f32_e32 v136, v122, v122
	v_mul_f32_e32 v138, v72, v72
	v_mul_f32_e32 v146, v126, v126
	v_mov_b32_e32 v152, v120
	v_mov_b32_e32 v153, v78
	v_mov_b32_e32 v78, v121
	v_pk_fma_f32 v[130:131], v[118:119], v[118:119], v[130:131] op_sel_hi:[1,1,0]
	v_pk_fma_f32 v[132:133], v[76:77], v[76:77], v[132:133] op_sel_hi:[1,1,0]
	v_pk_fma_f32 v[120:121], v[120:121], v[120:121], v[134:135]
	v_lshlrev_b32_e32 v84, 16, v74
	v_and_b32_e32 v85, 0xffff0000, v74
	v_lshlrev_b32_e32 v74, 16, v75
	v_and_b32_e32 v75, 0xffff0000, v75
	v_and_b32_e32 v141, 0xffff0000, v64
	v_pk_mul_f32 v[142:143], v[68:69], v[68:69]
	v_mul_f32_e32 v71, v116, v116
	v_mul_f32_e32 v145, v117, v117
	v_mov_b32_e32 v144, v70
	v_pk_fma_f32 v[134:135], v[122:123], v[122:123], v[136:137] op_sel_hi:[1,1,0]
	v_pk_fma_f32 v[136:137], v[72:73], v[72:73], v[138:139] op_sel_hi:[1,1,0]
	v_pk_fma_f32 v[138:139], v[126:127], v[126:127], v[146:147] op_sel_hi:[1,1,0]
	v_pk_add_f32 v[120:121], v[120:121], v[120:121] op_sel_hi:[0,1]
	v_pk_add_f32 v[130:131], v[130:131], v[132:133]
	v_mul_f32_e32 v140, v84, v84
	v_mov_b32_e32 v154, v124
	v_mov_b32_e32 v155, v68
	v_mov_b32_e32 v68, v125
	v_pk_fma_f32 v[124:125], v[124:125], v[124:125], v[142:143]
	v_pk_add_f32 v[142:143], v[70:71], v[144:145]
	v_mov_b32_e32 v71, v141
	v_mul_f32_e32 v134, v74, v74
	v_mul_f32_e32 v136, v75, v75
	v_mul_f32_e32 v138, v141, v141
	v_mul_f32_e32 v120, v85, v85
	v_mov_b32_e32 v141, v131
	v_pk_add_f32 v[134:135], v[134:135], v[136:137]
	v_pk_add_f32 v[120:121], v[140:141], v[120:121]
	v_lshlrev_b32_e32 v129, 16, v67
	v_lshlrev_b32_e32 v128, 16, v66
	v_and_b32_e32 v67, 0xffff0000, v67
	v_and_b32_e32 v66, 0xffff0000, v66
	v_pk_add_f32 v[120:121], v[120:121], v[134:135]
	v_lshlrev_b32_e32 v64, 16, v65
	v_and_b32_e32 v65, 0xffff0000, v65
	v_pk_mul_f32 v[150:151], v[66:67], v[66:67]
	v_pk_add_f32 v[124:125], v[124:125], v[124:125] op_sel_hi:[0,1]
	v_pk_add_f32 v[120:121], v[120:121], v[120:121] op_sel_hi:[0,1]
	v_mul_f32_e32 v148, v70, v70
	v_mov_b32_e32 v156, v128
	v_mov_b32_e32 v157, v66
	v_mov_b32_e32 v66, v129
	v_pk_fma_f32 v[128:129], v[128:129], v[128:129], v[150:151]
	v_mov_b32_e32 v149, v143
	v_mul_f32_e32 v124, v64, v64
	v_mul_f32_e32 v120, v65, v65
	s_waitcnt vmcnt(27)
; __device__ __forceinline__ void unpack8(const u32x4 w, f32x4& a, f32x4& b) { a = (f32x4){bflo(w.x), bfhi(w.x), bflo(w.y), bfhi(w.y)}; b = (f32x4){bflo(w.z), bfhi(w.z), bflo(w.w), bfhi(w.w)}; }
; __device__ __forceinline__ float wave_sum(float v) {
; #pragma unroll
;     for (int o = 1; o < 64; o <<= 1) v += __shfl_xor(v, o);
;     return v;
; }
; __device__ __forceinline__ void load_xrow(Frame& F, int m, f32x4 (&v)[16]) {
;     const v4u* xr = (const v4u*)((const bf16*)(F.ws + WS_XRES) + (size_t)m * D) + F.lane;
;     v4u w[8];
; #pragma unroll
;     for (int j = 0; j < 8; ++j) w[j] = xr[64 * j];
; #pragma unroll
;     for (int j = 0; j < 8; ++j) pg8::unpack8(w[j], v[2 * j], v[2 * j + 1]);
; }
; __device__ __forceinline__ float row_rnorm(const f32x4 (&v)[16]) {
;     float s = 0.f;
; #pragma unroll
;     for (int j = 0; j < 16; ++j) s += (v[j].x * v[j].x + v[j].y * v[j].y) + (v[j].z * v[j].z + v[j].w * v[j].w);
;     return 1.0f / sqrtf(wave_sum(s) * (1.0f / D) + EPS);
	v_lshlrev_b32_e32 v158, 16, v100
	v_and_b32_e32 v159, 0xffff0000, v100
	v_lshlrev_b32_e32 v100, 16, v102
	v_lshlrev_b32_e32 v144, 16, v101
	v_pk_add_f32 v[128:129], v[128:129], v[128:129] op_sel_hi:[0,1]
	v_pk_add_f32 v[136:137], v[148:149], v[138:139]
	v_pk_add_f32 v[120:121], v[124:125], v[120:121]
	v_and_b32_e32 v145, 0xffff0000, v101
	v_mul_f32_e32 v101, v158, v158
	v_mul_f32_e32 v133, v159, v159
	v_mul_f32_e32 v128, v144, v144
	v_mov_b32_e32 v132, v100
	v_pk_add_f32 v[120:121], v[136:137], v[120:121]
	v_and_b32_e32 v173, 0xffff0000, v102
	v_lshlrev_b32_e32 v102, 16, v103
	v_and_b32_e32 v103, 0xffff0000, v103
	v_pk_fma_f32 v[138:139], v[144:145], v[144:145], v[128:129] op_sel_hi:[1,1,0]
	v_pk_add_f32 v[132:133], v[100:101], v[132:133]
	v_pk_add_f32 v[120:121], v[120:121], v[120:121] op_sel_hi:[0,1]
	s_waitcnt vmcnt(26)
	v_lshlrev_b32_e32 v147, 16, v105
	v_lshlrev_b32_e32 v146, 16, v104
	v_and_b32_e32 v105, 0xffff0000, v105
	v_and_b32_e32 v104, 0xffff0000, v104
	v_mul_f32_e32 v130, v100, v100
	v_mul_f32_e32 v128, v102, v102
	v_mul_f32_e32 v138, v173, v173
	v_mov_b32_e32 v131, v133
	v_mul_f32_e32 v120, v103, v103
	v_lshlrev_b32_e32 v160, 16, v106
	v_and_b32_e32 v161, 0xffff0000, v106
	s_waitcnt vmcnt(25)
	v_lshlrev_b32_e32 v106, 16, v108
	v_lshlrev_b32_e32 v150, 16, v107
	v_pk_mul_f32 v[142:143], v[104:105], v[104:105]
	v_pk_add_f32 v[130:131], v[130:131], v[138:139]
	v_pk_add_f32 v[120:121], v[128:129], v[120:121]
	v_and_b32_e32 v151, 0xffff0000, v107
	v_mul_f32_e32 v107, v160, v160
	v_mul_f32_e32 v169, v161, v161
	v_mul_f32_e32 v170, v150, v150
	v_mov_b32_e32 v168, v106
	v_pk_fma_f32 v[142:143], v[146:147], v[146:147], v[142:143]
	v_pk_add_f32 v[120:121], v[130:131], v[120:121]
	v_and_b32_e32 v179, 0xffff0000, v108
	v_lshlrev_b32_e32 v108, 16, v109
	v_and_b32_e32 v109, 0xffff0000, v109
	v_mov_b32_e32 v182, v146
	v_mov_b32_e32 v183, v104
	v_mov_b32_e32 v104, v147
	v_pk_fma_f32 v[146:147], v[150:151], v[150:151], v[170:171] op_sel_hi:[1,1,0]
	v_pk_add_f32 v[148:149], v[106:107], v[168:169]
	v_pk_add_f32 v[132:133], v[142:143], v[142:143] op_sel_hi:[0,1]
	v_pk_add_f32 v[120:121], v[120:121], v[120:121] op_sel_hi:[0,1]
	v_lshlrev_b32_e32 v165, 16, v111
	v_lshlrev_b32_e32 v164, 16, v110
	v_and_b32_e32 v111, 0xffff0000, v111
	v_and_b32_e32 v110, 0xffff0000, v110
	v_mul_f32_e32 v172, v106, v106
	v_mov_b32_e32 v101, v173
	v_mul_f32_e32 v146, v179, v179
	v_mov_b32_e32 v173, v149
	v_mul_f32_e32 v132, v108, v108
	v_mul_f32_e32 v120, v109, v109
	s_waitcnt vmcnt(24)
	v_lshlrev_b32_e32 v162, 16, v112
	v_and_b32_e32 v163, 0xffff0000, v112
	v_lshlrev_b32_e32 v112, 16, v114
	v_lshlrev_b32_e32 v166, 16, v113
	v_pk_mul_f32 v[174:175], v[110:111], v[110:111]
	v_pk_add_f32 v[134:135], v[172:173], v[146:147]
	v_pk_add_f32 v[120:121], v[132:133], v[120:121]
	v_and_b32_e32 v167, 0xffff0000, v113
	v_mul_f32_e32 v113, v162, v162
	v_mul_f32_e32 v177, v163, v163
	v_mul_f32_e32 v178, v166, v166
	v_mov_b32_e32 v176, v112
	v_mov_b32_e32 v184, v164
	v_mov_b32_e32 v185, v110
	v_mov_b32_e32 v110, v165
	v_pk_fma_f32 v[164:165], v[164:165], v[164:165], v[174:175]
	v_pk_add_f32 v[120:121], v[134:135], v[120:121]
	v_and_b32_e32 v181, 0xffff0000, v114
	v_lshlrev_b32_e32 v114, 16, v115
	v_and_b32_e32 v115, 0xffff0000, v115
	v_pk_fma_f32 v[168:169], v[166:167], v[166:167], v[178:179] op_sel_hi:[1,1,0]
	v_pk_add_f32 v[170:171], v[112:113], v[176:177]
	v_pk_add_f32 v[140:141], v[164:165], v[164:165] op_sel_hi:[0,1]
	v_pk_add_f32 v[120:121], v[120:121], v[120:121] op_sel_hi:[0,1]
	v_mul_f32_e32 v180, v112, v112
	v_mov_b32_e32 v113, v181
	v_mul_f32_e32 v168, v181, v181
	v_mov_b32_e32 v181, v171
	v_mul_f32_e32 v140, v114, v114
	v_mul_f32_e32 v120, v115, v115
	v_pk_add_f32 v[138:139], v[180:181], v[168:169]
	v_pk_add_f32 v[120:121], v[140:141], v[120:121]
	v_mov_b32_e32 v107, v179
	v_pk_add_f32 v[120:121], v[138:139], v[120:121]
	s_nop 0
	v_add_f32_e32 v120, v120, v121
	ds_bpermute_b32 v121, v92, v120
	s_waitcnt lgkmcnt(0)
	v_add_f32_e32 v120, v120, v121
	ds_bpermute_b32 v121, v93, v120
	s_waitcnt lgkmcnt(0)
	v_add_f32_e32 v120, v120, v121
	ds_bpermute_b32 v121, v94, v120
	s_waitcnt lgkmcnt(0)
	v_add_f32_e32 v120, v120, v121
	ds_bpermute_b32 v121, v95, v120
	s_waitcnt lgkmcnt(0)
	v_add_f32_e32 v120, v120, v121
	ds_bpermute_b32 v121, v96, v120
	s_waitcnt lgkmcnt(0)
	v_add_f32_e32 v120, v120, v121
	ds_bpermute_b32 v121, v97, v120
	s_waitcnt lgkmcnt(0)
; __device__ __forceinline__ float row_rnorm(const f32x4 (&v)[16]) {
;     float s = 0.f;
; #pragma unroll
;     for (int j = 0; j < 16; ++j) s += (v[j].x * v[j].x + v[j].y * v[j].y) + (v[j].z * v[j].z + v[j].w * v[j].w);
;     return 1.0f / sqrtf(wave_sum(s) * (1.0f / D) + EPS);
; __device__ __forceinline__ void final_norm_phase(Frame& F, const Args& A, int nsplit, float scale) {
;     ...
;     for (int m = F.gw; m < NPROMPT; m += F.ngw) {
;         f32x4 v[16]; load_xrow(F, m, v);
;         const float r = row_rnorm(v);
; #pragma unroll
;         for (int j = 0; j < 8; ++j) { f32x4* o = (f32x4*)(F.out + (size_t)m * D + 8 * (64 * j + F.lane)); o[0] = v[2 * j] * r * gn[2 * j]; o[1] = v[2 * j + 1] * r * gn[2 * j + 1]; }
;     }
	v_add_f32_e32 v120, v120, v121
	v_fmamk_f32 v120, v120, 0x39800000, v98
	v_mul_f32_e32 v121, 0x4f800000, v120
	v_cmp_gt_f32_e32 vcc, s9, v120
	s_nop 1
	v_cndmask_b32_e32 v120, v120, v121, vcc
	v_sqrt_f32_e32 v121, v120
	s_nop 0
	v_add_u32_e32 v124, -1, v121
	v_add_u32_e32 v125, 1, v121
	v_fma_f32 v128, -v124, v121, v120
	v_fma_f32 v129, -v125, v121, v120
	v_cmp_ge_f32_e64 s[0:1], 0, v128
	s_nop 1
	v_cndmask_b32_e64 v121, v121, v124, s[0:1]
	v_cmp_lt_f32_e64 s[0:1], 0, v129
	s_nop 1
	v_cndmask_b32_e64 v121, v121, v125, s[0:1]
	v_mul_f32_e32 v124, 0x37800000, v121
	v_cndmask_b32_e32 v121, v121, v124, vcc
	v_cmp_class_f32_e32 vcc, v120, v99
	s_nop 1
	v_cndmask_b32_e32 v120, v121, v120, vcc
	v_div_scale_f32 v121, s[0:1], v120, v120, 1.0
	v_rcp_f32_e32 v125, v121
	v_div_scale_f32 v124, vcc, 1.0, v120, 1.0
	v_fma_f32 v128, -v121, v125, 1.0
	v_fmac_f32_e32 v125, v128, v125
	v_mul_f32_e32 v128, v124, v125
	v_fma_f32 v129, -v121, v128, v124
	v_fmac_f32_e32 v128, v129, v125
	v_fma_f32 v121, -v121, v128, v124
	v_div_fmas_f32 v121, v121, v125, v128
	v_div_fixup_f32 v120, v121, v120, 1.0
	v_pk_mul_f32 v[118:119], v[120:121], v[118:119] op_sel_hi:[0,1]
	v_pk_mul_f32 v[76:77], v[120:121], v[76:77] op_sel_hi:[0,1]
	v_pk_mul_f32 v[124:125], v[120:121], v[152:153] op_sel_hi:[0,1]
	v_pk_mul_f32 v[78:79], v[120:121], v[78:79] op_sel_hi:[0,1]
	v_pk_mul_f32 v[122:123], v[120:121], v[122:123] op_sel_hi:[0,1]
	v_pk_mul_f32 v[72:73], v[120:121], v[72:73] op_sel_hi:[0,1]
	v_pk_mul_f32 v[84:85], v[120:121], v[84:85] op_sel_hi:[0,1]
	v_pk_mul_f32 v[128:129], v[120:121], v[74:75] op_sel_hi:[0,1]
	v_pk_mul_f32 v[130:131], v[120:121], v[154:155] op_sel_hi:[0,1]
	v_pk_mul_f32 v[132:133], v[120:121], v[68:69] op_sel_hi:[0,1]
	v_pk_mul_f32 v[116:117], v[120:121], v[116:117] op_sel_hi:[0,1]
	v_pk_mul_f32 v[126:127], v[120:121], v[126:127] op_sel_hi:[0,1]
	v_pk_mul_f32 v[134:135], v[120:121], v[70:71] op_sel_hi:[0,1]
	v_pk_mul_f32 v[136:137], v[120:121], v[64:65] op_sel_hi:[0,1]
	v_pk_mul_f32 v[138:139], v[120:121], v[156:157] op_sel_hi:[0,1]
	v_pk_mul_f32 v[140:141], v[120:121], v[66:67] op_sel_hi:[0,1]
	v_pk_mul_f32 v[142:143], v[120:121], v[158:159] op_sel_hi:[0,1]
	v_pk_mul_f32 v[144:145], v[120:121], v[144:145] op_sel_hi:[0,1]
	v_pk_mul_f32 v[146:147], v[120:121], v[100:101] op_sel_hi:[0,1]
	v_pk_mul_f32 v[148:149], v[120:121], v[102:103] op_sel_hi:[0,1]
	v_pk_mul_f32 v[152:153], v[120:121], v[182:183] op_sel_hi:[0,1]
	v_pk_mul_f32 v[154:155], v[120:121], v[104:105] op_sel_hi:[0,1]
	v_pk_mul_f32 v[156:157], v[120:121], v[160:161] op_sel_hi:[0,1]
	v_pk_mul_f32 v[150:151], v[120:121], v[150:151] op_sel_hi:[0,1]
	v_pk_mul_f32 v[158:159], v[120:121], v[106:107] op_sel_hi:[0,1]
	v_pk_mul_f32 v[160:161], v[120:121], v[108:109] op_sel_hi:[0,1]
	v_pk_mul_f32 v[164:165], v[120:121], v[184:185] op_sel_hi:[0,1]
	v_pk_mul_f32 v[168:169], v[120:121], v[110:111] op_sel_hi:[0,1]
	v_pk_mul_f32 v[162:163], v[120:121], v[162:163] op_sel_hi:[0,1]
	v_pk_mul_f32 v[166:167], v[120:121], v[166:167] op_sel_hi:[0,1]
	v_pk_mul_f32 v[170:171], v[120:121], v[112:113] op_sel_hi:[0,1]
	v_pk_mul_f32 v[172:173], v[120:121], v[114:115] op_sel_hi:[0,1]
	v_pk_mul_f32 v[66:67], v[6:7], v[76:77]
	v_pk_mul_f32 v[64:65], v[4:5], v[118:119]
	v_pk_mul_f32 v[70:71], v[2:3], v[78:79]
	v_pk_mul_f32 v[68:69], v[0:1], v[124:125]
	v_pk_mul_f32 v[74:75], v[14:15], v[72:73]
	v_pk_mul_f32 v[72:73], v[12:13], v[122:123]
	v_pk_mul_f32 v[78:79], v[10:11], v[128:129]
	v_pk_mul_f32 v[76:77], v[8:9], v[84:85]
	v_pk_mul_f32 v[102:103], v[22:23], v[132:133]
	v_pk_mul_f32 v[100:101], v[20:21], v[130:131]
	v_pk_mul_f32 v[106:107], v[18:19], v[126:127]
	v_pk_mul_f32 v[104:105], v[16:17], v[116:117]
	v_pk_mul_f32 v[110:111], v[30:31], v[136:137]
	v_pk_mul_f32 v[108:109], v[28:29], v[134:135]
	v_pk_mul_f32 v[114:115], v[26:27], v[140:141]
	v_pk_mul_f32 v[112:113], v[24:25], v[138:139]
	v_pk_mul_f32 v[118:119], v[38:39], v[144:145]
	v_pk_mul_f32 v[116:117], v[36:37], v[142:143]
	v_pk_mul_f32 v[122:123], v[34:35], v[148:149]
	v_pk_mul_f32 v[120:121], v[32:33], v[146:147]
	v_pk_mul_f32 v[126:127], v[46:47], v[154:155]
	v_pk_mul_f32 v[124:125], v[44:45], v[152:153]
	v_pk_mul_f32 v[130:131], v[42:43], v[150:151]
	v_pk_mul_f32 v[128:129], v[40:41], v[156:157]
	v_pk_mul_f32 v[134:135], v[54:55], v[160:161]
	v_pk_mul_f32 v[132:133], v[52:53], v[158:159]
	v_pk_mul_f32 v[138:139], v[50:51], v[168:169]
	v_pk_mul_f32 v[136:137], v[48:49], v[164:165]
	v_pk_mul_f32 v[142:143], v[62:63], v[166:167]
	v_pk_mul_f32 v[140:141], v[60:61], v[162:163]
	v_pk_mul_f32 v[146:147], v[58:59], v[172:173]
	v_pk_mul_f32 v[144:145], v[56:57], v[170:171]
	global_store_dwordx4 v[82:83], v[64:67], off
	global_store_dwordx4 v[82:83], v[68:71], off offset:16
	global_store_dwordx4 v[82:83], v[72:75], off offset:2048
	global_store_dwordx4 v[82:83], v[76:79], off offset:2064
	global_store_dwordx4 v[88:89], v[100:103], off offset:-4096
	global_store_dwordx4 v[86:87], v[104:107], off offset:16
	global_store_dwordx4 v[86:87], v[108:111], off offset:2048
	global_store_dwordx4 v[86:87], v[112:115], off offset:2064
	global_store_dwordx4 v[88:89], v[116:119], off
	global_store_dwordx4 v[88:89], v[120:123], off offset:16
	global_store_dwordx4 v[88:89], v[124:127], off offset:2048
	global_store_dwordx4 v[88:89], v[128:131], off offset:2064
	global_store_dwordx4 v[90:91], v[132:135], off
	global_store_dwordx4 v[90:91], v[136:139], off offset:16
	global_store_dwordx4 v[90:91], v[140:143], off offset:2048
	global_store_dwordx4 v[90:91], v[144:147], off offset:2064
	v_lshl_add_u64 v[82:83], v[82:83], 0, s[4:5]
	v_add_co_u32_e32 v84, vcc, s6, v80
	v_add_co_u32_e64 v86, s[0:1], s6, v82
	s_nop 0
	v_addc_co_u32_e32 v85, vcc, 0, v81, vcc
	v_addc_co_u32_e64 v87, s[0:1], 0, v83, s[0:1]
	v_add_co_u32_e64 v88, s[0:1], s7, v82
	s_add_i32 s88, s88, s90
	s_nop 0
	v_addc_co_u32_e64 v89, s[0:1], 0, v83, s[0:1]
	v_add_co_u32_e64 v90, s[0:1], s8, v82
	v_lshl_add_u64 v[80:81], v[80:81], 0, s[2:3]
	s_nop 0
	v_addc_co_u32_e64 v91, s[0:1], 0, v83, s[0:1]
	s_cmpk_lt_i32 s88, 0x2000
	s_waitcnt vmcnt(23)
; __device__ __forceinline__ void unpack8(const u32x4 w, f32x4& a, f32x4& b) { a = (f32x4){bflo(w.x), bfhi(w.x), bflo(w.y), bfhi(w.y)}; b = (f32x4){bflo(w.z), bfhi(w.z), bflo(w.w), bfhi(w.w)}; }
; __device__ __forceinline__ void load_xrow(Frame& F, int m, f32x4 (&v)[16]) {
;     ...
;     for (int j = 0; j < 8; ++j) w[j] = xr[64 * j];
; #pragma unroll
;     for (int j = 0; j < 8; ++j) pg8::unpack8(w[j], v[2 * j], v[2 * j + 1]);
; }
; __device__ __forceinline__ float row_rnorm(const f32x4 (&v)[16]) {
;     float s = 0.f;
; #pragma unroll
;     for (int j = 0; j < 16; ++j) s += (v[j].x * v[j].x + v[j].y * v[j].y) + (v[j].z * v[j].z + v[j].w * v[j].w);
	v_lshlrev_b32_e32 v122, 16, v200
	v_and_b32_e32 v123, 0xffff0000, v200
	v_lshlrev_b32_e32 v200, 16, v201
	s_waitcnt vmcnt(20)
	v_lshlrev_b32_e32 v118, 16, v212
	v_and_b32_e32 v119, 0xffff0000, v212
	v_lshlrev_b32_e32 v212, 16, v213
	v_lshlrev_b32_e32 v121, 16, v215
	v_lshlrev_b32_e32 v120, 16, v214
	v_and_b32_e32 v215, 0xffff0000, v215
	v_and_b32_e32 v214, 0xffff0000, v214
	v_and_b32_e32 v213, 0xffff0000, v213
	v_lshlrev_b32_e32 v126, 16, v207
	v_mul_f32_e32 v130, v118, v118
	v_mul_f32_e32 v132, v212, v212
	v_pk_mul_f32 v[134:135], v[214:215], v[214:215]
	v_lshlrev_b32_e32 v116, 16, v206
	v_and_b32_e32 v117, 0xffff0000, v206
	v_lshlrev_b32_e32 v206, 16, v208
	v_and_b32_e32 v201, 0xffff0000, v201
	v_lshlrev_b32_e32 v125, 16, v205
	v_lshlrev_b32_e32 v124, 16, v204
	v_and_b32_e32 v205, 0xffff0000, v205
	v_and_b32_e32 v204, 0xffff0000, v204
	v_and_b32_e32 v127, 0xffff0000, v207
	v_mul_f32_e32 v136, v122, v122
	v_mul_f32_e32 v138, v200, v200
	v_mul_f32_e32 v146, v126, v126
	v_mov_b32_e32 v152, v120
	v_mov_b32_e32 v153, v214
	v_mov_b32_e32 v214, v121
	v_pk_fma_f32 v[130:131], v[118:119], v[118:119], v[130:131] op_sel_hi:[1,1,0]
	v_pk_fma_f32 v[132:133], v[212:213], v[212:213], v[132:133] op_sel_hi:[1,1,0]
	v_pk_fma_f32 v[120:121], v[120:121], v[120:121], v[134:135]
	v_lshlrev_b32_e32 v84, 16, v202
	v_and_b32_e32 v85, 0xffff0000, v202
	v_lshlrev_b32_e32 v202, 16, v203
	v_and_b32_e32 v203, 0xffff0000, v203
	v_and_b32_e32 v141, 0xffff0000, v208
	v_pk_mul_f32 v[142:143], v[204:205], v[204:205]
	v_mul_f32_e32 v207, v116, v116
	v_mul_f32_e32 v145, v117, v117
	v_mov_b32_e32 v144, v206
	v_pk_fma_f32 v[134:135], v[122:123], v[122:123], v[136:137] op_sel_hi:[1,1,0]
	v_pk_fma_f32 v[136:137], v[200:201], v[200:201], v[138:139] op_sel_hi:[1,1,0]
	v_pk_fma_f32 v[138:139], v[126:127], v[126:127], v[146:147] op_sel_hi:[1,1,0]
	v_pk_add_f32 v[120:121], v[120:121], v[120:121] op_sel_hi:[0,1]
	v_pk_add_f32 v[130:131], v[130:131], v[132:133]
	v_mul_f32_e32 v140, v84, v84
	v_mov_b32_e32 v154, v124
	v_mov_b32_e32 v155, v204
	v_mov_b32_e32 v204, v125
	v_pk_fma_f32 v[124:125], v[124:125], v[124:125], v[142:143]
	v_pk_add_f32 v[142:143], v[206:207], v[144:145]
	v_mov_b32_e32 v207, v141
	v_mul_f32_e32 v134, v202, v202
	v_mul_f32_e32 v136, v203, v203
	v_mul_f32_e32 v138, v141, v141
	v_mul_f32_e32 v120, v85, v85
	v_mov_b32_e32 v141, v131
	v_pk_add_f32 v[134:135], v[134:135], v[136:137]
	v_pk_add_f32 v[120:121], v[140:141], v[120:121]
	v_lshlrev_b32_e32 v129, 16, v211
	v_lshlrev_b32_e32 v128, 16, v210
	v_and_b32_e32 v211, 0xffff0000, v211
	v_and_b32_e32 v210, 0xffff0000, v210
	v_pk_add_f32 v[120:121], v[120:121], v[134:135]
	v_lshlrev_b32_e32 v208, 16, v209
	v_and_b32_e32 v209, 0xffff0000, v209
	v_pk_mul_f32 v[150:151], v[210:211], v[210:211]
	v_pk_add_f32 v[124:125], v[124:125], v[124:125] op_sel_hi:[0,1]
	v_pk_add_f32 v[120:121], v[120:121], v[120:121] op_sel_hi:[0,1]
	v_mul_f32_e32 v148, v206, v206
	v_mov_b32_e32 v156, v128
	v_mov_b32_e32 v157, v210
	v_mov_b32_e32 v210, v129
	v_pk_fma_f32 v[128:129], v[128:129], v[128:129], v[150:151]
	v_mov_b32_e32 v149, v143
	v_mul_f32_e32 v124, v208, v208
	v_mul_f32_e32 v120, v209, v209
	s_waitcnt vmcnt(19)
	v_lshlrev_b32_e32 v158, 16, v216
	v_and_b32_e32 v159, 0xffff0000, v216
	v_lshlrev_b32_e32 v216, 16, v218
	v_lshlrev_b32_e32 v144, 16, v217
	v_pk_add_f32 v[128:129], v[128:129], v[128:129] op_sel_hi:[0,1]
	v_pk_add_f32 v[136:137], v[148:149], v[138:139]
	v_pk_add_f32 v[120:121], v[124:125], v[120:121]
	v_and_b32_e32 v145, 0xffff0000, v217
	v_mul_f32_e32 v217, v158, v158
	v_mul_f32_e32 v133, v159, v159
	v_mul_f32_e32 v128, v144, v144
	v_mov_b32_e32 v132, v216
	v_pk_add_f32 v[120:121], v[136:137], v[120:121]
	v_and_b32_e32 v173, 0xffff0000, v218
	v_lshlrev_b32_e32 v218, 16, v219
	v_and_b32_e32 v219, 0xffff0000, v219
	v_pk_fma_f32 v[138:139], v[144:145], v[144:145], v[128:129] op_sel_hi:[1,1,0]
	v_pk_add_f32 v[132:133], v[216:217], v[132:133]
	v_pk_add_f32 v[120:121], v[120:121], v[120:121] op_sel_hi:[0,1]
	s_waitcnt vmcnt(18)
	v_lshlrev_b32_e32 v147, 16, v221
	v_lshlrev_b32_e32 v146, 16, v220
	v_and_b32_e32 v221, 0xffff0000, v221
	v_and_b32_e32 v220, 0xffff0000, v220
	v_mul_f32_e32 v130, v216, v216
	v_mul_f32_e32 v128, v218, v218
	v_mul_f32_e32 v138, v173, v173
	v_mov_b32_e32 v131, v133
	v_mul_f32_e32 v120, v219, v219
	v_lshlrev_b32_e32 v160, 16, v222
	v_and_b32_e32 v161, 0xffff0000, v222
	s_waitcnt vmcnt(17)
	v_lshlrev_b32_e32 v222, 16, v224
	v_lshlrev_b32_e32 v150, 16, v223
	v_pk_mul_f32 v[142:143], v[220:221], v[220:221]
	v_pk_add_f32 v[130:131], v[130:131], v[138:139]
	v_pk_add_f32 v[120:121], v[128:129], v[120:121]
	v_and_b32_e32 v151, 0xffff0000, v223
	v_mul_f32_e32 v223, v160, v160
	v_mul_f32_e32 v169, v161, v161
	v_mul_f32_e32 v170, v150, v150
	v_mov_b32_e32 v168, v222
	v_pk_fma_f32 v[142:143], v[146:147], v[146:147], v[142:143]
	v_pk_add_f32 v[120:121], v[130:131], v[120:121]
	v_and_b32_e32 v179, 0xffff0000, v224
	v_lshlrev_b32_e32 v224, 16, v225
	v_and_b32_e32 v225, 0xffff0000, v225
	v_mov_b32_e32 v182, v146
	v_mov_b32_e32 v183, v220
	v_mov_b32_e32 v220, v147
	v_pk_fma_f32 v[146:147], v[150:151], v[150:151], v[170:171] op_sel_hi:[1,1,0]
	v_pk_add_f32 v[148:149], v[222:223], v[168:169]
	v_pk_add_f32 v[132:133], v[142:143], v[142:143] op_sel_hi:[0,1]
	v_pk_add_f32 v[120:121], v[120:121], v[120:121] op_sel_hi:[0,1]
	v_lshlrev_b32_e32 v165, 16, v227
	v_lshlrev_b32_e32 v164, 16, v226
	v_and_b32_e32 v227, 0xffff0000, v227
	v_and_b32_e32 v226, 0xffff0000, v226
	v_mul_f32_e32 v172, v222, v222
	v_mov_b32_e32 v217, v173
	v_mul_f32_e32 v146, v179, v179
	v_mov_b32_e32 v173, v149
	v_mul_f32_e32 v132, v224, v224
	v_mul_f32_e32 v120, v225, v225
	s_waitcnt vmcnt(16)
; __device__ __forceinline__ float wave_sum(float v) {
; #pragma unroll
;     for (int o = 1; o < 64; o <<= 1) v += __shfl_xor(v, o);
;     return v;
; __device__ __forceinline__ float row_rnorm(const f32x4 (&v)[16]) {
;     float s = 0.f;
; #pragma unroll
;     for (int j = 0; j < 16; ++j) s += (v[j].x * v[j].x + v[j].y * v[j].y) + (v[j].z * v[j].z + v[j].w * v[j].w);
;     return 1.0f / sqrtf(wave_sum(s) * (1.0f / D) + EPS);
	v_lshlrev_b32_e32 v162, 16, v228
	v_and_b32_e32 v163, 0xffff0000, v228
	v_lshlrev_b32_e32 v228, 16, v230
	v_lshlrev_b32_e32 v166, 16, v229
	v_pk_mul_f32 v[174:175], v[226:227], v[226:227]
	v_pk_add_f32 v[134:135], v[172:173], v[146:147]
	v_pk_add_f32 v[120:121], v[132:133], v[120:121]
	v_and_b32_e32 v167, 0xffff0000, v229
	v_mul_f32_e32 v229, v162, v162
	v_mul_f32_e32 v177, v163, v163
	v_mul_f32_e32 v178, v166, v166
	v_mov_b32_e32 v176, v228
	v_mov_b32_e32 v184, v164
	v_mov_b32_e32 v185, v226
	v_mov_b32_e32 v226, v165
	v_pk_fma_f32 v[164:165], v[164:165], v[164:165], v[174:175]
	v_pk_add_f32 v[120:121], v[134:135], v[120:121]
	v_and_b32_e32 v181, 0xffff0000, v230
	v_lshlrev_b32_e32 v230, 16, v231
	v_and_b32_e32 v231, 0xffff0000, v231
	v_pk_fma_f32 v[168:169], v[166:167], v[166:167], v[178:179] op_sel_hi:[1,1,0]
	v_pk_add_f32 v[170:171], v[228:229], v[176:177]
	v_pk_add_f32 v[140:141], v[164:165], v[164:165] op_sel_hi:[0,1]
	v_pk_add_f32 v[120:121], v[120:121], v[120:121] op_sel_hi:[0,1]
	v_mul_f32_e32 v180, v228, v228
	v_mov_b32_e32 v229, v181
	v_mul_f32_e32 v168, v181, v181
	v_mov_b32_e32 v181, v171
	v_mul_f32_e32 v140, v230, v230
	v_mul_f32_e32 v120, v231, v231
	v_pk_add_f32 v[138:139], v[180:181], v[168:169]
	v_pk_add_f32 v[120:121], v[140:141], v[120:121]
	v_mov_b32_e32 v223, v179
	v_pk_add_f32 v[120:121], v[138:139], v[120:121]
	s_nop 0
	v_add_f32_e32 v120, v120, v121
	ds_bpermute_b32 v121, v92, v120
	s_waitcnt lgkmcnt(0)
	v_add_f32_e32 v120, v120, v121
	ds_bpermute_b32 v121, v93, v120
	s_waitcnt lgkmcnt(0)
	v_add_f32_e32 v120, v120, v121
	ds_bpermute_b32 v121, v94, v120
	s_waitcnt lgkmcnt(0)
	v_add_f32_e32 v120, v120, v121
	ds_bpermute_b32 v121, v95, v120
	s_waitcnt lgkmcnt(0)
	v_add_f32_e32 v120, v120, v121
	ds_bpermute_b32 v121, v96, v120
	s_waitcnt lgkmcnt(0)
	v_add_f32_e32 v120, v120, v121
	ds_bpermute_b32 v121, v97, v120
	s_waitcnt lgkmcnt(0)
; __device__ __forceinline__ float row_rnorm(const f32x4 (&v)[16]) {
;     float s = 0.f;
; #pragma unroll
;     for (int j = 0; j < 16; ++j) s += (v[j].x * v[j].x + v[j].y * v[j].y) + (v[j].z * v[j].z + v[j].w * v[j].w);
;     return 1.0f / sqrtf(wave_sum(s) * (1.0f / D) + EPS);
; __device__ __forceinline__ void final_norm_phase(Frame& F, const Args& A, int nsplit, float scale) {
;     ...
;     for (int m = F.gw; m < NPROMPT; m += F.ngw) {
;         f32x4 v[16]; load_xrow(F, m, v);
;         const float r = row_rnorm(v);
; #pragma unroll
;         for (int j = 0; j < 8; ++j) { f32x4* o = (f32x4*)(F.out + (size_t)m * D + 8 * (64 * j + F.lane)); o[0] = v[2 * j] * r * gn[2 * j]; o[1] = v[2 * j + 1] * r * gn[2 * j + 1]; }
;     }
	v_add_f32_e32 v120, v120, v121
	v_fmamk_f32 v120, v120, 0x39800000, v98
	v_mul_f32_e32 v121, 0x4f800000, v120
	v_cmp_gt_f32_e32 vcc, s9, v120
	s_nop 1
	v_cndmask_b32_e32 v120, v120, v121, vcc
	v_sqrt_f32_e32 v121, v120
	s_nop 0
	v_add_u32_e32 v124, -1, v121
	v_add_u32_e32 v125, 1, v121
	v_fma_f32 v128, -v124, v121, v120
	v_fma_f32 v129, -v125, v121, v120
	v_cmp_ge_f32_e64 s[0:1], 0, v128
	s_nop 1
	v_cndmask_b32_e64 v121, v121, v124, s[0:1]
	v_cmp_lt_f32_e64 s[0:1], 0, v129
	s_nop 1
	v_cndmask_b32_e64 v121, v121, v125, s[0:1]
	v_mul_f32_e32 v124, 0x37800000, v121
	v_cndmask_b32_e32 v121, v121, v124, vcc
	v_cmp_class_f32_e32 vcc, v120, v99
	s_nop 1
	v_cndmask_b32_e32 v120, v121, v120, vcc
	v_div_scale_f32 v121, s[0:1], v120, v120, 1.0
	v_rcp_f32_e32 v125, v121
	v_div_scale_f32 v124, vcc, 1.0, v120, 1.0
	v_fma_f32 v128, -v121, v125, 1.0
	v_fmac_f32_e32 v125, v128, v125
	v_mul_f32_e32 v128, v124, v125
	v_fma_f32 v129, -v121, v128, v124
	v_fmac_f32_e32 v128, v129, v125
	v_fma_f32 v121, -v121, v128, v124
	v_div_fmas_f32 v121, v121, v125, v128
	v_div_fixup_f32 v120, v121, v120, 1.0
	v_pk_mul_f32 v[118:119], v[120:121], v[118:119] op_sel_hi:[0,1]
	v_pk_mul_f32 v[212:213], v[120:121], v[212:213] op_sel_hi:[0,1]
	v_pk_mul_f32 v[124:125], v[120:121], v[152:153] op_sel_hi:[0,1]
	v_pk_mul_f32 v[214:215], v[120:121], v[214:215] op_sel_hi:[0,1]
	v_pk_mul_f32 v[122:123], v[120:121], v[122:123] op_sel_hi:[0,1]
	v_pk_mul_f32 v[200:201], v[120:121], v[200:201] op_sel_hi:[0,1]
	v_pk_mul_f32 v[84:85], v[120:121], v[84:85] op_sel_hi:[0,1]
	v_pk_mul_f32 v[128:129], v[120:121], v[202:203] op_sel_hi:[0,1]
	v_pk_mul_f32 v[130:131], v[120:121], v[154:155] op_sel_hi:[0,1]
	v_pk_mul_f32 v[132:133], v[120:121], v[204:205] op_sel_hi:[0,1]
	v_pk_mul_f32 v[116:117], v[120:121], v[116:117] op_sel_hi:[0,1]
	v_pk_mul_f32 v[126:127], v[120:121], v[126:127] op_sel_hi:[0,1]
	v_pk_mul_f32 v[134:135], v[120:121], v[206:207] op_sel_hi:[0,1]
	v_pk_mul_f32 v[136:137], v[120:121], v[208:209] op_sel_hi:[0,1]
	v_pk_mul_f32 v[138:139], v[120:121], v[156:157] op_sel_hi:[0,1]
	v_pk_mul_f32 v[140:141], v[120:121], v[210:211] op_sel_hi:[0,1]
	v_pk_mul_f32 v[142:143], v[120:121], v[158:159] op_sel_hi:[0,1]
	v_pk_mul_f32 v[144:145], v[120:121], v[144:145] op_sel_hi:[0,1]
	v_pk_mul_f32 v[146:147], v[120:121], v[216:217] op_sel_hi:[0,1]
	v_pk_mul_f32 v[148:149], v[120:121], v[218:219] op_sel_hi:[0,1]
	v_pk_mul_f32 v[152:153], v[120:121], v[182:183] op_sel_hi:[0,1]
	v_pk_mul_f32 v[154:155], v[120:121], v[220:221] op_sel_hi:[0,1]
	v_pk_mul_f32 v[156:157], v[120:121], v[160:161] op_sel_hi:[0,1]
	v_pk_mul_f32 v[150:151], v[120:121], v[150:151] op_sel_hi:[0,1]
	v_pk_mul_f32 v[158:159], v[120:121], v[222:223] op_sel_hi:[0,1]
	v_pk_mul_f32 v[160:161], v[120:121], v[224:225] op_sel_hi:[0,1]
	v_pk_mul_f32 v[164:165], v[120:121], v[184:185] op_sel_hi:[0,1]
	v_pk_mul_f32 v[168:169], v[120:121], v[226:227] op_sel_hi:[0,1]
	v_pk_mul_f32 v[162:163], v[120:121], v[162:163] op_sel_hi:[0,1]
	v_pk_mul_f32 v[166:167], v[120:121], v[166:167] op_sel_hi:[0,1]
	v_pk_mul_f32 v[170:171], v[120:121], v[228:229] op_sel_hi:[0,1]
	v_pk_mul_f32 v[172:173], v[120:121], v[230:231] op_sel_hi:[0,1]
	v_pk_mul_f32 v[210:211], v[6:7], v[212:213]
	v_pk_mul_f32 v[208:209], v[4:5], v[118:119]
	v_pk_mul_f32 v[206:207], v[2:3], v[214:215]
	v_pk_mul_f32 v[204:205], v[0:1], v[124:125]
	v_pk_mul_f32 v[202:203], v[14:15], v[200:201]
	v_pk_mul_f32 v[200:201], v[12:13], v[122:123]
	v_pk_mul_f32 v[214:215], v[10:11], v[128:129]
	v_pk_mul_f32 v[212:213], v[8:9], v[84:85]
	v_pk_mul_f32 v[218:219], v[22:23], v[132:133]
	v_pk_mul_f32 v[216:217], v[20:21], v[130:131]
	v_pk_mul_f32 v[222:223], v[18:19], v[126:127]
	v_pk_mul_f32 v[220:221], v[16:17], v[116:117]
	v_pk_mul_f32 v[226:227], v[30:31], v[136:137]
	v_pk_mul_f32 v[224:225], v[28:29], v[134:135]
	v_pk_mul_f32 v[230:231], v[26:27], v[140:141]
	v_pk_mul_f32 v[228:229], v[24:25], v[138:139]
	v_pk_mul_f32 v[118:119], v[38:39], v[144:145]
	v_pk_mul_f32 v[116:117], v[36:37], v[142:143]
	v_pk_mul_f32 v[122:123], v[34:35], v[148:149]
	v_pk_mul_f32 v[120:121], v[32:33], v[146:147]
	v_pk_mul_f32 v[126:127], v[46:47], v[154:155]
	v_pk_mul_f32 v[124:125], v[44:45], v[152:153]
	v_pk_mul_f32 v[130:131], v[42:43], v[150:151]
	v_pk_mul_f32 v[128:129], v[40:41], v[156:157]
	v_pk_mul_f32 v[134:135], v[54:55], v[160:161]
	v_pk_mul_f32 v[132:133], v[52:53], v[158:159]
	v_pk_mul_f32 v[138:139], v[50:51], v[168:169]
	v_pk_mul_f32 v[136:137], v[48:49], v[164:165]
	v_pk_mul_f32 v[142:143], v[62:63], v[166:167]
	v_pk_mul_f32 v[140:141], v[60:61], v[162:163]
	v_pk_mul_f32 v[146:147], v[58:59], v[172:173]
	v_pk_mul_f32 v[144:145], v[56:57], v[170:171]
	global_store_dwordx4 v[82:83], v[208:211], off
	global_store_dwordx4 v[82:83], v[204:207], off offset:16
	global_store_dwordx4 v[82:83], v[200:203], off offset:2048
	global_store_dwordx4 v[82:83], v[212:215], off offset:2064
	global_store_dwordx4 v[88:89], v[216:219], off offset:-4096
	global_store_dwordx4 v[86:87], v[220:223], off offset:16
	global_store_dwordx4 v[86:87], v[224:227], off offset:2048
	global_store_dwordx4 v[86:87], v[228:231], off offset:2064
	global_store_dwordx4 v[88:89], v[116:119], off
	global_store_dwordx4 v[88:89], v[120:123], off offset:16
	global_store_dwordx4 v[88:89], v[124:127], off offset:2048
	global_store_dwordx4 v[88:89], v[128:131], off offset:2064
	global_store_dwordx4 v[90:91], v[132:135], off
	global_store_dwordx4 v[90:91], v[136:139], off offset:16
	global_store_dwordx4 v[90:91], v[140:143], off offset:2048
	global_store_dwordx4 v[90:91], v[144:147], off offset:2064
	v_lshl_add_u64 v[82:83], v[82:83], 0, s[4:5]
